# WAR guards armed at the seam and checked lazily at the next phase's first epilogue; fused epilogues issue h/gain loads ahead of the team barrier; fourth arriver skips polling
# speedup vs baseline: 1.0354x; 1.0181x over previous
; #define LAS __attribute__((address_space(3)))
; __device__ __forceinline__ unsigned xb_ld(unsigned* p)              { return __hip_atomic_load(p, __ATOMIC_RELAXED, __HIP_MEMORY_SCOPE_AGENT); }
; __device__ __forceinline__ unsigned xb_add(unsigned* p, unsigned v) { return __hip_atomic_fetch_add(p, v, __ATOMIC_RELAXED, __HIP_MEMORY_SCOPE_AGENT); }
; __device__ __forceinline__ unsigned xb_xcc_id() { return (unsigned)__builtin_amdgcn_s_getreg((3 << 11) | 20) & 0xFu; }
; __device__ __forceinline__ XcdBarrier xcd_barrier_post(unsigned* bar, volatile LAS unsigned* st) {
;     XcdBarrier b; b.bar = bar; b.x = xb_xcc_id(); b.st = st;
;     if (threadIdx.x == 0) (void)xb_add(&bar[XB_XCNT(b.x)], 1u);
;     return b;
; }
; __device__ __forceinline__ void xcd_barrier_complete(unsigned* bar, unsigned x, unsigned& nloc, unsigned& nx) {
;     const unsigned G = gridDim.x * gridDim.y * gridDim.z;
;     unsigned sum, cnt, mine, sp = 0u;
;     for (;;) {
;         sum = 0u; cnt = 0u; mine = 0u;
; #pragma unroll
;         for (unsigned j = 0; j < 16; ++j) { const unsigned c = xb_ld(&bar[XB_XCNT(j)]); sum += c; cnt += (c > 0u) ? 1u : 0u; mine = (j == x) ? c : mine; }
;         if (sum == G) break;
;         __builtin_amdgcn_s_sleep(1);
;         if ((++sp & 255u) == 0u) { if (xb_ld(&bar[XB_TMO])) break; if (sp > XB_SPIN_CAP) { atomicAdd(&bar[XB_TMO], 1u); break; } }
;     }
;     nloc = mine > 0u ? mine : 1u; nx = cnt > 0u ? cnt : 1u;
; }
.LBB0_212:
	s_add_u32 s4, s28, 0x3903600
	s_addc_u32 s5, s29, 0
	v_and_b32_e32 v0, 63, v195
	v_lshlrev_b32_e32 v0, 5, v0
	global_load_dwordx4 v[0:3], v0, s[4:5] offset:16 sc1
	s_waitcnt vmcnt(0)
	v_min_u32_e32 v4, v0, v1
	v_max_u32_e32 v5, v0, v1
	v_min3_u32 v4, v4, v2, v3
	v_max3_u32 v5, v5, v2, v3
	s_nop 1
	v_min_u32_dpp v4, v4, v4 quad_perm:[1,0,3,2] row_mask:0xf bank_mask:0xf
	v_max_u32_dpp v5, v5, v5 quad_perm:[1,0,3,2] row_mask:0xf bank_mask:0xf
	s_nop 1
	v_min_u32_dpp v4, v4, v4 quad_perm:[2,3,0,1] row_mask:0xf bank_mask:0xf
	v_max_u32_dpp v5, v5, v5 quad_perm:[2,3,0,1] row_mask:0xf bank_mask:0xf
	s_nop 1
	v_min_u32_dpp v4, v4, v4 row_half_mirror row_mask:0xf bank_mask:0xf
	v_max_u32_dpp v5, v5, v5 row_half_mirror row_mask:0xf bank_mask:0xf
	s_nop 1
	v_cmp_eq_u32_e32 vcc, v4, v5
	s_mov_b64 s[4:5], vcc
	v_cmp_ne_u32_e32 vcc, 0, v4
	s_and_b64 s[4:5], s[4:5], vcc
	s_cmp_eq_u64 s[4:5], exec
	s_cselect_b32 s99, 1, 0
	s_mov_b32 s100, 0
	s_cmp_lt_i32 s30, 2
	s_cselect_b64 s[4:5], -1, 0
	s_add_u32 s16, s28, 0x9000000
	s_addc_u32 s17, s29, 0
	s_and_b64 s[12:13], s[4:5], s[0:1]
	s_andn2_b64 vcc, exec, s[12:13]
	s_cbranch_vccnz .LBB0_257
	s_mov_b32 s14, -1
	s_ashr_i32 s3, s2, 31
	s_mov_b32 s15, s14
	s_ashr_i32 s8, s33, 31
	s_waitcnt vmcnt(15)
	v_mov_b64_e32 v[0:1], 0xb00
	v_mov_b64_e32 v[2:3], 0xaff
	s_movk_i32 s24, 0x161
	s_mov_b64 s[20:21], s[2:3]
	s_mov_b32 s9, s14
	s_mov_b64 s[18:19], s[14:15]
	s_branch .LBB0_216

; __device__ __forceinline__ unsigned pk2(float lo, float hi) { bf16x2_t r = __builtin_convertvector((f32x2_t){lo, hi}, bf16x2_t); return __builtin_bit_cast(unsigned, r); }
;     __device__ __forceinline__ void operator()(const pg8::f32x4 (&acc)[2][2][4][2], const pg8::Unit& u, int wr, int wc, int fr, int fq) const {
;     ...
;                     if (PART) {
; #pragma unroll
;                         for (int j = 0; j < 8; ++j) s += r[j] * r[j];
;                     }
;                     v4u w; w.x = pk2(r[0], r[1]); w.y = pk2(r[2], r[3]); w.z = pk2(r[4], r[5]); w.w = pk2(r[6], r[7]);
;                     st16_wt(O + off + bj * 128, w);
;                 }
;                 if (PART) { s += __shfl_xor(s, 16); s += __shfl_xor(s, 32); st4_wt(part + (size_t)row * 16 + u.pn * 4 + wc, s); }
; template <bool SRC_F32, bool FINAL, int R> __device__ __forceinline__ void ew_compute(const EwSet<SRC_F32, R>& S, int rb, const f32x4 (&g)[4], bf16* hb_out, float* out32, float scale, float* rs_out, int lane) {
; #pragma unroll
;     for (int i = 0; i < R; ++i) {
;         float q = S.p[i];
;         q += __shfl_xor(q, 1); q += __shfl_xor(q, 2); q += __shfl_xor(q, 4); q += __shfl_xor(q, 8);
;         const float ss = __shfl(q, 0);
;         const float rs = scale / sqrtf(ss * (1.f / D) + EPS);
.LBB0_332:
	s_waitcnt lgkmcnt(0)
	v_lshl_or_b32 v242, s62, 8, v148
	v_lshl_add_u32 v243, s61, 8, v146
	v_lshlrev_b32_e32 v246, 2, v242
	v_lshlrev_b32_e32 v153, 1, v242
	v_lshl_add_u32 v153, v243, 11, v153
	v_xor_b32_e32 v166, 16, v152
	v_lshlrev_b32_e32 v166, 2, v166
	v_xor_b32_e32 v168, 32, v152
	v_lshlrev_b32_e32 v168, 2, v168
	v_lshrrev_b32_e32 v161, 4, v152
	v_and_b32_e32 v161, 3, v161
	v_lshlrev_b32_e32 v161, 4, v161
	v_lshl_add_u32 v161, v243, 6, v161
	s_lshl_b32 s95, s62, 4
	s_add_u32 s95, s95, s14
	v_lshl_add_u32 v157, v243, 6, s95
	v_pk_mul_f32 v[242:243], v[124:125], v[124:125]
	v_pk_fma_f32 v[242:243], v[126:127], v[126:127], v[242:243]
	v_pk_fma_f32 v[242:243], v[120:121], v[120:121], v[242:243]
	v_pk_fma_f32 v[242:243], v[122:123], v[122:123], v[242:243]
	v_pk_fma_f32 v[242:243], v[116:117], v[116:117], v[242:243]
	v_pk_fma_f32 v[242:243], v[118:119], v[118:119], v[242:243]
	v_pk_fma_f32 v[242:243], v[112:113], v[112:113], v[242:243]
	v_pk_fma_f32 v[242:243], v[114:115], v[114:115], v[242:243]
	v_add_f32_e32 v145, v242, v243
	v_pk_mul_f32 v[244:245], v[108:109], v[108:109]
	v_pk_fma_f32 v[244:245], v[110:111], v[110:111], v[244:245]
	v_pk_fma_f32 v[244:245], v[104:105], v[104:105], v[244:245]
	v_pk_fma_f32 v[244:245], v[106:107], v[106:107], v[244:245]
	v_pk_fma_f32 v[244:245], v[100:101], v[100:101], v[244:245]
	v_pk_fma_f32 v[244:245], v[102:103], v[102:103], v[244:245]
	v_pk_fma_f32 v[244:245], v[96:97], v[96:97], v[244:245]
	v_pk_fma_f32 v[244:245], v[98:99], v[98:99], v[244:245]
	v_add_f32_e32 v155, v244, v245
	v_pk_mul_f32 v[242:243], v[92:93], v[92:93]
	v_pk_fma_f32 v[242:243], v[94:95], v[94:95], v[242:243]
	v_pk_fma_f32 v[242:243], v[88:89], v[88:89], v[242:243]
	v_pk_fma_f32 v[242:243], v[90:91], v[90:91], v[242:243]
	v_pk_fma_f32 v[242:243], v[84:85], v[84:85], v[242:243]
	v_pk_fma_f32 v[242:243], v[86:87], v[86:87], v[242:243]
	v_pk_fma_f32 v[242:243], v[80:81], v[80:81], v[242:243]
	v_pk_fma_f32 v[242:243], v[82:83], v[82:83], v[242:243]
	v_add_f32_e32 v159, v242, v243
	v_pk_mul_f32 v[244:245], v[76:77], v[76:77]
	v_pk_fma_f32 v[244:245], v[78:79], v[78:79], v[244:245]
	v_pk_fma_f32 v[244:245], v[72:73], v[72:73], v[244:245]
	v_pk_fma_f32 v[244:245], v[74:75], v[74:75], v[244:245]
	v_pk_fma_f32 v[244:245], v[68:69], v[68:69], v[244:245]
	v_pk_fma_f32 v[244:245], v[70:71], v[70:71], v[244:245]
	v_pk_fma_f32 v[244:245], v[64:65], v[64:65], v[244:245]
	v_pk_fma_f32 v[244:245], v[66:67], v[66:67], v[244:245]
	v_add_f32_e32 v163, v244, v245
	v_pk_mul_f32 v[242:243], v[60:61], v[60:61]
	v_pk_fma_f32 v[242:243], v[62:63], v[62:63], v[242:243]
	v_pk_fma_f32 v[242:243], v[56:57], v[56:57], v[242:243]
	v_pk_fma_f32 v[242:243], v[58:59], v[58:59], v[242:243]
	v_pk_fma_f32 v[242:243], v[52:53], v[52:53], v[242:243]
	v_pk_fma_f32 v[242:243], v[54:55], v[54:55], v[242:243]
	v_pk_fma_f32 v[242:243], v[48:49], v[48:49], v[242:243]
	v_pk_fma_f32 v[242:243], v[50:51], v[50:51], v[242:243]
	v_add_f32_e32 v165, v242, v243
	v_pk_mul_f32 v[244:245], v[44:45], v[44:45]
	v_pk_fma_f32 v[244:245], v[46:47], v[46:47], v[244:245]
	v_pk_fma_f32 v[244:245], v[40:41], v[40:41], v[244:245]
	v_pk_fma_f32 v[244:245], v[42:43], v[42:43], v[244:245]
	v_pk_fma_f32 v[244:245], v[36:37], v[36:37], v[244:245]
	v_pk_fma_f32 v[244:245], v[38:39], v[38:39], v[244:245]
	v_pk_fma_f32 v[244:245], v[32:33], v[32:33], v[244:245]
	v_pk_fma_f32 v[244:245], v[34:35], v[34:35], v[244:245]
	v_add_f32_e32 v171, v244, v245
	v_pk_mul_f32 v[242:243], v[28:29], v[28:29]
	v_pk_fma_f32 v[242:243], v[30:31], v[30:31], v[242:243]
	v_pk_fma_f32 v[242:243], v[24:25], v[24:25], v[242:243]
	v_pk_fma_f32 v[242:243], v[26:27], v[26:27], v[242:243]
	v_pk_fma_f32 v[242:243], v[20:21], v[20:21], v[242:243]
	v_pk_fma_f32 v[242:243], v[22:23], v[22:23], v[242:243]
	v_pk_fma_f32 v[242:243], v[16:17], v[16:17], v[242:243]
	v_pk_fma_f32 v[242:243], v[18:19], v[18:19], v[242:243]
	v_add_f32_e32 v193, v242, v243
	v_pk_mul_f32 v[244:245], v[12:13], v[12:13]
	v_pk_fma_f32 v[244:245], v[14:15], v[14:15], v[244:245]
	v_pk_fma_f32 v[244:245], v[8:9], v[8:9], v[244:245]
	v_pk_fma_f32 v[244:245], v[10:11], v[10:11], v[244:245]
	v_pk_fma_f32 v[244:245], v[4:5], v[4:5], v[244:245]
	v_pk_fma_f32 v[244:245], v[6:7], v[6:7], v[244:245]
	v_pk_fma_f32 v[244:245], v[0:1], v[0:1], v[244:245]
	v_pk_fma_f32 v[244:245], v[2:3], v[2:3], v[244:245]
	v_add_f32_e32 v241, v244, v245
	s_nop 1
	ds_bpermute_b32 v188, v166, v145
	ds_bpermute_b32 v196, v166, v155
	ds_bpermute_b32 v200, v166, v159
	ds_bpermute_b32 v204, v166, v163
	ds_bpermute_b32 v208, v166, v165
	ds_bpermute_b32 v212, v166, v171
	ds_bpermute_b32 v216, v166, v193
	ds_bpermute_b32 v220, v166, v241
	s_waitcnt lgkmcnt(0)
	v_add_f32_e32 v145, v145, v188
	v_add_f32_e32 v155, v155, v196
	v_add_f32_e32 v159, v159, v200
	v_add_f32_e32 v163, v163, v204
	v_add_f32_e32 v165, v165, v208
	v_add_f32_e32 v171, v171, v212
	v_add_f32_e32 v193, v193, v216
	v_add_f32_e32 v241, v241, v220
	s_nop 1
	ds_bpermute_b32 v188, v168, v145
	ds_bpermute_b32 v196, v168, v155
	ds_bpermute_b32 v200, v168, v159
	ds_bpermute_b32 v204, v168, v163
	ds_bpermute_b32 v208, v168, v165
	ds_bpermute_b32 v212, v168, v171
	ds_bpermute_b32 v216, v168, v193
	ds_bpermute_b32 v220, v168, v241
	s_waitcnt lgkmcnt(0)
	v_add_f32_e32 v145, v145, v188
	v_add_f32_e32 v155, v155, v196
	v_add_f32_e32 v159, v159, v200
	v_add_f32_e32 v163, v163, v204
	v_add_f32_e32 v165, v165, v208
	v_add_f32_e32 v171, v171, v212
	v_add_f32_e32 v193, v193, v216
	v_add_f32_e32 v241, v241, v220
	global_store_dword v157, v145, s[20:21]
	v_add_u32_e32 v196, 0x400, v157
	global_store_dword v196, v155, s[20:21]
	v_add_u32_e32 v200, 0x800, v157
	global_store_dword v200, v159, s[20:21]
	v_add_u32_e32 v204, 0xc00, v157
	global_store_dword v204, v163, s[20:21]
	v_add_u32_e32 v208, 0x2000, v157
	global_store_dword v208, v165, s[20:21]
	v_add_u32_e32 v212, 0x2400, v157
	global_store_dword v212, v171, s[20:21]
	v_add_u32_e32 v216, 0x2800, v157
	global_store_dword v216, v193, s[20:21]
	v_add_u32_e32 v220, 0x2c00, v157
	global_store_dword v220, v241, s[20:21]
	s_add_u32 s62, s84, 0xffffff10
	s_addc_u32 s63, s85, -1
	s_load_dwordx2 s[64:65], s[62:63], 0x30
	s_add_u32 s66, s28, 0x5000000
	s_addc_u32 s67, s29, 0
	s_add_u32 s78, s28, 0x4c00000
	s_addc_u32 s79, s29, 0
	global_load_dwordx4 v[224:227], v153, s[66:67]
	global_load_dwordx4 v[228:231], v153, s[66:67] offset:256
	v_add_u32_e32 v244, 0x8000, v153
	global_load_dwordx4 v[232:235], v244, s[66:67]
	global_load_dwordx4 v[236:239], v244, s[66:67] offset:256
	s_waitcnt lgkmcnt(0)
	global_load_dwordx4 v[172:175], v246, s[64:65]
	global_load_dwordx4 v[176:179], v246, s[64:65] offset:16
	global_load_dwordx4 v[180:183], v246, s[64:65] offset:512
	global_load_dwordx4 v[184:187], v246, s[64:65] offset:528
	s_waitcnt vmcnt(0)
	s_barrier
; __device__ __forceinline__ unsigned xb_ld(unsigned* p)              { return __hip_atomic_load(p, __ATOMIC_RELAXED, __HIP_MEMORY_SCOPE_AGENT); }
; __device__ __forceinline__ unsigned xb_add(unsigned* p, unsigned v) { return __hip_atomic_fetch_add(p, v, __ATOMIC_RELAXED, __HIP_MEMORY_SCOPE_AGENT); }
; #define XB_SPIN(cond, bar) do { unsigned _sp = 0; while (cond) { __builtin_amdgcn_s_sleep(1); \
;     if ((++_sp & 255u) == 0u) { if (xb_ld(&(bar)[XB_TMO])) break; if (_sp > XB_SPIN_CAP) { atomicAdd(&(bar)[XB_TMO], 1u); break; } } } } while (0)
; __device__ __forceinline__ void xcd_barrier(const XcdBarrier& b) {
;     asm volatile("s_waitcnt vmcnt(0)" ::: "memory");
;     __syncthreads();
;     if (threadIdx.x == 0) {
;         unsigned* bar = b.bar;
;         __builtin_amdgcn_s_waitcnt(0);
;         unsigned nloc = b.st[0], nx = b.st[1];
;         if (nloc == 0u) { xcd_barrier_complete(bar, b.x, nloc, nx); b.st[0] = nloc; b.st[1] = nx; }
;         const unsigned old = xb_add(&bar[XB_XSUB(b.x)], 1u);
;         const unsigned gen = old / nloc;
;         if (old + 1u == (gen + 1u) * nloc) {
;             __builtin_amdgcn_fence(__ATOMIC_RELEASE, "agent");
;             asm volatile("s_waitcnt vmcnt(0)" ::: "memory");
;             const unsigned og = xb_add(&bar[XB_TOP], 1u);
;             const unsigned tg = og / nx;
;             if (og + 1u == (tg + 1u) * nx) xb_add(&bar[XB_TOPGEN], 1u);
;             else XB_SPIN(xb_ld(&bar[XB_TOPGEN]) == tg, bar);
;             __builtin_amdgcn_fence(__ATOMIC_ACQUIRE, "agent");
;             xb_add(&bar[XB_XGEN(b.x)], 1u);
;             asm volatile("s_waitcnt vmcnt(0)" ::: "memory");
;         } else {
;             XB_SPIN(xb_ld(&bar[XB_XGEN(b.x)]) == gen, bar);
;             __builtin_amdgcn_fence(__ATOMIC_ACQUIRE, "agent");
;             asm volatile("s_waitcnt vmcnt(0)" ::: "memory");
;         }
;     }
;     __syncthreads();
; }
	v_readfirstlane_b32 s94, v195
	s_cmp_lg_u32 s94, 0
	s_cbranch_scc1 .Lfe0_bskip
	s_mov_b64 exec, 1
	s_and_b32 s94, s2, 7
	s_lshl_b32 s94, s94, 3
	s_bfe_u32 s96, s2, 0x30003
	s_or_b32 s94, s94, s96
	s_lshl_b32 s94, s94, 5
	s_add_u32 s62, s28, 0x3903600
	s_addc_u32 s63, s29, 0
	v_mov_b32_e32 v242, s94
	v_mov_b32_e32 v243, 1
	s_cmp_eq_u32 s99, 1
	s_cbranch_scc1 .Lfe0_bfast
	buffer_wbl2 sc1
	s_waitcnt vmcnt(0)
.Lfe0_bfast:
	global_atomic_add v244, v242, v243, s[62:63] offset:8 sc0
	buffer_inv sc1
	s_waitcnt vmcnt(0)
	v_add_u32_e32 v245, 1, v244
	v_and_b32_e32 v245, 3, v245
	v_cmp_eq_u32_e32 vcc, 0, v245
	s_cbranch_vccnz .Lfe0_bdone
	v_lshrrev_b32_e32 v244, 2, v244
	v_add_u32_e32 v244, 1, v244
	v_lshlrev_b32_e32 v244, 2, v244
	s_mov_b32 s94, 0

; template <bool SRC_F32, int R> __device__ __forceinline__ void ew_load(EwSet<SRC_F32, R>& S, int rb, const float* hsrc32, const bf16* hsrcb, const bf16* f, const float* part, int lane) {
; #pragma unroll
;     for (int i = 0; i < R; ++i) S.p[i] = (lane < 16) ? part[(size_t)(rb + i) * 16 + lane] : 0.f;
; #pragma unroll
;     for (int i = 0; i < R; ++i)
; #pragma unroll
;         for (int j = 0; j < 4; ++j) {
;             S.fw[i][j] = ((const v2u*)(f + (size_t)(rb + i) * D) + lane)[64 * j];
;             if constexpr (SRC_F32) S.h32[i][j] = __builtin_nontemporal_load((const f32x4*)(hsrc32 + (size_t)(rb + i) * D) + lane + 64 * j);
;             else S.hb[i][j] = ((const v2u*)(hsrcb + (size_t)(rb + i) * D) + lane)[64 * j];
;         }
; }
; template <bool SRC_F32, bool FINAL, int R> __device__ __forceinline__ void ew_compute(const EwSet<SRC_F32, R>& S, int rb, const f32x4 (&g)[4], bf16* hb_out, float* out32, float scale, float* rs_out, int lane) {
; #pragma unroll
;     for (int i = 0; i < R; ++i) {
;         float q = S.p[i];
;         q += __shfl_xor(q, 1); q += __shfl_xor(q, 2); q += __shfl_xor(q, 4); q += __shfl_xor(q, 8);
;         const float ss = __shfl(q, 0);
;         const float rs = scale / sqrtf(ss * (1.f / D) + EPS);
.Lfe0_bskip:
	s_barrier
	global_load_dwordx4 v[188:191], v161, s[20:21]
	v_add_u32_e32 v244, 0x400, v161
	global_load_dwordx4 v[196:199], v244, s[20:21]
	v_add_u32_e32 v244, 0x800, v161
	global_load_dwordx4 v[200:203], v244, s[20:21]
	v_add_u32_e32 v244, 0xc00, v161
	global_load_dwordx4 v[204:207], v244, s[20:21]
	v_add_u32_e32 v244, 0x2000, v161
	global_load_dwordx4 v[208:211], v244, s[20:21]
	v_add_u32_e32 v244, 0x2400, v161
	global_load_dwordx4 v[212:215], v244, s[20:21]
	v_add_u32_e32 v244, 0x2800, v161
	global_load_dwordx4 v[216:219], v244, s[20:21]
	v_add_u32_e32 v244, 0x2c00, v161
	global_load_dwordx4 v[220:223], v244, s[20:21]
	s_waitcnt vmcnt(0)
	v_add_f32_e32 v145, v188, v189
	v_add_f32_e32 v145, v190, v145
	v_add_f32_e32 v145, v191, v145
	v_add_f32_e32 v155, v196, v197
	v_add_f32_e32 v155, v198, v155
	v_add_f32_e32 v155, v199, v155
	v_add_f32_e32 v159, v200, v201
	v_add_f32_e32 v159, v202, v159
	v_add_f32_e32 v159, v203, v159
	v_add_f32_e32 v163, v204, v205
	v_add_f32_e32 v163, v206, v163
	v_add_f32_e32 v163, v207, v163
	v_add_f32_e32 v165, v208, v209
	v_add_f32_e32 v165, v210, v165
	v_add_f32_e32 v165, v211, v165
	v_add_f32_e32 v171, v212, v213
	v_add_f32_e32 v171, v214, v171
	v_add_f32_e32 v171, v215, v171
	v_add_f32_e32 v193, v216, v217
	v_add_f32_e32 v193, v218, v193
	v_add_f32_e32 v193, v219, v193
	v_add_f32_e32 v241, v220, v221
	v_add_f32_e32 v241, v222, v241
	v_add_f32_e32 v241, v223, v241
	s_nop 1
	ds_bpermute_b32 v188, v166, v145
	ds_bpermute_b32 v196, v166, v155
	ds_bpermute_b32 v200, v166, v159
	ds_bpermute_b32 v204, v166, v163
	ds_bpermute_b32 v208, v166, v165
	ds_bpermute_b32 v212, v166, v171
	ds_bpermute_b32 v216, v166, v193
	ds_bpermute_b32 v220, v166, v241
	s_waitcnt lgkmcnt(0)
	v_add_f32_e32 v145, v145, v188
	v_add_f32_e32 v155, v155, v196
	v_add_f32_e32 v159, v159, v200
	v_add_f32_e32 v163, v163, v204
	v_add_f32_e32 v165, v165, v208
	v_add_f32_e32 v171, v171, v212
	v_add_f32_e32 v193, v193, v216
	v_add_f32_e32 v241, v241, v220
	s_nop 1
	ds_bpermute_b32 v188, v168, v145
	ds_bpermute_b32 v196, v168, v155
	ds_bpermute_b32 v200, v168, v159
	ds_bpermute_b32 v204, v168, v163
	ds_bpermute_b32 v208, v168, v165
	ds_bpermute_b32 v212, v168, v171
	ds_bpermute_b32 v216, v168, v193
	ds_bpermute_b32 v220, v168, v241
	s_waitcnt lgkmcnt(0)
	v_add_f32_e32 v145, v145, v188
	v_add_f32_e32 v155, v155, v196
	v_add_f32_e32 v159, v159, v200
	v_add_f32_e32 v163, v163, v204
	v_add_f32_e32 v165, v165, v208
	v_add_f32_e32 v171, v171, v212
	v_add_f32_e32 v193, v193, v216
	v_add_f32_e32 v241, v241, v220
	v_mul_f32_e32 v145, 0x3a800000, v145
	v_mul_f32_e32 v155, 0x3a800000, v155
	v_mul_f32_e32 v159, 0x3a800000, v159
	v_mul_f32_e32 v163, 0x3a800000, v163
	v_mul_f32_e32 v165, 0x3a800000, v165
	v_mul_f32_e32 v171, 0x3a800000, v171
	v_mul_f32_e32 v193, 0x3a800000, v193
	v_mul_f32_e32 v241, 0x3a800000, v241
	v_add_f32_e32 v145, 0x358637bd, v145
	v_add_f32_e32 v155, 0x358637bd, v155
	v_add_f32_e32 v159, 0x358637bd, v159
	v_add_f32_e32 v163, 0x358637bd, v163
	v_add_f32_e32 v165, 0x358637bd, v165
	v_add_f32_e32 v171, 0x358637bd, v171
	v_add_f32_e32 v193, 0x358637bd, v193
	v_add_f32_e32 v241, 0x358637bd, v241
	v_rsq_f32_e32 v144, v145
	v_rsq_f32_e32 v154, v155
	v_rsq_f32_e32 v158, v159
	v_rsq_f32_e32 v162, v163
	v_rsq_f32_e32 v164, v165
	v_rsq_f32_e32 v170, v171
	v_rsq_f32_e32 v192, v193
	v_rsq_f32_e32 v240, v241
	s_nop 0
	v_mul_f32_e32 v144, 0x3f000000, v144
	v_mul_f32_e32 v154, 0x3f000000, v154
	v_mul_f32_e32 v158, 0x3f000000, v158
	v_mul_f32_e32 v162, 0x3f000000, v162
	v_mul_f32_e32 v164, 0x3f000000, v164
	v_mul_f32_e32 v170, 0x3f000000, v170
	v_mul_f32_e32 v192, 0x3f000000, v192
	v_mul_f32_e32 v240, 0x3f000000, v240
	v_add_u32_e32 v244, 0x10000, v153
	global_load_dwordx4 v[188:191], v244, s[66:67]
	global_load_dwordx4 v[196:199], v244, s[66:67] offset:256
	v_add_u32_e32 v244, 0x18000, v153
	global_load_dwordx4 v[200:203], v244, s[66:67]
	global_load_dwordx4 v[204:207], v244, s[66:67] offset:256
	v_add_u32_e32 v244, 0x40000, v153
	global_load_dwordx4 v[208:211], v244, s[66:67]
	global_load_dwordx4 v[212:215], v244, s[66:67] offset:256
	v_add_u32_e32 v244, 0x48000, v153
	global_load_dwordx4 v[216:219], v244, s[66:67]
	global_load_dwordx4 v[220:223], v244, s[66:67] offset:256
	v_lshlrev_b32_e32 v242, 16, v224
	v_and_b32_e32 v243, 0xffff0000, v224
	v_pk_mul_f32 v[124:125], v[124:125], v[144:145] op_sel_hi:[1,0]
	v_pk_fma_f32 v[124:125], v[124:125], v[172:173], v[242:243]
	v_lshlrev_b32_e32 v244, 16, v225
	v_and_b32_e32 v245, 0xffff0000, v225
	v_pk_mul_f32 v[126:127], v[126:127], v[144:145] op_sel_hi:[1,0]
	v_pk_fma_f32 v[126:127], v[126:127], v[174:175], v[244:245]
	v_lshlrev_b32_e32 v242, 16, v226
	v_and_b32_e32 v243, 0xffff0000, v226
	v_pk_mul_f32 v[120:121], v[120:121], v[144:145] op_sel_hi:[1,0]
	v_pk_fma_f32 v[120:121], v[120:121], v[176:177], v[242:243]
	v_lshlrev_b32_e32 v244, 16, v227
	v_and_b32_e32 v245, 0xffff0000, v227
	v_pk_mul_f32 v[122:123], v[122:123], v[144:145] op_sel_hi:[1,0]
	v_pk_fma_f32 v[122:123], v[122:123], v[178:179], v[244:245]
	v_lshlrev_b32_e32 v242, 16, v228
	v_and_b32_e32 v243, 0xffff0000, v228
	v_pk_mul_f32 v[116:117], v[116:117], v[144:145] op_sel_hi:[1,0]
	v_pk_fma_f32 v[116:117], v[116:117], v[180:181], v[242:243]
	v_lshlrev_b32_e32 v244, 16, v229
	v_and_b32_e32 v245, 0xffff0000, v229
	v_pk_mul_f32 v[118:119], v[118:119], v[144:145] op_sel_hi:[1,0]
	v_pk_fma_f32 v[118:119], v[118:119], v[182:183], v[244:245]
	v_lshlrev_b32_e32 v242, 16, v230
	v_and_b32_e32 v243, 0xffff0000, v230
	v_pk_mul_f32 v[112:113], v[112:113], v[144:145] op_sel_hi:[1,0]
	v_pk_fma_f32 v[112:113], v[112:113], v[184:185], v[242:243]
; __device__ __forceinline__ float bf_lo(unsigned w) { return __uint_as_float(w << 16); }
; __device__ __forceinline__ float bf_hi(unsigned w) { return __uint_as_float(w & 0xffff0000u); }
; __device__ __forceinline__ unsigned pk2(float lo, float hi) { bf16x2_t r = __builtin_convertvector((f32x2_t){lo, hi}, bf16x2_t); return __builtin_bit_cast(unsigned, r); }
; template <bool SRC_F32, bool FINAL, int R> __device__ __forceinline__ void ew_compute(const EwSet<SRC_F32, R>& S, int rb, const f32x4 (&g)[4], bf16* hb_out, float* out32, float scale, float* rs_out, int lane) {
;     ...
;         float s2 = 0.f;
; #pragma unroll
;         for (int j = 0; j < 4; ++j) {
;             f32x4 h;
;             if constexpr (SRC_F32) h = S.h32[i][j];
;             else { const v2u hw = S.hb[i][j]; h.x = bf_lo(hw.x); h.y = bf_hi(hw.x); h.z = bf_lo(hw.y); h.w = bf_hi(hw.y); }
;             const v2u fw = S.fw[i][j];
;             f32x4 v; v.x = h.x + bf_lo(fw.x) * rs * g[j].x; v.y = h.y + bf_hi(fw.x) * rs * g[j].y; v.z = h.z + bf_lo(fw.y) * rs * g[j].z; v.w = h.w + bf_hi(fw.y) * rs * g[j].w;
;             if (FINAL) __builtin_nontemporal_store(v, (f32x4*)(out32 + (size_t)(rb + i) * D) + lane + 64 * j);
;             else { v2u o; o.x = pk2(v.x, v.y); o.y = pk2(v.z, v.w); ((v2u*)(hb_out + (size_t)(rb + i) * D) + lane)[64 * j] = o; s2 += (v.x * v.x + v.y * v.y) + (v.z * v.z + v.w * v.w); }
;         }
;         if (!FINAL) { const float tot = wave_sum(s2); if (lane == 0) rs_out[rb + i] = 1.0f / sqrtf(tot * (1.f / D) + EPS); }
	v_lshlrev_b32_e32 v244, 16, v231
	v_and_b32_e32 v245, 0xffff0000, v231
	v_pk_mul_f32 v[114:115], v[114:115], v[144:145] op_sel_hi:[1,0]
	v_pk_fma_f32 v[114:115], v[114:115], v[186:187], v[244:245]
	v_pk_mul_f32 v[242:243], v[124:125], v[124:125]
	v_pk_fma_f32 v[242:243], v[126:127], v[126:127], v[242:243]
	v_pk_fma_f32 v[242:243], v[120:121], v[120:121], v[242:243]
	v_pk_fma_f32 v[242:243], v[122:123], v[122:123], v[242:243]
	v_pk_fma_f32 v[242:243], v[116:117], v[116:117], v[242:243]
	v_pk_fma_f32 v[242:243], v[118:119], v[118:119], v[242:243]
	v_pk_fma_f32 v[242:243], v[112:113], v[112:113], v[242:243]
	v_pk_fma_f32 v[242:243], v[114:115], v[114:115], v[242:243]
	v_add_f32_e32 v145, v242, v243
	v_cvt_pk_bf16_f32 v224, v124, v125
	v_cvt_pk_bf16_f32 v225, v126, v127
	v_cvt_pk_bf16_f32 v226, v120, v121
	v_cvt_pk_bf16_f32 v227, v122, v123
	v_cvt_pk_bf16_f32 v228, v116, v117
	v_cvt_pk_bf16_f32 v229, v118, v119
	v_cvt_pk_bf16_f32 v230, v112, v113
	v_cvt_pk_bf16_f32 v231, v114, v115
	s_nop 0
	global_store_dwordx4 v153, v[224:227], s[66:67]
	global_store_dwordx4 v153, v[228:231], s[66:67] offset:256
	v_lshlrev_b32_e32 v242, 16, v232
	v_and_b32_e32 v243, 0xffff0000, v232
	v_pk_mul_f32 v[108:109], v[108:109], v[154:155] op_sel_hi:[1,0]
	v_pk_fma_f32 v[108:109], v[108:109], v[172:173], v[242:243]
	v_lshlrev_b32_e32 v244, 16, v233
	v_and_b32_e32 v245, 0xffff0000, v233
	v_pk_mul_f32 v[110:111], v[110:111], v[154:155] op_sel_hi:[1,0]
	v_pk_fma_f32 v[110:111], v[110:111], v[174:175], v[244:245]
	v_lshlrev_b32_e32 v242, 16, v234
	v_and_b32_e32 v243, 0xffff0000, v234
	v_pk_mul_f32 v[104:105], v[104:105], v[154:155] op_sel_hi:[1,0]
	v_pk_fma_f32 v[104:105], v[104:105], v[176:177], v[242:243]
	v_lshlrev_b32_e32 v244, 16, v235
	v_and_b32_e32 v245, 0xffff0000, v235
	v_pk_mul_f32 v[106:107], v[106:107], v[154:155] op_sel_hi:[1,0]
	v_pk_fma_f32 v[106:107], v[106:107], v[178:179], v[244:245]
	v_lshlrev_b32_e32 v242, 16, v236
	v_and_b32_e32 v243, 0xffff0000, v236
	v_pk_mul_f32 v[100:101], v[100:101], v[154:155] op_sel_hi:[1,0]
	v_pk_fma_f32 v[100:101], v[100:101], v[180:181], v[242:243]
	v_lshlrev_b32_e32 v244, 16, v237
	v_and_b32_e32 v245, 0xffff0000, v237
	v_pk_mul_f32 v[102:103], v[102:103], v[154:155] op_sel_hi:[1,0]
	v_pk_fma_f32 v[102:103], v[102:103], v[182:183], v[244:245]
	v_lshlrev_b32_e32 v242, 16, v238
	v_and_b32_e32 v243, 0xffff0000, v238
	v_pk_mul_f32 v[96:97], v[96:97], v[154:155] op_sel_hi:[1,0]
	v_pk_fma_f32 v[96:97], v[96:97], v[184:185], v[242:243]
	v_lshlrev_b32_e32 v244, 16, v239
	v_and_b32_e32 v245, 0xffff0000, v239
	v_pk_mul_f32 v[98:99], v[98:99], v[154:155] op_sel_hi:[1,0]
	v_pk_fma_f32 v[98:99], v[98:99], v[186:187], v[244:245]
	v_pk_mul_f32 v[242:243], v[108:109], v[108:109]
	v_pk_fma_f32 v[242:243], v[110:111], v[110:111], v[242:243]
	v_pk_fma_f32 v[242:243], v[104:105], v[104:105], v[242:243]
	v_pk_fma_f32 v[242:243], v[106:107], v[106:107], v[242:243]
	v_pk_fma_f32 v[242:243], v[100:101], v[100:101], v[242:243]
	v_pk_fma_f32 v[242:243], v[102:103], v[102:103], v[242:243]
	v_pk_fma_f32 v[242:243], v[96:97], v[96:97], v[242:243]
	v_pk_fma_f32 v[242:243], v[98:99], v[98:99], v[242:243]
	v_add_f32_e32 v155, v242, v243
	v_cvt_pk_bf16_f32 v232, v108, v109
	v_cvt_pk_bf16_f32 v233, v110, v111
	v_cvt_pk_bf16_f32 v234, v104, v105
	v_cvt_pk_bf16_f32 v235, v106, v107
	v_cvt_pk_bf16_f32 v236, v100, v101
	v_cvt_pk_bf16_f32 v237, v102, v103
	v_cvt_pk_bf16_f32 v238, v96, v97
	v_cvt_pk_bf16_f32 v239, v98, v99
	v_add_u32_e32 v244, 0x8000, v153
	s_nop 0
	global_store_dwordx4 v244, v[232:235], s[66:67]
	global_store_dwordx4 v244, v[236:239], s[66:67] offset:256
	s_nop 1
	v_add_u32_e32 v244, 0x50000, v153
	global_load_dwordx4 v[224:227], v244, s[66:67]
	global_load_dwordx4 v[228:231], v244, s[66:67] offset:256
	v_add_u32_e32 v244, 0x58000, v153
	global_load_dwordx4 v[232:235], v244, s[66:67]
	global_load_dwordx4 v[236:239], v244, s[66:67] offset:256
	s_waitcnt vmcnt(14)
	v_lshlrev_b32_e32 v242, 16, v188
	v_and_b32_e32 v243, 0xffff0000, v188
	v_pk_mul_f32 v[92:93], v[92:93], v[158:159] op_sel_hi:[1,0]
	v_pk_fma_f32 v[92:93], v[92:93], v[172:173], v[242:243]
	v_lshlrev_b32_e32 v244, 16, v189
	v_and_b32_e32 v245, 0xffff0000, v189
	v_pk_mul_f32 v[94:95], v[94:95], v[158:159] op_sel_hi:[1,0]
	v_pk_fma_f32 v[94:95], v[94:95], v[174:175], v[244:245]
	v_lshlrev_b32_e32 v242, 16, v190
	v_and_b32_e32 v243, 0xffff0000, v190
	v_pk_mul_f32 v[88:89], v[88:89], v[158:159] op_sel_hi:[1,0]
	v_pk_fma_f32 v[88:89], v[88:89], v[176:177], v[242:243]
	v_lshlrev_b32_e32 v244, 16, v191
	v_and_b32_e32 v245, 0xffff0000, v191
	v_pk_mul_f32 v[90:91], v[90:91], v[158:159] op_sel_hi:[1,0]
	v_pk_fma_f32 v[90:91], v[90:91], v[178:179], v[244:245]
	v_lshlrev_b32_e32 v242, 16, v196
	v_and_b32_e32 v243, 0xffff0000, v196
	v_pk_mul_f32 v[84:85], v[84:85], v[158:159] op_sel_hi:[1,0]
	v_pk_fma_f32 v[84:85], v[84:85], v[180:181], v[242:243]
	v_lshlrev_b32_e32 v244, 16, v197
	v_and_b32_e32 v245, 0xffff0000, v197
	v_pk_mul_f32 v[86:87], v[86:87], v[158:159] op_sel_hi:[1,0]
	v_pk_fma_f32 v[86:87], v[86:87], v[182:183], v[244:245]
	v_lshlrev_b32_e32 v242, 16, v198
	v_and_b32_e32 v243, 0xffff0000, v198
	v_pk_mul_f32 v[80:81], v[80:81], v[158:159] op_sel_hi:[1,0]
	v_pk_fma_f32 v[80:81], v[80:81], v[184:185], v[242:243]
	v_lshlrev_b32_e32 v244, 16, v199
	v_and_b32_e32 v245, 0xffff0000, v199
	v_pk_mul_f32 v[82:83], v[82:83], v[158:159] op_sel_hi:[1,0]
	v_pk_fma_f32 v[82:83], v[82:83], v[186:187], v[244:245]
	v_pk_mul_f32 v[242:243], v[92:93], v[92:93]
	v_pk_fma_f32 v[242:243], v[94:95], v[94:95], v[242:243]
	v_pk_fma_f32 v[242:243], v[88:89], v[88:89], v[242:243]
	v_pk_fma_f32 v[242:243], v[90:91], v[90:91], v[242:243]
	v_pk_fma_f32 v[242:243], v[84:85], v[84:85], v[242:243]
	v_pk_fma_f32 v[242:243], v[86:87], v[86:87], v[242:243]
	v_pk_fma_f32 v[242:243], v[80:81], v[80:81], v[242:243]
	v_pk_fma_f32 v[242:243], v[82:83], v[82:83], v[242:243]
	v_add_f32_e32 v159, v242, v243
	v_cvt_pk_bf16_f32 v188, v92, v93
	v_cvt_pk_bf16_f32 v189, v94, v95
	v_cvt_pk_bf16_f32 v190, v88, v89
	v_cvt_pk_bf16_f32 v191, v90, v91
	v_cvt_pk_bf16_f32 v196, v84, v85
	v_cvt_pk_bf16_f32 v197, v86, v87
	v_cvt_pk_bf16_f32 v198, v80, v81
	v_cvt_pk_bf16_f32 v199, v82, v83
	v_add_u32_e32 v244, 0x10000, v153
	s_nop 0
	global_store_dwordx4 v244, v[188:191], s[66:67]
	global_store_dwordx4 v244, v[196:199], s[66:67] offset:256
	s_waitcnt vmcnt(14)
; __device__ __forceinline__ float bf_lo(unsigned w) { return __uint_as_float(w << 16); }
; __device__ __forceinline__ float bf_hi(unsigned w) { return __uint_as_float(w & 0xffff0000u); }
; __device__ __forceinline__ unsigned pk2(float lo, float hi) { bf16x2_t r = __builtin_convertvector((f32x2_t){lo, hi}, bf16x2_t); return __builtin_bit_cast(unsigned, r); }
; template <bool SRC_F32, bool FINAL, int R> __device__ __forceinline__ void ew_compute(const EwSet<SRC_F32, R>& S, int rb, const f32x4 (&g)[4], bf16* hb_out, float* out32, float scale, float* rs_out, int lane) {
;     ...
;         float s2 = 0.f;
; #pragma unroll
;         for (int j = 0; j < 4; ++j) {
;             f32x4 h;
;             if constexpr (SRC_F32) h = S.h32[i][j];
;             else { const v2u hw = S.hb[i][j]; h.x = bf_lo(hw.x); h.y = bf_hi(hw.x); h.z = bf_lo(hw.y); h.w = bf_hi(hw.y); }
;             const v2u fw = S.fw[i][j];
;             f32x4 v; v.x = h.x + bf_lo(fw.x) * rs * g[j].x; v.y = h.y + bf_hi(fw.x) * rs * g[j].y; v.z = h.z + bf_lo(fw.y) * rs * g[j].z; v.w = h.w + bf_hi(fw.y) * rs * g[j].w;
;             if (FINAL) __builtin_nontemporal_store(v, (f32x4*)(out32 + (size_t)(rb + i) * D) + lane + 64 * j);
;             else { v2u o; o.x = pk2(v.x, v.y); o.y = pk2(v.z, v.w); ((v2u*)(hb_out + (size_t)(rb + i) * D) + lane)[64 * j] = o; s2 += (v.x * v.x + v.y * v.y) + (v.z * v.z + v.w * v.w); }
;         }
;         if (!FINAL) { const float tot = wave_sum(s2); if (lane == 0) rs_out[rb + i] = 1.0f / sqrtf(tot * (1.f / D) + EPS); }
	v_lshlrev_b32_e32 v242, 16, v200
	v_and_b32_e32 v243, 0xffff0000, v200
	v_pk_mul_f32 v[76:77], v[76:77], v[162:163] op_sel_hi:[1,0]
	v_pk_fma_f32 v[76:77], v[76:77], v[172:173], v[242:243]
	v_lshlrev_b32_e32 v244, 16, v201
	v_and_b32_e32 v245, 0xffff0000, v201
	v_pk_mul_f32 v[78:79], v[78:79], v[162:163] op_sel_hi:[1,0]
	v_pk_fma_f32 v[78:79], v[78:79], v[174:175], v[244:245]
	v_lshlrev_b32_e32 v242, 16, v202
	v_and_b32_e32 v243, 0xffff0000, v202
	v_pk_mul_f32 v[72:73], v[72:73], v[162:163] op_sel_hi:[1,0]
	v_pk_fma_f32 v[72:73], v[72:73], v[176:177], v[242:243]
	v_lshlrev_b32_e32 v244, 16, v203
	v_and_b32_e32 v245, 0xffff0000, v203
	v_pk_mul_f32 v[74:75], v[74:75], v[162:163] op_sel_hi:[1,0]
	v_pk_fma_f32 v[74:75], v[74:75], v[178:179], v[244:245]
	v_lshlrev_b32_e32 v242, 16, v204
	v_and_b32_e32 v243, 0xffff0000, v204
	v_pk_mul_f32 v[68:69], v[68:69], v[162:163] op_sel_hi:[1,0]
	v_pk_fma_f32 v[68:69], v[68:69], v[180:181], v[242:243]
	v_lshlrev_b32_e32 v244, 16, v205
	v_and_b32_e32 v245, 0xffff0000, v205
	v_pk_mul_f32 v[70:71], v[70:71], v[162:163] op_sel_hi:[1,0]
	v_pk_fma_f32 v[70:71], v[70:71], v[182:183], v[244:245]
	v_lshlrev_b32_e32 v242, 16, v206
	v_and_b32_e32 v243, 0xffff0000, v206
	v_pk_mul_f32 v[64:65], v[64:65], v[162:163] op_sel_hi:[1,0]
	v_pk_fma_f32 v[64:65], v[64:65], v[184:185], v[242:243]
	v_lshlrev_b32_e32 v244, 16, v207
	v_and_b32_e32 v245, 0xffff0000, v207
	v_pk_mul_f32 v[66:67], v[66:67], v[162:163] op_sel_hi:[1,0]
	v_pk_fma_f32 v[66:67], v[66:67], v[186:187], v[244:245]
	v_pk_mul_f32 v[242:243], v[76:77], v[76:77]
	v_pk_fma_f32 v[242:243], v[78:79], v[78:79], v[242:243]
	v_pk_fma_f32 v[242:243], v[72:73], v[72:73], v[242:243]
	v_pk_fma_f32 v[242:243], v[74:75], v[74:75], v[242:243]
	v_pk_fma_f32 v[242:243], v[68:69], v[68:69], v[242:243]
	v_pk_fma_f32 v[242:243], v[70:71], v[70:71], v[242:243]
	v_pk_fma_f32 v[242:243], v[64:65], v[64:65], v[242:243]
	v_pk_fma_f32 v[242:243], v[66:67], v[66:67], v[242:243]
	v_add_f32_e32 v163, v242, v243
	v_cvt_pk_bf16_f32 v200, v76, v77
	v_cvt_pk_bf16_f32 v201, v78, v79
	v_cvt_pk_bf16_f32 v202, v72, v73
	v_cvt_pk_bf16_f32 v203, v74, v75
	v_cvt_pk_bf16_f32 v204, v68, v69
	v_cvt_pk_bf16_f32 v205, v70, v71
	v_cvt_pk_bf16_f32 v206, v64, v65
	v_cvt_pk_bf16_f32 v207, v66, v67
	v_add_u32_e32 v244, 0x18000, v153
	s_nop 0
	global_store_dwordx4 v244, v[200:203], s[66:67]
	global_store_dwordx4 v244, v[204:207], s[66:67] offset:256
	s_waitcnt vmcnt(14)
	v_lshlrev_b32_e32 v242, 16, v208
	v_and_b32_e32 v243, 0xffff0000, v208
	v_pk_mul_f32 v[60:61], v[60:61], v[164:165] op_sel_hi:[1,0]
	v_pk_fma_f32 v[60:61], v[60:61], v[172:173], v[242:243]
	v_lshlrev_b32_e32 v244, 16, v209
	v_and_b32_e32 v245, 0xffff0000, v209
	v_pk_mul_f32 v[62:63], v[62:63], v[164:165] op_sel_hi:[1,0]
	v_pk_fma_f32 v[62:63], v[62:63], v[174:175], v[244:245]
	v_lshlrev_b32_e32 v242, 16, v210
	v_and_b32_e32 v243, 0xffff0000, v210
	v_pk_mul_f32 v[56:57], v[56:57], v[164:165] op_sel_hi:[1,0]
	v_pk_fma_f32 v[56:57], v[56:57], v[176:177], v[242:243]
	v_lshlrev_b32_e32 v244, 16, v211
	v_and_b32_e32 v245, 0xffff0000, v211
	v_pk_mul_f32 v[58:59], v[58:59], v[164:165] op_sel_hi:[1,0]
	v_pk_fma_f32 v[58:59], v[58:59], v[178:179], v[244:245]
	v_lshlrev_b32_e32 v242, 16, v212
	v_and_b32_e32 v243, 0xffff0000, v212
	v_pk_mul_f32 v[52:53], v[52:53], v[164:165] op_sel_hi:[1,0]
	v_pk_fma_f32 v[52:53], v[52:53], v[180:181], v[242:243]
	v_lshlrev_b32_e32 v244, 16, v213
	v_and_b32_e32 v245, 0xffff0000, v213
	v_pk_mul_f32 v[54:55], v[54:55], v[164:165] op_sel_hi:[1,0]
	v_pk_fma_f32 v[54:55], v[54:55], v[182:183], v[244:245]
	v_lshlrev_b32_e32 v242, 16, v214
	v_and_b32_e32 v243, 0xffff0000, v214
	v_pk_mul_f32 v[48:49], v[48:49], v[164:165] op_sel_hi:[1,0]
	v_pk_fma_f32 v[48:49], v[48:49], v[184:185], v[242:243]
	v_lshlrev_b32_e32 v244, 16, v215
	v_and_b32_e32 v245, 0xffff0000, v215
	v_pk_mul_f32 v[50:51], v[50:51], v[164:165] op_sel_hi:[1,0]
	v_pk_fma_f32 v[50:51], v[50:51], v[186:187], v[244:245]
	v_pk_mul_f32 v[242:243], v[60:61], v[60:61]
	v_pk_fma_f32 v[242:243], v[62:63], v[62:63], v[242:243]
	v_pk_fma_f32 v[242:243], v[56:57], v[56:57], v[242:243]
	v_pk_fma_f32 v[242:243], v[58:59], v[58:59], v[242:243]
	v_pk_fma_f32 v[242:243], v[52:53], v[52:53], v[242:243]
	v_pk_fma_f32 v[242:243], v[54:55], v[54:55], v[242:243]
	v_pk_fma_f32 v[242:243], v[48:49], v[48:49], v[242:243]
	v_pk_fma_f32 v[242:243], v[50:51], v[50:51], v[242:243]
	v_add_f32_e32 v165, v242, v243
	v_cvt_pk_bf16_f32 v208, v60, v61
	v_cvt_pk_bf16_f32 v209, v62, v63
	v_cvt_pk_bf16_f32 v210, v56, v57
	v_cvt_pk_bf16_f32 v211, v58, v59
	v_cvt_pk_bf16_f32 v212, v52, v53
	v_cvt_pk_bf16_f32 v213, v54, v55
	v_cvt_pk_bf16_f32 v214, v48, v49
	v_cvt_pk_bf16_f32 v215, v50, v51
	v_add_u32_e32 v244, 0x40000, v153
	s_nop 0
	global_store_dwordx4 v244, v[208:211], s[66:67]
	global_store_dwordx4 v244, v[212:215], s[66:67] offset:256
	s_waitcnt vmcnt(14)
; __device__ __forceinline__ float bf_lo(unsigned w) { return __uint_as_float(w << 16); }
; __device__ __forceinline__ float bf_hi(unsigned w) { return __uint_as_float(w & 0xffff0000u); }
; __device__ __forceinline__ unsigned pk2(float lo, float hi) { bf16x2_t r = __builtin_convertvector((f32x2_t){lo, hi}, bf16x2_t); return __builtin_bit_cast(unsigned, r); }
; template <bool SRC_F32, bool FINAL, int R> __device__ __forceinline__ void ew_compute(const EwSet<SRC_F32, R>& S, int rb, const f32x4 (&g)[4], bf16* hb_out, float* out32, float scale, float* rs_out, int lane) {
;     ...
;         float s2 = 0.f;
; #pragma unroll
;         for (int j = 0; j < 4; ++j) {
;             f32x4 h;
;             if constexpr (SRC_F32) h = S.h32[i][j];
;             else { const v2u hw = S.hb[i][j]; h.x = bf_lo(hw.x); h.y = bf_hi(hw.x); h.z = bf_lo(hw.y); h.w = bf_hi(hw.y); }
;             const v2u fw = S.fw[i][j];
;             f32x4 v; v.x = h.x + bf_lo(fw.x) * rs * g[j].x; v.y = h.y + bf_hi(fw.x) * rs * g[j].y; v.z = h.z + bf_lo(fw.y) * rs * g[j].z; v.w = h.w + bf_hi(fw.y) * rs * g[j].w;
;             if (FINAL) __builtin_nontemporal_store(v, (f32x4*)(out32 + (size_t)(rb + i) * D) + lane + 64 * j);
;             else { v2u o; o.x = pk2(v.x, v.y); o.y = pk2(v.z, v.w); ((v2u*)(hb_out + (size_t)(rb + i) * D) + lane)[64 * j] = o; s2 += (v.x * v.x + v.y * v.y) + (v.z * v.z + v.w * v.w); }
;         }
;         if (!FINAL) { const float tot = wave_sum(s2); if (lane == 0) rs_out[rb + i] = 1.0f / sqrtf(tot * (1.f / D) + EPS); }
	v_lshlrev_b32_e32 v242, 16, v216
	v_and_b32_e32 v243, 0xffff0000, v216
	v_pk_mul_f32 v[44:45], v[44:45], v[170:171] op_sel_hi:[1,0]
	v_pk_fma_f32 v[44:45], v[44:45], v[172:173], v[242:243]
	v_lshlrev_b32_e32 v244, 16, v217
	v_and_b32_e32 v245, 0xffff0000, v217
	v_pk_mul_f32 v[46:47], v[46:47], v[170:171] op_sel_hi:[1,0]
	v_pk_fma_f32 v[46:47], v[46:47], v[174:175], v[244:245]
	v_lshlrev_b32_e32 v242, 16, v218
	v_and_b32_e32 v243, 0xffff0000, v218
	v_pk_mul_f32 v[40:41], v[40:41], v[170:171] op_sel_hi:[1,0]
	v_pk_fma_f32 v[40:41], v[40:41], v[176:177], v[242:243]
	v_lshlrev_b32_e32 v244, 16, v219
	v_and_b32_e32 v245, 0xffff0000, v219
	v_pk_mul_f32 v[42:43], v[42:43], v[170:171] op_sel_hi:[1,0]
	v_pk_fma_f32 v[42:43], v[42:43], v[178:179], v[244:245]
	v_lshlrev_b32_e32 v242, 16, v220
	v_and_b32_e32 v243, 0xffff0000, v220
	v_pk_mul_f32 v[36:37], v[36:37], v[170:171] op_sel_hi:[1,0]
	v_pk_fma_f32 v[36:37], v[36:37], v[180:181], v[242:243]
	v_lshlrev_b32_e32 v244, 16, v221
	v_and_b32_e32 v245, 0xffff0000, v221
	v_pk_mul_f32 v[38:39], v[38:39], v[170:171] op_sel_hi:[1,0]
	v_pk_fma_f32 v[38:39], v[38:39], v[182:183], v[244:245]
	v_lshlrev_b32_e32 v242, 16, v222
	v_and_b32_e32 v243, 0xffff0000, v222
	v_pk_mul_f32 v[32:33], v[32:33], v[170:171] op_sel_hi:[1,0]
	v_pk_fma_f32 v[32:33], v[32:33], v[184:185], v[242:243]
	v_lshlrev_b32_e32 v244, 16, v223
	v_and_b32_e32 v245, 0xffff0000, v223
	v_pk_mul_f32 v[34:35], v[34:35], v[170:171] op_sel_hi:[1,0]
	v_pk_fma_f32 v[34:35], v[34:35], v[186:187], v[244:245]
	v_pk_mul_f32 v[242:243], v[44:45], v[44:45]
	v_pk_fma_f32 v[242:243], v[46:47], v[46:47], v[242:243]
	v_pk_fma_f32 v[242:243], v[40:41], v[40:41], v[242:243]
	v_pk_fma_f32 v[242:243], v[42:43], v[42:43], v[242:243]
	v_pk_fma_f32 v[242:243], v[36:37], v[36:37], v[242:243]
	v_pk_fma_f32 v[242:243], v[38:39], v[38:39], v[242:243]
	v_pk_fma_f32 v[242:243], v[32:33], v[32:33], v[242:243]
	v_pk_fma_f32 v[242:243], v[34:35], v[34:35], v[242:243]
	v_add_f32_e32 v171, v242, v243
	v_cvt_pk_bf16_f32 v216, v44, v45
	v_cvt_pk_bf16_f32 v217, v46, v47
	v_cvt_pk_bf16_f32 v218, v40, v41
	v_cvt_pk_bf16_f32 v219, v42, v43
	v_cvt_pk_bf16_f32 v220, v36, v37
	v_cvt_pk_bf16_f32 v221, v38, v39
	v_cvt_pk_bf16_f32 v222, v32, v33
	v_cvt_pk_bf16_f32 v223, v34, v35
	v_add_u32_e32 v244, 0x48000, v153
	s_nop 0
	global_store_dwordx4 v244, v[216:219], s[66:67]
	global_store_dwordx4 v244, v[220:223], s[66:67] offset:256
	s_waitcnt vmcnt(10)
	v_lshlrev_b32_e32 v242, 16, v224
	v_and_b32_e32 v243, 0xffff0000, v224
	v_pk_mul_f32 v[28:29], v[28:29], v[192:193] op_sel_hi:[1,0]
	v_pk_fma_f32 v[28:29], v[28:29], v[172:173], v[242:243]
	v_lshlrev_b32_e32 v244, 16, v225
	v_and_b32_e32 v245, 0xffff0000, v225
	v_pk_mul_f32 v[30:31], v[30:31], v[192:193] op_sel_hi:[1,0]
	v_pk_fma_f32 v[30:31], v[30:31], v[174:175], v[244:245]
	v_lshlrev_b32_e32 v242, 16, v226
	v_and_b32_e32 v243, 0xffff0000, v226
	v_pk_mul_f32 v[24:25], v[24:25], v[192:193] op_sel_hi:[1,0]
	v_pk_fma_f32 v[24:25], v[24:25], v[176:177], v[242:243]
	v_lshlrev_b32_e32 v244, 16, v227
	v_and_b32_e32 v245, 0xffff0000, v227
	v_pk_mul_f32 v[26:27], v[26:27], v[192:193] op_sel_hi:[1,0]
	v_pk_fma_f32 v[26:27], v[26:27], v[178:179], v[244:245]
	v_lshlrev_b32_e32 v242, 16, v228
	v_and_b32_e32 v243, 0xffff0000, v228
	v_pk_mul_f32 v[20:21], v[20:21], v[192:193] op_sel_hi:[1,0]
	v_pk_fma_f32 v[20:21], v[20:21], v[180:181], v[242:243]
	v_lshlrev_b32_e32 v244, 16, v229
	v_and_b32_e32 v245, 0xffff0000, v229
	v_pk_mul_f32 v[22:23], v[22:23], v[192:193] op_sel_hi:[1,0]
	v_pk_fma_f32 v[22:23], v[22:23], v[182:183], v[244:245]
	v_lshlrev_b32_e32 v242, 16, v230
	v_and_b32_e32 v243, 0xffff0000, v230
	v_pk_mul_f32 v[16:17], v[16:17], v[192:193] op_sel_hi:[1,0]
	v_pk_fma_f32 v[16:17], v[16:17], v[184:185], v[242:243]
	v_lshlrev_b32_e32 v244, 16, v231
	v_and_b32_e32 v245, 0xffff0000, v231
	v_pk_mul_f32 v[18:19], v[18:19], v[192:193] op_sel_hi:[1,0]
	v_pk_fma_f32 v[18:19], v[18:19], v[186:187], v[244:245]
	v_pk_mul_f32 v[242:243], v[28:29], v[28:29]
	v_pk_fma_f32 v[242:243], v[30:31], v[30:31], v[242:243]
	v_pk_fma_f32 v[242:243], v[24:25], v[24:25], v[242:243]
	v_pk_fma_f32 v[242:243], v[26:27], v[26:27], v[242:243]
	v_pk_fma_f32 v[242:243], v[20:21], v[20:21], v[242:243]
	v_pk_fma_f32 v[242:243], v[22:23], v[22:23], v[242:243]
	v_pk_fma_f32 v[242:243], v[16:17], v[16:17], v[242:243]
	v_pk_fma_f32 v[242:243], v[18:19], v[18:19], v[242:243]
	v_add_f32_e32 v193, v242, v243
	v_cvt_pk_bf16_f32 v224, v28, v29
	v_cvt_pk_bf16_f32 v225, v30, v31
	v_cvt_pk_bf16_f32 v226, v24, v25
	v_cvt_pk_bf16_f32 v227, v26, v27
	v_cvt_pk_bf16_f32 v228, v20, v21
	v_cvt_pk_bf16_f32 v229, v22, v23
	v_cvt_pk_bf16_f32 v230, v16, v17
	v_cvt_pk_bf16_f32 v231, v18, v19
	v_add_u32_e32 v244, 0x50000, v153
	s_nop 0
	global_store_dwordx4 v244, v[224:227], s[66:67]
	global_store_dwordx4 v244, v[228:231], s[66:67] offset:256
	s_waitcnt vmcnt(10)
; __device__ __forceinline__ float bf_lo(unsigned w) { return __uint_as_float(w << 16); }
; __device__ __forceinline__ float bf_hi(unsigned w) { return __uint_as_float(w & 0xffff0000u); }
; __device__ __forceinline__ unsigned pk2(float lo, float hi) { bf16x2_t r = __builtin_convertvector((f32x2_t){lo, hi}, bf16x2_t); return __builtin_bit_cast(unsigned, r); }
; template <bool SRC_F32, bool FINAL, int R> __device__ __forceinline__ void ew_compute(const EwSet<SRC_F32, R>& S, int rb, const f32x4 (&g)[4], bf16* hb_out, float* out32, float scale, float* rs_out, int lane) {
;     ...
;         float s2 = 0.f;
; #pragma unroll
;         for (int j = 0; j < 4; ++j) {
;             f32x4 h;
;             if constexpr (SRC_F32) h = S.h32[i][j];
;             else { const v2u hw = S.hb[i][j]; h.x = bf_lo(hw.x); h.y = bf_hi(hw.x); h.z = bf_lo(hw.y); h.w = bf_hi(hw.y); }
;             const v2u fw = S.fw[i][j];
;             f32x4 v; v.x = h.x + bf_lo(fw.x) * rs * g[j].x; v.y = h.y + bf_hi(fw.x) * rs * g[j].y; v.z = h.z + bf_lo(fw.y) * rs * g[j].z; v.w = h.w + bf_hi(fw.y) * rs * g[j].w;
;             if (FINAL) __builtin_nontemporal_store(v, (f32x4*)(out32 + (size_t)(rb + i) * D) + lane + 64 * j);
;             else { v2u o; o.x = pk2(v.x, v.y); o.y = pk2(v.z, v.w); ((v2u*)(hb_out + (size_t)(rb + i) * D) + lane)[64 * j] = o; s2 += (v.x * v.x + v.y * v.y) + (v.z * v.z + v.w * v.w); }
;         }
;         if (!FINAL) { const float tot = wave_sum(s2); if (lane == 0) rs_out[rb + i] = 1.0f / sqrtf(tot * (1.f / D) + EPS); }
;     }
	v_lshlrev_b32_e32 v242, 16, v232
	v_and_b32_e32 v243, 0xffff0000, v232
	v_pk_mul_f32 v[12:13], v[12:13], v[240:241] op_sel_hi:[1,0]
	v_pk_fma_f32 v[12:13], v[12:13], v[172:173], v[242:243]
	v_lshlrev_b32_e32 v244, 16, v233
	v_and_b32_e32 v245, 0xffff0000, v233
	v_pk_mul_f32 v[14:15], v[14:15], v[240:241] op_sel_hi:[1,0]
	v_pk_fma_f32 v[14:15], v[14:15], v[174:175], v[244:245]
	v_lshlrev_b32_e32 v242, 16, v234
	v_and_b32_e32 v243, 0xffff0000, v234
	v_pk_mul_f32 v[8:9], v[8:9], v[240:241] op_sel_hi:[1,0]
	v_pk_fma_f32 v[8:9], v[8:9], v[176:177], v[242:243]
	v_lshlrev_b32_e32 v244, 16, v235
	v_and_b32_e32 v245, 0xffff0000, v235
	v_pk_mul_f32 v[10:11], v[10:11], v[240:241] op_sel_hi:[1,0]
	v_pk_fma_f32 v[10:11], v[10:11], v[178:179], v[244:245]
	v_lshlrev_b32_e32 v242, 16, v236
	v_and_b32_e32 v243, 0xffff0000, v236
	v_pk_mul_f32 v[4:5], v[4:5], v[240:241] op_sel_hi:[1,0]
	v_pk_fma_f32 v[4:5], v[4:5], v[180:181], v[242:243]
	v_lshlrev_b32_e32 v244, 16, v237
	v_and_b32_e32 v245, 0xffff0000, v237
	v_pk_mul_f32 v[6:7], v[6:7], v[240:241] op_sel_hi:[1,0]
	v_pk_fma_f32 v[6:7], v[6:7], v[182:183], v[244:245]
	v_lshlrev_b32_e32 v242, 16, v238
	v_and_b32_e32 v243, 0xffff0000, v238
	v_pk_mul_f32 v[0:1], v[0:1], v[240:241] op_sel_hi:[1,0]
	v_pk_fma_f32 v[0:1], v[0:1], v[184:185], v[242:243]
	v_lshlrev_b32_e32 v244, 16, v239
	v_and_b32_e32 v245, 0xffff0000, v239
	v_pk_mul_f32 v[2:3], v[2:3], v[240:241] op_sel_hi:[1,0]
	v_pk_fma_f32 v[2:3], v[2:3], v[186:187], v[244:245]
	v_pk_mul_f32 v[242:243], v[12:13], v[12:13]
	v_pk_fma_f32 v[242:243], v[14:15], v[14:15], v[242:243]
	v_pk_fma_f32 v[242:243], v[8:9], v[8:9], v[242:243]
	v_pk_fma_f32 v[242:243], v[10:11], v[10:11], v[242:243]
	v_pk_fma_f32 v[242:243], v[4:5], v[4:5], v[242:243]
	v_pk_fma_f32 v[242:243], v[6:7], v[6:7], v[242:243]
	v_pk_fma_f32 v[242:243], v[0:1], v[0:1], v[242:243]
	v_pk_fma_f32 v[242:243], v[2:3], v[2:3], v[242:243]
	v_add_f32_e32 v241, v242, v243
	v_cvt_pk_bf16_f32 v232, v12, v13
	v_cvt_pk_bf16_f32 v233, v14, v15
	v_cvt_pk_bf16_f32 v234, v8, v9
	v_cvt_pk_bf16_f32 v235, v10, v11
	v_cvt_pk_bf16_f32 v236, v4, v5
	v_cvt_pk_bf16_f32 v237, v6, v7
	v_cvt_pk_bf16_f32 v238, v0, v1
	v_cvt_pk_bf16_f32 v239, v2, v3
	v_add_u32_e32 v244, 0x58000, v153
	s_nop 0
	global_store_dwordx4 v244, v[232:235], s[66:67]
	global_store_dwordx4 v244, v[236:239], s[66:67] offset:256
	s_nop 1
	ds_bpermute_b32 v172, v166, v145
	ds_bpermute_b32 v173, v166, v155
	ds_bpermute_b32 v174, v166, v159
	ds_bpermute_b32 v175, v166, v163
	ds_bpermute_b32 v176, v166, v165
	ds_bpermute_b32 v177, v166, v171
	ds_bpermute_b32 v178, v166, v193
	ds_bpermute_b32 v179, v166, v241
	s_waitcnt lgkmcnt(0)
	v_add_f32_e32 v145, v145, v172
	v_add_f32_e32 v155, v155, v173
	v_add_f32_e32 v159, v159, v174
	v_add_f32_e32 v163, v163, v175
	v_add_f32_e32 v165, v165, v176
	v_add_f32_e32 v171, v171, v177
	v_add_f32_e32 v193, v193, v178
	v_add_f32_e32 v241, v241, v179
	s_nop 1
	ds_bpermute_b32 v172, v168, v145
	ds_bpermute_b32 v173, v168, v155
	ds_bpermute_b32 v174, v168, v159
	ds_bpermute_b32 v175, v168, v163
	ds_bpermute_b32 v176, v168, v165
	ds_bpermute_b32 v177, v168, v171
	ds_bpermute_b32 v178, v168, v193
	ds_bpermute_b32 v179, v168, v241
	s_waitcnt lgkmcnt(0)
	v_add_f32_e32 v145, v145, v172
	v_add_f32_e32 v155, v155, v173
	v_add_f32_e32 v159, v159, v174
	v_add_f32_e32 v163, v163, v175
	v_add_f32_e32 v165, v165, v176
	v_add_f32_e32 v171, v171, v177
	v_add_f32_e32 v193, v193, v178
	v_add_f32_e32 v241, v241, v179
	global_store_dword v157, v145, s[78:79]
	v_add_u32_e32 v173, 0x400, v157
	global_store_dword v173, v155, s[78:79]
	v_add_u32_e32 v174, 0x800, v157
	global_store_dword v174, v159, s[78:79]
	v_add_u32_e32 v175, 0xc00, v157
	global_store_dword v175, v163, s[78:79]
	v_add_u32_e32 v176, 0x2000, v157
	global_store_dword v176, v165, s[78:79]
	v_add_u32_e32 v177, 0x2400, v157
	global_store_dword v177, v171, s[78:79]
	v_add_u32_e32 v178, 0x2800, v157
	global_store_dword v178, v193, s[78:79]
	v_add_u32_e32 v179, 0x2c00, v157
	global_store_dword v179, v241, s[78:79]
	s_and_b64 vcc, exec, s[0:1]
	s_mov_b64 s[0:1], -1
	s_cbranch_vccnz .LBB0_317
	s_andn2_b64 vcc, exec, s[22:23]
	s_cbranch_vccnz .LBB0_316
	s_barrier
	s_branch .LBB0_316

; __device__ __forceinline__ unsigned xb_ld(unsigned* p)              { return __hip_atomic_load(p, __ATOMIC_RELAXED, __HIP_MEMORY_SCOPE_AGENT); }
; __device__ __forceinline__ unsigned xb_add(unsigned* p, unsigned v) { return __hip_atomic_fetch_add(p, v, __ATOMIC_RELAXED, __HIP_MEMORY_SCOPE_AGENT); }
; #define XB_SPIN(cond, bar) do { unsigned _sp = 0; while (cond) { __builtin_amdgcn_s_sleep(1); \
;     if ((++_sp & 255u) == 0u) { if (xb_ld(&(bar)[XB_TMO])) break; if (_sp > XB_SPIN_CAP) { atomicAdd(&(bar)[XB_TMO], 1u); break; } } } } while (0)
; __device__ __forceinline__ void xcd_barrier(const XcdBarrier& b) {
;     asm volatile("s_waitcnt vmcnt(0)" ::: "memory");
;     __syncthreads();
;     if (threadIdx.x == 0) {
;         unsigned* bar = b.bar;
;         __builtin_amdgcn_s_waitcnt(0);
;         unsigned nloc = b.st[0], nx = b.st[1];
;         if (nloc == 0u) { xcd_barrier_complete(bar, b.x, nloc, nx); b.st[0] = nloc; b.st[1] = nx; }
;         const unsigned old = xb_add(&bar[XB_XSUB(b.x)], 1u);
;         const unsigned gen = old / nloc;
;         if (old + 1u == (gen + 1u) * nloc) {
;             __builtin_amdgcn_fence(__ATOMIC_RELEASE, "agent");
;             asm volatile("s_waitcnt vmcnt(0)" ::: "memory");
;             const unsigned og = xb_add(&bar[XB_TOP], 1u);
;             const unsigned tg = og / nx;
;             if (og + 1u == (tg + 1u) * nx) xb_add(&bar[XB_TOPGEN], 1u);
;             else XB_SPIN(xb_ld(&bar[XB_TOPGEN]) == tg, bar);
;             __builtin_amdgcn_fence(__ATOMIC_ACQUIRE, "agent");
;             xb_add(&bar[XB_XGEN(b.x)], 1u);
;             asm volatile("s_waitcnt vmcnt(0)" ::: "memory");
;         } else {
;             XB_SPIN(xb_ld(&bar[XB_XGEN(b.x)]) == gen, bar);
;             __builtin_amdgcn_fence(__ATOMIC_ACQUIRE, "agent");
;             asm volatile("s_waitcnt vmcnt(0)" ::: "memory");
;         }
;     }
;     __syncthreads();
; }
.Ltb482_frel:
.Ltb482_done:
	s_or_b64 exec, exec, s[4:5]
	s_barrier
	s_mov_b32 s100, 8

; #define PG8_STAGE_T(bufoff, gbase, voff, AUX) do { _Pragma("unroll") for (int _i = 0; _i < 2; ++_i) \
;         __builtin_amdgcn_global_load_lds((const unsigned*)((const char*)(gbase) + (voff)[_i]), (PG8_LAS unsigned*)(lds + (bufoff) + ldsw + _i * 8192), 16, 0, AUX); } while (0)
; #define PG8_BAR __builtin_amdgcn_s_barrier()
;     ...
;         if constexpr (ALIGN_EPI) { if (wr == 0) PG8_BAR; }
;         if constexpr (PEEL) { static_assert(ALIGN_EPI && SP2, "PEEL is written for the aligned two-super-phase loop");
;             PG8_STAGE_T(PG8_SA(1, 1), nA + nk + hstep, voffA, AUX_A); }
;         if constexpr (!Epi::AFTER_DRAIN) { E(acc, cur, wr, wc, fr, fq); S.done(cur); }
.LBB0_519:
	s_cmp_eq_u32 s100, 0
	s_cbranch_scc1 .Llg519_skip
	v_readfirstlane_b32 s101, v195
	s_cmp_lg_u32 s101, 0
	s_cbranch_scc1 .Llg519_wait
	s_add_u32 s72, s28, 0x3903600
	s_addc_u32 s73, s29, 0
	v_lshlrev_b32_e32 v252, 5, v195
	s_mov_b32 s101, 0
.Llg519_spin:
	global_load_dword v253, v252, s[72:73] sc1
	s_waitcnt vmcnt(0)
	v_cmp_gt_u32_e32 vcc, s100, v253
	s_cmp_lg_u64 vcc, 0
	s_cbranch_scc0 .Llg519_wait
	s_sleep 1
	s_add_u32 s101, s101, 1
	s_cmp_lt_u32 s101, 0x400000
	s_cbranch_scc1 .Llg519_spin
.Llg519_wait:
	s_barrier
	s_mov_b32 s100, 0

; __device__ __forceinline__ unsigned pk2(float lo, float hi) { bf16x2_t r = __builtin_convertvector((f32x2_t){lo, hi}, bf16x2_t); return __builtin_bit_cast(unsigned, r); }
;     __device__ __forceinline__ void operator()(const pg8::f32x4 (&acc)[2][2][4][2], const pg8::Unit& u, int wr, int wc, int fr, int fq) const {
;     ...
;                     if (PART) {
; #pragma unroll
;                         for (int j = 0; j < 8; ++j) s += r[j] * r[j];
;                     }
;                     v4u w; w.x = pk2(r[0], r[1]); w.y = pk2(r[2], r[3]); w.z = pk2(r[4], r[5]); w.w = pk2(r[6], r[7]);
;                     st16_wt(O + off + bj * 128, w);
;                 }
;                 if (PART) { s += __shfl_xor(s, 16); s += __shfl_xor(s, 32); st4_wt(part + (size_t)row * 16 + u.pn * 4 + wc, s); }
; template <bool SRC_F32, bool FINAL, int R> __device__ __forceinline__ void ew_compute(const EwSet<SRC_F32, R>& S, int rb, const f32x4 (&g)[4], bf16* hb_out, float* out32, float scale, float* rs_out, int lane) {
; #pragma unroll
;     for (int i = 0; i < R; ++i) {
;         float q = S.p[i];
;         q += __shfl_xor(q, 1); q += __shfl_xor(q, 2); q += __shfl_xor(q, 4); q += __shfl_xor(q, 8);
;         const float ss = __shfl(q, 0);
;         const float rs = scale / sqrtf(ss * (1.f / D) + EPS);
.LBB0_889:
	s_waitcnt lgkmcnt(0)
	v_lshl_or_b32 v242, s41, 8, v148
	v_lshl_add_u32 v243, s40, 8, v146
	v_lshlrev_b32_e32 v194, 2, v242
	v_lshlrev_b32_e32 v153, 1, v242
	v_lshl_add_u32 v153, v243, 11, v153
	v_xor_b32_e32 v166, 16, v152
	v_lshlrev_b32_e32 v166, 2, v166
	v_xor_b32_e32 v168, 32, v152
	v_lshlrev_b32_e32 v168, 2, v168
	v_lshrrev_b32_e32 v161, 4, v152
	v_and_b32_e32 v161, 3, v161
	v_lshlrev_b32_e32 v161, 4, v161
	v_lshl_add_u32 v161, v243, 6, v161
	s_lshl_b32 s95, s41, 4
	s_add_u32 s95, s95, s6
	v_lshl_add_u32 v157, v243, 6, s95
	v_pk_mul_f32 v[242:243], v[124:125], v[124:125]
	v_pk_fma_f32 v[242:243], v[126:127], v[126:127], v[242:243]
	v_pk_fma_f32 v[242:243], v[120:121], v[120:121], v[242:243]
	v_pk_fma_f32 v[242:243], v[122:123], v[122:123], v[242:243]
	v_pk_fma_f32 v[242:243], v[116:117], v[116:117], v[242:243]
	v_pk_fma_f32 v[242:243], v[118:119], v[118:119], v[242:243]
	v_pk_fma_f32 v[242:243], v[112:113], v[112:113], v[242:243]
	v_pk_fma_f32 v[242:243], v[114:115], v[114:115], v[242:243]
	v_add_f32_e32 v145, v242, v243
	v_pk_mul_f32 v[244:245], v[108:109], v[108:109]
	v_pk_fma_f32 v[244:245], v[110:111], v[110:111], v[244:245]
	v_pk_fma_f32 v[244:245], v[104:105], v[104:105], v[244:245]
	v_pk_fma_f32 v[244:245], v[106:107], v[106:107], v[244:245]
	v_pk_fma_f32 v[244:245], v[100:101], v[100:101], v[244:245]
	v_pk_fma_f32 v[244:245], v[102:103], v[102:103], v[244:245]
	v_pk_fma_f32 v[244:245], v[96:97], v[96:97], v[244:245]
	v_pk_fma_f32 v[244:245], v[98:99], v[98:99], v[244:245]
	v_add_f32_e32 v155, v244, v245
	v_pk_mul_f32 v[242:243], v[92:93], v[92:93]
	v_pk_fma_f32 v[242:243], v[94:95], v[94:95], v[242:243]
	v_pk_fma_f32 v[242:243], v[88:89], v[88:89], v[242:243]
	v_pk_fma_f32 v[242:243], v[90:91], v[90:91], v[242:243]
	v_pk_fma_f32 v[242:243], v[84:85], v[84:85], v[242:243]
	v_pk_fma_f32 v[242:243], v[86:87], v[86:87], v[242:243]
	v_pk_fma_f32 v[242:243], v[80:81], v[80:81], v[242:243]
	v_pk_fma_f32 v[242:243], v[82:83], v[82:83], v[242:243]
	v_add_f32_e32 v159, v242, v243
	v_pk_mul_f32 v[244:245], v[76:77], v[76:77]
	v_pk_fma_f32 v[244:245], v[78:79], v[78:79], v[244:245]
	v_pk_fma_f32 v[244:245], v[72:73], v[72:73], v[244:245]
	v_pk_fma_f32 v[244:245], v[74:75], v[74:75], v[244:245]
	v_pk_fma_f32 v[244:245], v[68:69], v[68:69], v[244:245]
	v_pk_fma_f32 v[244:245], v[70:71], v[70:71], v[244:245]
	v_pk_fma_f32 v[244:245], v[64:65], v[64:65], v[244:245]
	v_pk_fma_f32 v[244:245], v[66:67], v[66:67], v[244:245]
	v_add_f32_e32 v163, v244, v245
	v_pk_mul_f32 v[242:243], v[60:61], v[60:61]
	v_pk_fma_f32 v[242:243], v[62:63], v[62:63], v[242:243]
	v_pk_fma_f32 v[242:243], v[56:57], v[56:57], v[242:243]
	v_pk_fma_f32 v[242:243], v[58:59], v[58:59], v[242:243]
	v_pk_fma_f32 v[242:243], v[52:53], v[52:53], v[242:243]
	v_pk_fma_f32 v[242:243], v[54:55], v[54:55], v[242:243]
	v_pk_fma_f32 v[242:243], v[48:49], v[48:49], v[242:243]
	v_pk_fma_f32 v[242:243], v[50:51], v[50:51], v[242:243]
	v_add_f32_e32 v165, v242, v243
	v_pk_mul_f32 v[244:245], v[44:45], v[44:45]
	v_pk_fma_f32 v[244:245], v[46:47], v[46:47], v[244:245]
	v_pk_fma_f32 v[244:245], v[40:41], v[40:41], v[244:245]
	v_pk_fma_f32 v[244:245], v[42:43], v[42:43], v[244:245]
	v_pk_fma_f32 v[244:245], v[36:37], v[36:37], v[244:245]
	v_pk_fma_f32 v[244:245], v[38:39], v[38:39], v[244:245]
	v_pk_fma_f32 v[244:245], v[32:33], v[32:33], v[244:245]
	v_pk_fma_f32 v[244:245], v[34:35], v[34:35], v[244:245]
	v_add_f32_e32 v171, v244, v245
	v_pk_mul_f32 v[242:243], v[28:29], v[28:29]
	v_pk_fma_f32 v[242:243], v[30:31], v[30:31], v[242:243]
	v_pk_fma_f32 v[242:243], v[24:25], v[24:25], v[242:243]
	v_pk_fma_f32 v[242:243], v[26:27], v[26:27], v[242:243]
	v_pk_fma_f32 v[242:243], v[20:21], v[20:21], v[242:243]
	v_pk_fma_f32 v[242:243], v[22:23], v[22:23], v[242:243]
	v_pk_fma_f32 v[242:243], v[16:17], v[16:17], v[242:243]
	v_pk_fma_f32 v[242:243], v[18:19], v[18:19], v[242:243]
	v_add_f32_e32 v193, v242, v243
	v_pk_mul_f32 v[244:245], v[12:13], v[12:13]
	v_pk_fma_f32 v[244:245], v[14:15], v[14:15], v[244:245]
	v_pk_fma_f32 v[244:245], v[8:9], v[8:9], v[244:245]
	v_pk_fma_f32 v[244:245], v[10:11], v[10:11], v[244:245]
	v_pk_fma_f32 v[244:245], v[4:5], v[4:5], v[244:245]
	v_pk_fma_f32 v[244:245], v[6:7], v[6:7], v[244:245]
	v_pk_fma_f32 v[244:245], v[0:1], v[0:1], v[244:245]
	v_pk_fma_f32 v[244:245], v[2:3], v[2:3], v[244:245]
	v_add_f32_e32 v241, v244, v245
	s_nop 1
	ds_bpermute_b32 v188, v166, v145
	ds_bpermute_b32 v196, v166, v155
	ds_bpermute_b32 v200, v166, v159
	ds_bpermute_b32 v204, v166, v163
	ds_bpermute_b32 v208, v166, v165
	ds_bpermute_b32 v212, v166, v171
	ds_bpermute_b32 v216, v166, v193
	ds_bpermute_b32 v220, v166, v241
	s_waitcnt lgkmcnt(0)
	v_add_f32_e32 v145, v145, v188
	v_add_f32_e32 v155, v155, v196
	v_add_f32_e32 v159, v159, v200
	v_add_f32_e32 v163, v163, v204
	v_add_f32_e32 v165, v165, v208
	v_add_f32_e32 v171, v171, v212
	v_add_f32_e32 v193, v193, v216
	v_add_f32_e32 v241, v241, v220
	s_nop 1
	ds_bpermute_b32 v188, v168, v145
	ds_bpermute_b32 v196, v168, v155
	ds_bpermute_b32 v200, v168, v159
	ds_bpermute_b32 v204, v168, v163
	ds_bpermute_b32 v208, v168, v165
	ds_bpermute_b32 v212, v168, v171
	ds_bpermute_b32 v216, v168, v193
	ds_bpermute_b32 v220, v168, v241
	s_waitcnt lgkmcnt(0)
	v_add_f32_e32 v145, v145, v188
	v_add_f32_e32 v155, v155, v196
	v_add_f32_e32 v159, v159, v200
	v_add_f32_e32 v163, v163, v204
	v_add_f32_e32 v165, v165, v208
	v_add_f32_e32 v171, v171, v212
	v_add_f32_e32 v193, v193, v216
	v_add_f32_e32 v241, v241, v220
	global_store_dword v157, v145, s[20:21]
	v_add_u32_e32 v196, 0x400, v157
	global_store_dword v196, v155, s[20:21]
	v_add_u32_e32 v200, 0x800, v157
	global_store_dword v200, v159, s[20:21]
	v_add_u32_e32 v204, 0xc00, v157
	global_store_dword v204, v163, s[20:21]
	v_add_u32_e32 v208, 0x2000, v157
	global_store_dword v208, v165, s[20:21]
	v_add_u32_e32 v212, 0x2400, v157
	global_store_dword v212, v171, s[20:21]
	v_add_u32_e32 v216, 0x2800, v157
	global_store_dword v216, v193, s[20:21]
	v_add_u32_e32 v220, 0x2c00, v157
	global_store_dword v220, v241, s[20:21]
	s_add_u32 s62, s84, 0xffffff10
	s_addc_u32 s63, s85, -1
	s_load_dwordx2 s[64:65], s[62:63], 0x88
	s_add_u32 s66, s28, 0x5000000
	s_addc_u32 s67, s29, 0
	s_add_u32 s78, s28, 0x4c00000
	s_addc_u32 s79, s29, 0
	global_load_dwordx4 v[224:227], v153, s[66:67]
	global_load_dwordx4 v[228:231], v153, s[66:67] offset:256
	v_add_u32_e32 v244, 0x8000, v153
	global_load_dwordx4 v[232:235], v244, s[66:67]
	global_load_dwordx4 v[236:239], v244, s[66:67] offset:256
	s_waitcnt lgkmcnt(0)
	global_load_dwordx4 v[172:175], v194, s[64:65]
	global_load_dwordx4 v[176:179], v194, s[64:65] offset:16
	global_load_dwordx4 v[180:183], v194, s[64:65] offset:512
	global_load_dwordx4 v[184:187], v194, s[64:65] offset:528
	s_waitcnt vmcnt(0)
	s_barrier
; __device__ __forceinline__ unsigned xb_ld(unsigned* p)              { return __hip_atomic_load(p, __ATOMIC_RELAXED, __HIP_MEMORY_SCOPE_AGENT); }
; __device__ __forceinline__ unsigned xb_add(unsigned* p, unsigned v) { return __hip_atomic_fetch_add(p, v, __ATOMIC_RELAXED, __HIP_MEMORY_SCOPE_AGENT); }
; #define XB_SPIN(cond, bar) do { unsigned _sp = 0; while (cond) { __builtin_amdgcn_s_sleep(1); \
;     if ((++_sp & 255u) == 0u) { if (xb_ld(&(bar)[XB_TMO])) break; if (_sp > XB_SPIN_CAP) { atomicAdd(&(bar)[XB_TMO], 1u); break; } } } } while (0)
; __device__ __forceinline__ void xcd_barrier(const XcdBarrier& b) {
;     asm volatile("s_waitcnt vmcnt(0)" ::: "memory");
;     __syncthreads();
;     if (threadIdx.x == 0) {
;         unsigned* bar = b.bar;
;         __builtin_amdgcn_s_waitcnt(0);
;         unsigned nloc = b.st[0], nx = b.st[1];
;         if (nloc == 0u) { xcd_barrier_complete(bar, b.x, nloc, nx); b.st[0] = nloc; b.st[1] = nx; }
;         const unsigned old = xb_add(&bar[XB_XSUB(b.x)], 1u);
;         const unsigned gen = old / nloc;
;         if (old + 1u == (gen + 1u) * nloc) {
;             __builtin_amdgcn_fence(__ATOMIC_RELEASE, "agent");
;             asm volatile("s_waitcnt vmcnt(0)" ::: "memory");
;             const unsigned og = xb_add(&bar[XB_TOP], 1u);
;             const unsigned tg = og / nx;
;             if (og + 1u == (tg + 1u) * nx) xb_add(&bar[XB_TOPGEN], 1u);
;             else XB_SPIN(xb_ld(&bar[XB_TOPGEN]) == tg, bar);
;             __builtin_amdgcn_fence(__ATOMIC_ACQUIRE, "agent");
;             xb_add(&bar[XB_XGEN(b.x)], 1u);
;             asm volatile("s_waitcnt vmcnt(0)" ::: "memory");
;         } else {
;             XB_SPIN(xb_ld(&bar[XB_XGEN(b.x)]) == gen, bar);
;             __builtin_amdgcn_fence(__ATOMIC_ACQUIRE, "agent");
;             asm volatile("s_waitcnt vmcnt(0)" ::: "memory");
;         }
;     }
;     __syncthreads();
; }
	v_readfirstlane_b32 s94, v195
	s_cmp_lg_u32 s94, 0
	s_cbranch_scc1 .Lfe1_bskip
	s_mov_b64 exec, 1
	s_and_b32 s94, s2, 7
	s_lshl_b32 s94, s94, 3
	s_bfe_u32 s96, s2, 0x30003
	s_or_b32 s94, s94, s96
	s_lshl_b32 s94, s94, 5
	s_add_u32 s62, s28, 0x3903600
	s_addc_u32 s63, s29, 0
	v_mov_b32_e32 v242, s94
	v_mov_b32_e32 v243, 1
	s_cmp_eq_u32 s99, 1
	s_cbranch_scc1 .Lfe1_bfast
	buffer_wbl2 sc1
	s_waitcnt vmcnt(0)

; template <bool SRC_F32, int R> __device__ __forceinline__ void ew_load(EwSet<SRC_F32, R>& S, int rb, const float* hsrc32, const bf16* hsrcb, const bf16* f, const float* part, int lane) {
; #pragma unroll
;     for (int i = 0; i < R; ++i) S.p[i] = (lane < 16) ? part[(size_t)(rb + i) * 16 + lane] : 0.f;
; #pragma unroll
;     for (int i = 0; i < R; ++i)
; #pragma unroll
;         for (int j = 0; j < 4; ++j) {
;             S.fw[i][j] = ((const v2u*)(f + (size_t)(rb + i) * D) + lane)[64 * j];
;             if constexpr (SRC_F32) S.h32[i][j] = __builtin_nontemporal_load((const f32x4*)(hsrc32 + (size_t)(rb + i) * D) + lane + 64 * j);
;             else S.hb[i][j] = ((const v2u*)(hsrcb + (size_t)(rb + i) * D) + lane)[64 * j];
;         }
; }
; template <bool SRC_F32, bool FINAL, int R> __device__ __forceinline__ void ew_compute(const EwSet<SRC_F32, R>& S, int rb, const f32x4 (&g)[4], bf16* hb_out, float* out32, float scale, float* rs_out, int lane) {
; #pragma unroll
;     for (int i = 0; i < R; ++i) {
;         float q = S.p[i];
;         q += __shfl_xor(q, 1); q += __shfl_xor(q, 2); q += __shfl_xor(q, 4); q += __shfl_xor(q, 8);
;         const float ss = __shfl(q, 0);
;         const float rs = scale / sqrtf(ss * (1.f / D) + EPS);
.Lfe1_bskip:
	s_barrier
	global_load_dwordx4 v[188:191], v161, s[20:21]
	v_add_u32_e32 v244, 0x400, v161
	global_load_dwordx4 v[196:199], v244, s[20:21]
	v_add_u32_e32 v244, 0x800, v161
	global_load_dwordx4 v[200:203], v244, s[20:21]
	v_add_u32_e32 v244, 0xc00, v161
	global_load_dwordx4 v[204:207], v244, s[20:21]
	v_add_u32_e32 v244, 0x2000, v161
	global_load_dwordx4 v[208:211], v244, s[20:21]
	v_add_u32_e32 v244, 0x2400, v161
	global_load_dwordx4 v[212:215], v244, s[20:21]
	v_add_u32_e32 v244, 0x2800, v161
	global_load_dwordx4 v[216:219], v244, s[20:21]
	v_add_u32_e32 v244, 0x2c00, v161
	global_load_dwordx4 v[220:223], v244, s[20:21]
	s_waitcnt vmcnt(0)
	v_add_f32_e32 v145, v188, v189
	v_add_f32_e32 v145, v190, v145
	v_add_f32_e32 v145, v191, v145
	v_add_f32_e32 v155, v196, v197
	v_add_f32_e32 v155, v198, v155
	v_add_f32_e32 v155, v199, v155
	v_add_f32_e32 v159, v200, v201
	v_add_f32_e32 v159, v202, v159
	v_add_f32_e32 v159, v203, v159
	v_add_f32_e32 v163, v204, v205
	v_add_f32_e32 v163, v206, v163
	v_add_f32_e32 v163, v207, v163
	v_add_f32_e32 v165, v208, v209
	v_add_f32_e32 v165, v210, v165
	v_add_f32_e32 v165, v211, v165
	v_add_f32_e32 v171, v212, v213
	v_add_f32_e32 v171, v214, v171
	v_add_f32_e32 v171, v215, v171
	v_add_f32_e32 v193, v216, v217
	v_add_f32_e32 v193, v218, v193
	v_add_f32_e32 v193, v219, v193
	v_add_f32_e32 v241, v220, v221
	v_add_f32_e32 v241, v222, v241
	v_add_f32_e32 v241, v223, v241
	s_nop 1
	ds_bpermute_b32 v188, v166, v145
	ds_bpermute_b32 v196, v166, v155
	ds_bpermute_b32 v200, v166, v159
	ds_bpermute_b32 v204, v166, v163
	ds_bpermute_b32 v208, v166, v165
	ds_bpermute_b32 v212, v166, v171
	ds_bpermute_b32 v216, v166, v193
	ds_bpermute_b32 v220, v166, v241
	s_waitcnt lgkmcnt(0)
	v_add_f32_e32 v145, v145, v188
	v_add_f32_e32 v155, v155, v196
	v_add_f32_e32 v159, v159, v200
	v_add_f32_e32 v163, v163, v204
	v_add_f32_e32 v165, v165, v208
	v_add_f32_e32 v171, v171, v212
	v_add_f32_e32 v193, v193, v216
	v_add_f32_e32 v241, v241, v220
	s_nop 1
	ds_bpermute_b32 v188, v168, v145
	ds_bpermute_b32 v196, v168, v155
	ds_bpermute_b32 v200, v168, v159
	ds_bpermute_b32 v204, v168, v163
	ds_bpermute_b32 v208, v168, v165
	ds_bpermute_b32 v212, v168, v171
	ds_bpermute_b32 v216, v168, v193
	ds_bpermute_b32 v220, v168, v241
	s_waitcnt lgkmcnt(0)
	v_add_f32_e32 v145, v145, v188
	v_add_f32_e32 v155, v155, v196
	v_add_f32_e32 v159, v159, v200
	v_add_f32_e32 v163, v163, v204
	v_add_f32_e32 v165, v165, v208
	v_add_f32_e32 v171, v171, v212
	v_add_f32_e32 v193, v193, v216
	v_add_f32_e32 v241, v241, v220
	v_mul_f32_e32 v145, 0x3a800000, v145
	v_mul_f32_e32 v155, 0x3a800000, v155
	v_mul_f32_e32 v159, 0x3a800000, v159
	v_mul_f32_e32 v163, 0x3a800000, v163
	v_mul_f32_e32 v165, 0x3a800000, v165
	v_mul_f32_e32 v171, 0x3a800000, v171
	v_mul_f32_e32 v193, 0x3a800000, v193
	v_mul_f32_e32 v241, 0x3a800000, v241
	v_add_f32_e32 v145, 0x358637bd, v145
	v_add_f32_e32 v155, 0x358637bd, v155
	v_add_f32_e32 v159, 0x358637bd, v159
	v_add_f32_e32 v163, 0x358637bd, v163
	v_add_f32_e32 v165, 0x358637bd, v165
	v_add_f32_e32 v171, 0x358637bd, v171
	v_add_f32_e32 v193, 0x358637bd, v193
	v_add_f32_e32 v241, 0x358637bd, v241
	v_rsq_f32_e32 v144, v145
	v_rsq_f32_e32 v154, v155
	v_rsq_f32_e32 v158, v159
	v_rsq_f32_e32 v162, v163
	v_rsq_f32_e32 v164, v165
	v_rsq_f32_e32 v170, v171
	v_rsq_f32_e32 v192, v193
	v_rsq_f32_e32 v240, v241
	s_nop 0
	v_add_u32_e32 v244, 0x10000, v153
	global_load_dwordx4 v[188:191], v244, s[66:67]
	global_load_dwordx4 v[196:199], v244, s[66:67] offset:256
	v_add_u32_e32 v244, 0x18000, v153
	global_load_dwordx4 v[200:203], v244, s[66:67]
	global_load_dwordx4 v[204:207], v244, s[66:67] offset:256
	v_add_u32_e32 v244, 0x40000, v153
	global_load_dwordx4 v[208:211], v244, s[66:67]
	global_load_dwordx4 v[212:215], v244, s[66:67] offset:256
	v_add_u32_e32 v244, 0x48000, v153
	global_load_dwordx4 v[216:219], v244, s[66:67]
	global_load_dwordx4 v[220:223], v244, s[66:67] offset:256
	v_lshlrev_b32_e32 v242, 16, v224
	v_and_b32_e32 v243, 0xffff0000, v224
	v_pk_mul_f32 v[124:125], v[124:125], v[144:145] op_sel_hi:[1,0]
	v_pk_fma_f32 v[124:125], v[124:125], v[172:173], v[242:243]
	v_lshlrev_b32_e32 v244, 16, v225
	v_and_b32_e32 v245, 0xffff0000, v225
	v_pk_mul_f32 v[126:127], v[126:127], v[144:145] op_sel_hi:[1,0]
	v_pk_fma_f32 v[126:127], v[126:127], v[174:175], v[244:245]
	v_lshlrev_b32_e32 v242, 16, v226
	v_and_b32_e32 v243, 0xffff0000, v226
	v_pk_mul_f32 v[120:121], v[120:121], v[144:145] op_sel_hi:[1,0]
	v_pk_fma_f32 v[120:121], v[120:121], v[176:177], v[242:243]
	v_lshlrev_b32_e32 v244, 16, v227
	v_and_b32_e32 v245, 0xffff0000, v227
	v_pk_mul_f32 v[122:123], v[122:123], v[144:145] op_sel_hi:[1,0]
	v_pk_fma_f32 v[122:123], v[122:123], v[178:179], v[244:245]
	v_lshlrev_b32_e32 v242, 16, v228
	v_and_b32_e32 v243, 0xffff0000, v228
	v_pk_mul_f32 v[116:117], v[116:117], v[144:145] op_sel_hi:[1,0]
	v_pk_fma_f32 v[116:117], v[116:117], v[180:181], v[242:243]
	v_lshlrev_b32_e32 v244, 16, v229
	v_and_b32_e32 v245, 0xffff0000, v229
	v_pk_mul_f32 v[118:119], v[118:119], v[144:145] op_sel_hi:[1,0]
	v_pk_fma_f32 v[118:119], v[118:119], v[182:183], v[244:245]
	v_lshlrev_b32_e32 v242, 16, v230
	v_and_b32_e32 v243, 0xffff0000, v230
	v_pk_mul_f32 v[112:113], v[112:113], v[144:145] op_sel_hi:[1,0]
	v_pk_fma_f32 v[112:113], v[112:113], v[184:185], v[242:243]
	v_lshlrev_b32_e32 v244, 16, v231
	v_and_b32_e32 v245, 0xffff0000, v231
	v_pk_mul_f32 v[114:115], v[114:115], v[144:145] op_sel_hi:[1,0]
	v_pk_fma_f32 v[114:115], v[114:115], v[186:187], v[244:245]
	v_pk_mul_f32 v[242:243], v[124:125], v[124:125]
	v_pk_fma_f32 v[242:243], v[126:127], v[126:127], v[242:243]
; __device__ __forceinline__ float bf_lo(unsigned w) { return __uint_as_float(w << 16); }
; __device__ __forceinline__ float bf_hi(unsigned w) { return __uint_as_float(w & 0xffff0000u); }
; __device__ __forceinline__ unsigned pk2(float lo, float hi) { bf16x2_t r = __builtin_convertvector((f32x2_t){lo, hi}, bf16x2_t); return __builtin_bit_cast(unsigned, r); }
; template <bool SRC_F32, bool FINAL, int R> __device__ __forceinline__ void ew_compute(const EwSet<SRC_F32, R>& S, int rb, const f32x4 (&g)[4], bf16* hb_out, float* out32, float scale, float* rs_out, int lane) {
;     ...
;         float s2 = 0.f;
; #pragma unroll
;         for (int j = 0; j < 4; ++j) {
;             f32x4 h;
;             if constexpr (SRC_F32) h = S.h32[i][j];
;             else { const v2u hw = S.hb[i][j]; h.x = bf_lo(hw.x); h.y = bf_hi(hw.x); h.z = bf_lo(hw.y); h.w = bf_hi(hw.y); }
;             const v2u fw = S.fw[i][j];
;             f32x4 v; v.x = h.x + bf_lo(fw.x) * rs * g[j].x; v.y = h.y + bf_hi(fw.x) * rs * g[j].y; v.z = h.z + bf_lo(fw.y) * rs * g[j].z; v.w = h.w + bf_hi(fw.y) * rs * g[j].w;
;             if (FINAL) __builtin_nontemporal_store(v, (f32x4*)(out32 + (size_t)(rb + i) * D) + lane + 64 * j);
;             else { v2u o; o.x = pk2(v.x, v.y); o.y = pk2(v.z, v.w); ((v2u*)(hb_out + (size_t)(rb + i) * D) + lane)[64 * j] = o; s2 += (v.x * v.x + v.y * v.y) + (v.z * v.z + v.w * v.w); }
;         }
;         if (!FINAL) { const float tot = wave_sum(s2); if (lane == 0) rs_out[rb + i] = 1.0f / sqrtf(tot * (1.f / D) + EPS); }
	v_pk_fma_f32 v[242:243], v[120:121], v[120:121], v[242:243]
	v_pk_fma_f32 v[242:243], v[122:123], v[122:123], v[242:243]
	v_pk_fma_f32 v[242:243], v[116:117], v[116:117], v[242:243]
	v_pk_fma_f32 v[242:243], v[118:119], v[118:119], v[242:243]
	v_pk_fma_f32 v[242:243], v[112:113], v[112:113], v[242:243]
	v_pk_fma_f32 v[242:243], v[114:115], v[114:115], v[242:243]
	v_add_f32_e32 v145, v242, v243
	v_cvt_pk_bf16_f32 v224, v124, v125
	v_cvt_pk_bf16_f32 v225, v126, v127
	v_cvt_pk_bf16_f32 v226, v120, v121
	v_cvt_pk_bf16_f32 v227, v122, v123
	v_cvt_pk_bf16_f32 v228, v116, v117
	v_cvt_pk_bf16_f32 v229, v118, v119
	v_cvt_pk_bf16_f32 v230, v112, v113
	v_cvt_pk_bf16_f32 v231, v114, v115
	s_nop 0
	global_store_dwordx4 v153, v[224:227], s[66:67]
	global_store_dwordx4 v153, v[228:231], s[66:67] offset:256
	v_lshlrev_b32_e32 v242, 16, v232
	v_and_b32_e32 v243, 0xffff0000, v232
	v_pk_mul_f32 v[108:109], v[108:109], v[154:155] op_sel_hi:[1,0]
	v_pk_fma_f32 v[108:109], v[108:109], v[172:173], v[242:243]
	v_lshlrev_b32_e32 v244, 16, v233
	v_and_b32_e32 v245, 0xffff0000, v233
	v_pk_mul_f32 v[110:111], v[110:111], v[154:155] op_sel_hi:[1,0]
	v_pk_fma_f32 v[110:111], v[110:111], v[174:175], v[244:245]
	v_lshlrev_b32_e32 v242, 16, v234
	v_and_b32_e32 v243, 0xffff0000, v234
	v_pk_mul_f32 v[104:105], v[104:105], v[154:155] op_sel_hi:[1,0]
	v_pk_fma_f32 v[104:105], v[104:105], v[176:177], v[242:243]
	v_lshlrev_b32_e32 v244, 16, v235
	v_and_b32_e32 v245, 0xffff0000, v235
	v_pk_mul_f32 v[106:107], v[106:107], v[154:155] op_sel_hi:[1,0]
	v_pk_fma_f32 v[106:107], v[106:107], v[178:179], v[244:245]
	v_lshlrev_b32_e32 v242, 16, v236
	v_and_b32_e32 v243, 0xffff0000, v236
	v_pk_mul_f32 v[100:101], v[100:101], v[154:155] op_sel_hi:[1,0]
	v_pk_fma_f32 v[100:101], v[100:101], v[180:181], v[242:243]
	v_lshlrev_b32_e32 v244, 16, v237
	v_and_b32_e32 v245, 0xffff0000, v237
	v_pk_mul_f32 v[102:103], v[102:103], v[154:155] op_sel_hi:[1,0]
	v_pk_fma_f32 v[102:103], v[102:103], v[182:183], v[244:245]
	v_lshlrev_b32_e32 v242, 16, v238
	v_and_b32_e32 v243, 0xffff0000, v238
	v_pk_mul_f32 v[96:97], v[96:97], v[154:155] op_sel_hi:[1,0]
	v_pk_fma_f32 v[96:97], v[96:97], v[184:185], v[242:243]
	v_lshlrev_b32_e32 v244, 16, v239
	v_and_b32_e32 v245, 0xffff0000, v239
	v_pk_mul_f32 v[98:99], v[98:99], v[154:155] op_sel_hi:[1,0]
	v_pk_fma_f32 v[98:99], v[98:99], v[186:187], v[244:245]
	v_pk_mul_f32 v[242:243], v[108:109], v[108:109]
	v_pk_fma_f32 v[242:243], v[110:111], v[110:111], v[242:243]
	v_pk_fma_f32 v[242:243], v[104:105], v[104:105], v[242:243]
	v_pk_fma_f32 v[242:243], v[106:107], v[106:107], v[242:243]
	v_pk_fma_f32 v[242:243], v[100:101], v[100:101], v[242:243]
	v_pk_fma_f32 v[242:243], v[102:103], v[102:103], v[242:243]
	v_pk_fma_f32 v[242:243], v[96:97], v[96:97], v[242:243]
	v_pk_fma_f32 v[242:243], v[98:99], v[98:99], v[242:243]
	v_add_f32_e32 v155, v242, v243
	v_cvt_pk_bf16_f32 v232, v108, v109
	v_cvt_pk_bf16_f32 v233, v110, v111
	v_cvt_pk_bf16_f32 v234, v104, v105
	v_cvt_pk_bf16_f32 v235, v106, v107
	v_cvt_pk_bf16_f32 v236, v100, v101
	v_cvt_pk_bf16_f32 v237, v102, v103
	v_cvt_pk_bf16_f32 v238, v96, v97
	v_cvt_pk_bf16_f32 v239, v98, v99
	v_add_u32_e32 v244, 0x8000, v153
	s_nop 0
	global_store_dwordx4 v244, v[232:235], s[66:67]
	global_store_dwordx4 v244, v[236:239], s[66:67] offset:256
	s_nop 1
	v_add_u32_e32 v244, 0x50000, v153
	global_load_dwordx4 v[224:227], v244, s[66:67]
	global_load_dwordx4 v[228:231], v244, s[66:67] offset:256
	v_add_u32_e32 v244, 0x58000, v153
	global_load_dwordx4 v[232:235], v244, s[66:67]
	global_load_dwordx4 v[236:239], v244, s[66:67] offset:256
	s_waitcnt vmcnt(14)
	v_lshlrev_b32_e32 v242, 16, v188
	v_and_b32_e32 v243, 0xffff0000, v188
	v_pk_mul_f32 v[92:93], v[92:93], v[158:159] op_sel_hi:[1,0]
	v_pk_fma_f32 v[92:93], v[92:93], v[172:173], v[242:243]
	v_lshlrev_b32_e32 v244, 16, v189
	v_and_b32_e32 v245, 0xffff0000, v189
	v_pk_mul_f32 v[94:95], v[94:95], v[158:159] op_sel_hi:[1,0]
	v_pk_fma_f32 v[94:95], v[94:95], v[174:175], v[244:245]
	v_lshlrev_b32_e32 v242, 16, v190
	v_and_b32_e32 v243, 0xffff0000, v190
	v_pk_mul_f32 v[88:89], v[88:89], v[158:159] op_sel_hi:[1,0]
	v_pk_fma_f32 v[88:89], v[88:89], v[176:177], v[242:243]
	v_lshlrev_b32_e32 v244, 16, v191
	v_and_b32_e32 v245, 0xffff0000, v191
	v_pk_mul_f32 v[90:91], v[90:91], v[158:159] op_sel_hi:[1,0]
	v_pk_fma_f32 v[90:91], v[90:91], v[178:179], v[244:245]
	v_lshlrev_b32_e32 v242, 16, v196
	v_and_b32_e32 v243, 0xffff0000, v196
	v_pk_mul_f32 v[84:85], v[84:85], v[158:159] op_sel_hi:[1,0]
	v_pk_fma_f32 v[84:85], v[84:85], v[180:181], v[242:243]
	v_lshlrev_b32_e32 v244, 16, v197
	v_and_b32_e32 v245, 0xffff0000, v197
	v_pk_mul_f32 v[86:87], v[86:87], v[158:159] op_sel_hi:[1,0]
	v_pk_fma_f32 v[86:87], v[86:87], v[182:183], v[244:245]
	v_lshlrev_b32_e32 v242, 16, v198
	v_and_b32_e32 v243, 0xffff0000, v198
	v_pk_mul_f32 v[80:81], v[80:81], v[158:159] op_sel_hi:[1,0]
	v_pk_fma_f32 v[80:81], v[80:81], v[184:185], v[242:243]
	v_lshlrev_b32_e32 v244, 16, v199
	v_and_b32_e32 v245, 0xffff0000, v199
	v_pk_mul_f32 v[82:83], v[82:83], v[158:159] op_sel_hi:[1,0]
	v_pk_fma_f32 v[82:83], v[82:83], v[186:187], v[244:245]
	v_pk_mul_f32 v[242:243], v[92:93], v[92:93]
	v_pk_fma_f32 v[242:243], v[94:95], v[94:95], v[242:243]
	v_pk_fma_f32 v[242:243], v[88:89], v[88:89], v[242:243]
	v_pk_fma_f32 v[242:243], v[90:91], v[90:91], v[242:243]
	v_pk_fma_f32 v[242:243], v[84:85], v[84:85], v[242:243]
	v_pk_fma_f32 v[242:243], v[86:87], v[86:87], v[242:243]
	v_pk_fma_f32 v[242:243], v[80:81], v[80:81], v[242:243]
	v_pk_fma_f32 v[242:243], v[82:83], v[82:83], v[242:243]
	v_add_f32_e32 v159, v242, v243
	v_cvt_pk_bf16_f32 v188, v92, v93
	v_cvt_pk_bf16_f32 v189, v94, v95
	v_cvt_pk_bf16_f32 v190, v88, v89
	v_cvt_pk_bf16_f32 v191, v90, v91
	v_cvt_pk_bf16_f32 v196, v84, v85
	v_cvt_pk_bf16_f32 v197, v86, v87
	v_cvt_pk_bf16_f32 v198, v80, v81
	v_cvt_pk_bf16_f32 v199, v82, v83
	v_add_u32_e32 v244, 0x10000, v153
	s_nop 0
	global_store_dwordx4 v244, v[188:191], s[66:67]
	global_store_dwordx4 v244, v[196:199], s[66:67] offset:256
	s_waitcnt vmcnt(14)
; __device__ __forceinline__ float bf_lo(unsigned w) { return __uint_as_float(w << 16); }
; __device__ __forceinline__ float bf_hi(unsigned w) { return __uint_as_float(w & 0xffff0000u); }
; __device__ __forceinline__ unsigned pk2(float lo, float hi) { bf16x2_t r = __builtin_convertvector((f32x2_t){lo, hi}, bf16x2_t); return __builtin_bit_cast(unsigned, r); }
; template <bool SRC_F32, bool FINAL, int R> __device__ __forceinline__ void ew_compute(const EwSet<SRC_F32, R>& S, int rb, const f32x4 (&g)[4], bf16* hb_out, float* out32, float scale, float* rs_out, int lane) {
;     ...
;         float s2 = 0.f;
; #pragma unroll
;         for (int j = 0; j < 4; ++j) {
;             f32x4 h;
;             if constexpr (SRC_F32) h = S.h32[i][j];
;             else { const v2u hw = S.hb[i][j]; h.x = bf_lo(hw.x); h.y = bf_hi(hw.x); h.z = bf_lo(hw.y); h.w = bf_hi(hw.y); }
;             const v2u fw = S.fw[i][j];
;             f32x4 v; v.x = h.x + bf_lo(fw.x) * rs * g[j].x; v.y = h.y + bf_hi(fw.x) * rs * g[j].y; v.z = h.z + bf_lo(fw.y) * rs * g[j].z; v.w = h.w + bf_hi(fw.y) * rs * g[j].w;
;             if (FINAL) __builtin_nontemporal_store(v, (f32x4*)(out32 + (size_t)(rb + i) * D) + lane + 64 * j);
;             else { v2u o; o.x = pk2(v.x, v.y); o.y = pk2(v.z, v.w); ((v2u*)(hb_out + (size_t)(rb + i) * D) + lane)[64 * j] = o; s2 += (v.x * v.x + v.y * v.y) + (v.z * v.z + v.w * v.w); }
;         }
;         if (!FINAL) { const float tot = wave_sum(s2); if (lane == 0) rs_out[rb + i] = 1.0f / sqrtf(tot * (1.f / D) + EPS); }
	v_lshlrev_b32_e32 v242, 16, v200
	v_and_b32_e32 v243, 0xffff0000, v200
	v_pk_mul_f32 v[76:77], v[76:77], v[162:163] op_sel_hi:[1,0]
	v_pk_fma_f32 v[76:77], v[76:77], v[172:173], v[242:243]
	v_lshlrev_b32_e32 v244, 16, v201
	v_and_b32_e32 v245, 0xffff0000, v201
	v_pk_mul_f32 v[78:79], v[78:79], v[162:163] op_sel_hi:[1,0]
	v_pk_fma_f32 v[78:79], v[78:79], v[174:175], v[244:245]
	v_lshlrev_b32_e32 v242, 16, v202
	v_and_b32_e32 v243, 0xffff0000, v202
	v_pk_mul_f32 v[72:73], v[72:73], v[162:163] op_sel_hi:[1,0]
	v_pk_fma_f32 v[72:73], v[72:73], v[176:177], v[242:243]
	v_lshlrev_b32_e32 v244, 16, v203
	v_and_b32_e32 v245, 0xffff0000, v203
	v_pk_mul_f32 v[74:75], v[74:75], v[162:163] op_sel_hi:[1,0]
	v_pk_fma_f32 v[74:75], v[74:75], v[178:179], v[244:245]
	v_lshlrev_b32_e32 v242, 16, v204
	v_and_b32_e32 v243, 0xffff0000, v204
	v_pk_mul_f32 v[68:69], v[68:69], v[162:163] op_sel_hi:[1,0]
	v_pk_fma_f32 v[68:69], v[68:69], v[180:181], v[242:243]
	v_lshlrev_b32_e32 v244, 16, v205
	v_and_b32_e32 v245, 0xffff0000, v205
	v_pk_mul_f32 v[70:71], v[70:71], v[162:163] op_sel_hi:[1,0]
	v_pk_fma_f32 v[70:71], v[70:71], v[182:183], v[244:245]
	v_lshlrev_b32_e32 v242, 16, v206
	v_and_b32_e32 v243, 0xffff0000, v206
	v_pk_mul_f32 v[64:65], v[64:65], v[162:163] op_sel_hi:[1,0]
	v_pk_fma_f32 v[64:65], v[64:65], v[184:185], v[242:243]
	v_lshlrev_b32_e32 v244, 16, v207
	v_and_b32_e32 v245, 0xffff0000, v207
	v_pk_mul_f32 v[66:67], v[66:67], v[162:163] op_sel_hi:[1,0]
	v_pk_fma_f32 v[66:67], v[66:67], v[186:187], v[244:245]
	v_pk_mul_f32 v[242:243], v[76:77], v[76:77]
	v_pk_fma_f32 v[242:243], v[78:79], v[78:79], v[242:243]
	v_pk_fma_f32 v[242:243], v[72:73], v[72:73], v[242:243]
	v_pk_fma_f32 v[242:243], v[74:75], v[74:75], v[242:243]
	v_pk_fma_f32 v[242:243], v[68:69], v[68:69], v[242:243]
	v_pk_fma_f32 v[242:243], v[70:71], v[70:71], v[242:243]
	v_pk_fma_f32 v[242:243], v[64:65], v[64:65], v[242:243]
	v_pk_fma_f32 v[242:243], v[66:67], v[66:67], v[242:243]
	v_add_f32_e32 v163, v242, v243
	v_cvt_pk_bf16_f32 v200, v76, v77
	v_cvt_pk_bf16_f32 v201, v78, v79
	v_cvt_pk_bf16_f32 v202, v72, v73
	v_cvt_pk_bf16_f32 v203, v74, v75
	v_cvt_pk_bf16_f32 v204, v68, v69
	v_cvt_pk_bf16_f32 v205, v70, v71
	v_cvt_pk_bf16_f32 v206, v64, v65
	v_cvt_pk_bf16_f32 v207, v66, v67
	v_add_u32_e32 v244, 0x18000, v153
	s_nop 0
	global_store_dwordx4 v244, v[200:203], s[66:67]
	global_store_dwordx4 v244, v[204:207], s[66:67] offset:256
	s_waitcnt vmcnt(14)
	v_lshlrev_b32_e32 v242, 16, v208
	v_and_b32_e32 v243, 0xffff0000, v208
	v_pk_mul_f32 v[60:61], v[60:61], v[164:165] op_sel_hi:[1,0]
	v_pk_fma_f32 v[60:61], v[60:61], v[172:173], v[242:243]
	v_lshlrev_b32_e32 v244, 16, v209
	v_and_b32_e32 v245, 0xffff0000, v209
	v_pk_mul_f32 v[62:63], v[62:63], v[164:165] op_sel_hi:[1,0]
	v_pk_fma_f32 v[62:63], v[62:63], v[174:175], v[244:245]
	v_lshlrev_b32_e32 v242, 16, v210
	v_and_b32_e32 v243, 0xffff0000, v210
	v_pk_mul_f32 v[56:57], v[56:57], v[164:165] op_sel_hi:[1,0]
	v_pk_fma_f32 v[56:57], v[56:57], v[176:177], v[242:243]
	v_lshlrev_b32_e32 v244, 16, v211
	v_and_b32_e32 v245, 0xffff0000, v211
	v_pk_mul_f32 v[58:59], v[58:59], v[164:165] op_sel_hi:[1,0]
	v_pk_fma_f32 v[58:59], v[58:59], v[178:179], v[244:245]
	v_lshlrev_b32_e32 v242, 16, v212
	v_and_b32_e32 v243, 0xffff0000, v212
	v_pk_mul_f32 v[52:53], v[52:53], v[164:165] op_sel_hi:[1,0]
	v_pk_fma_f32 v[52:53], v[52:53], v[180:181], v[242:243]
	v_lshlrev_b32_e32 v244, 16, v213
	v_and_b32_e32 v245, 0xffff0000, v213
	v_pk_mul_f32 v[54:55], v[54:55], v[164:165] op_sel_hi:[1,0]
	v_pk_fma_f32 v[54:55], v[54:55], v[182:183], v[244:245]
	v_lshlrev_b32_e32 v242, 16, v214
	v_and_b32_e32 v243, 0xffff0000, v214
	v_pk_mul_f32 v[48:49], v[48:49], v[164:165] op_sel_hi:[1,0]
	v_pk_fma_f32 v[48:49], v[48:49], v[184:185], v[242:243]
	v_lshlrev_b32_e32 v244, 16, v215
	v_and_b32_e32 v245, 0xffff0000, v215
	v_pk_mul_f32 v[50:51], v[50:51], v[164:165] op_sel_hi:[1,0]
	v_pk_fma_f32 v[50:51], v[50:51], v[186:187], v[244:245]
	v_pk_mul_f32 v[242:243], v[60:61], v[60:61]
	v_pk_fma_f32 v[242:243], v[62:63], v[62:63], v[242:243]
	v_pk_fma_f32 v[242:243], v[56:57], v[56:57], v[242:243]
	v_pk_fma_f32 v[242:243], v[58:59], v[58:59], v[242:243]
	v_pk_fma_f32 v[242:243], v[52:53], v[52:53], v[242:243]
	v_pk_fma_f32 v[242:243], v[54:55], v[54:55], v[242:243]
	v_pk_fma_f32 v[242:243], v[48:49], v[48:49], v[242:243]
	v_pk_fma_f32 v[242:243], v[50:51], v[50:51], v[242:243]
	v_add_f32_e32 v165, v242, v243
	v_cvt_pk_bf16_f32 v208, v60, v61
	v_cvt_pk_bf16_f32 v209, v62, v63
	v_cvt_pk_bf16_f32 v210, v56, v57
	v_cvt_pk_bf16_f32 v211, v58, v59
	v_cvt_pk_bf16_f32 v212, v52, v53
	v_cvt_pk_bf16_f32 v213, v54, v55
	v_cvt_pk_bf16_f32 v214, v48, v49
	v_cvt_pk_bf16_f32 v215, v50, v51
	v_add_u32_e32 v244, 0x40000, v153
	s_nop 0
	global_store_dwordx4 v244, v[208:211], s[66:67]
	global_store_dwordx4 v244, v[212:215], s[66:67] offset:256
	s_waitcnt vmcnt(14)
; __device__ __forceinline__ float bf_lo(unsigned w) { return __uint_as_float(w << 16); }
; __device__ __forceinline__ float bf_hi(unsigned w) { return __uint_as_float(w & 0xffff0000u); }
; __device__ __forceinline__ unsigned pk2(float lo, float hi) { bf16x2_t r = __builtin_convertvector((f32x2_t){lo, hi}, bf16x2_t); return __builtin_bit_cast(unsigned, r); }
; template <bool SRC_F32, bool FINAL, int R> __device__ __forceinline__ void ew_compute(const EwSet<SRC_F32, R>& S, int rb, const f32x4 (&g)[4], bf16* hb_out, float* out32, float scale, float* rs_out, int lane) {
;     ...
;         float s2 = 0.f;
; #pragma unroll
;         for (int j = 0; j < 4; ++j) {
;             f32x4 h;
;             if constexpr (SRC_F32) h = S.h32[i][j];
;             else { const v2u hw = S.hb[i][j]; h.x = bf_lo(hw.x); h.y = bf_hi(hw.x); h.z = bf_lo(hw.y); h.w = bf_hi(hw.y); }
;             const v2u fw = S.fw[i][j];
;             f32x4 v; v.x = h.x + bf_lo(fw.x) * rs * g[j].x; v.y = h.y + bf_hi(fw.x) * rs * g[j].y; v.z = h.z + bf_lo(fw.y) * rs * g[j].z; v.w = h.w + bf_hi(fw.y) * rs * g[j].w;
;             if (FINAL) __builtin_nontemporal_store(v, (f32x4*)(out32 + (size_t)(rb + i) * D) + lane + 64 * j);
;             else { v2u o; o.x = pk2(v.x, v.y); o.y = pk2(v.z, v.w); ((v2u*)(hb_out + (size_t)(rb + i) * D) + lane)[64 * j] = o; s2 += (v.x * v.x + v.y * v.y) + (v.z * v.z + v.w * v.w); }
;         }
;         if (!FINAL) { const float tot = wave_sum(s2); if (lane == 0) rs_out[rb + i] = 1.0f / sqrtf(tot * (1.f / D) + EPS); }
	v_lshlrev_b32_e32 v242, 16, v216
	v_and_b32_e32 v243, 0xffff0000, v216
	v_pk_mul_f32 v[44:45], v[44:45], v[170:171] op_sel_hi:[1,0]
	v_pk_fma_f32 v[44:45], v[44:45], v[172:173], v[242:243]
	v_lshlrev_b32_e32 v244, 16, v217
	v_and_b32_e32 v245, 0xffff0000, v217
	v_pk_mul_f32 v[46:47], v[46:47], v[170:171] op_sel_hi:[1,0]
	v_pk_fma_f32 v[46:47], v[46:47], v[174:175], v[244:245]
	v_lshlrev_b32_e32 v242, 16, v218
	v_and_b32_e32 v243, 0xffff0000, v218
	v_pk_mul_f32 v[40:41], v[40:41], v[170:171] op_sel_hi:[1,0]
	v_pk_fma_f32 v[40:41], v[40:41], v[176:177], v[242:243]
	v_lshlrev_b32_e32 v244, 16, v219
	v_and_b32_e32 v245, 0xffff0000, v219
	v_pk_mul_f32 v[42:43], v[42:43], v[170:171] op_sel_hi:[1,0]
	v_pk_fma_f32 v[42:43], v[42:43], v[178:179], v[244:245]
	v_lshlrev_b32_e32 v242, 16, v220
	v_and_b32_e32 v243, 0xffff0000, v220
	v_pk_mul_f32 v[36:37], v[36:37], v[170:171] op_sel_hi:[1,0]
	v_pk_fma_f32 v[36:37], v[36:37], v[180:181], v[242:243]
	v_lshlrev_b32_e32 v244, 16, v221
	v_and_b32_e32 v245, 0xffff0000, v221
	v_pk_mul_f32 v[38:39], v[38:39], v[170:171] op_sel_hi:[1,0]
	v_pk_fma_f32 v[38:39], v[38:39], v[182:183], v[244:245]
	v_lshlrev_b32_e32 v242, 16, v222
	v_and_b32_e32 v243, 0xffff0000, v222
	v_pk_mul_f32 v[32:33], v[32:33], v[170:171] op_sel_hi:[1,0]
	v_pk_fma_f32 v[32:33], v[32:33], v[184:185], v[242:243]
	v_lshlrev_b32_e32 v244, 16, v223
	v_and_b32_e32 v245, 0xffff0000, v223
	v_pk_mul_f32 v[34:35], v[34:35], v[170:171] op_sel_hi:[1,0]
	v_pk_fma_f32 v[34:35], v[34:35], v[186:187], v[244:245]
	v_pk_mul_f32 v[242:243], v[44:45], v[44:45]
	v_pk_fma_f32 v[242:243], v[46:47], v[46:47], v[242:243]
	v_pk_fma_f32 v[242:243], v[40:41], v[40:41], v[242:243]
	v_pk_fma_f32 v[242:243], v[42:43], v[42:43], v[242:243]
	v_pk_fma_f32 v[242:243], v[36:37], v[36:37], v[242:243]
	v_pk_fma_f32 v[242:243], v[38:39], v[38:39], v[242:243]
	v_pk_fma_f32 v[242:243], v[32:33], v[32:33], v[242:243]
	v_pk_fma_f32 v[242:243], v[34:35], v[34:35], v[242:243]
	v_add_f32_e32 v171, v242, v243
	v_cvt_pk_bf16_f32 v216, v44, v45
	v_cvt_pk_bf16_f32 v217, v46, v47
	v_cvt_pk_bf16_f32 v218, v40, v41
	v_cvt_pk_bf16_f32 v219, v42, v43
	v_cvt_pk_bf16_f32 v220, v36, v37
	v_cvt_pk_bf16_f32 v221, v38, v39
	v_cvt_pk_bf16_f32 v222, v32, v33
	v_cvt_pk_bf16_f32 v223, v34, v35
	v_add_u32_e32 v244, 0x48000, v153
	s_nop 0
	global_store_dwordx4 v244, v[216:219], s[66:67]
	global_store_dwordx4 v244, v[220:223], s[66:67] offset:256
	s_waitcnt vmcnt(10)
	v_lshlrev_b32_e32 v242, 16, v224
	v_and_b32_e32 v243, 0xffff0000, v224
	v_pk_mul_f32 v[28:29], v[28:29], v[192:193] op_sel_hi:[1,0]
	v_pk_fma_f32 v[28:29], v[28:29], v[172:173], v[242:243]
	v_lshlrev_b32_e32 v244, 16, v225
	v_and_b32_e32 v245, 0xffff0000, v225
	v_pk_mul_f32 v[30:31], v[30:31], v[192:193] op_sel_hi:[1,0]
	v_pk_fma_f32 v[30:31], v[30:31], v[174:175], v[244:245]
	v_lshlrev_b32_e32 v242, 16, v226
	v_and_b32_e32 v243, 0xffff0000, v226
	v_pk_mul_f32 v[24:25], v[24:25], v[192:193] op_sel_hi:[1,0]
	v_pk_fma_f32 v[24:25], v[24:25], v[176:177], v[242:243]
	v_lshlrev_b32_e32 v244, 16, v227
	v_and_b32_e32 v245, 0xffff0000, v227
	v_pk_mul_f32 v[26:27], v[26:27], v[192:193] op_sel_hi:[1,0]
	v_pk_fma_f32 v[26:27], v[26:27], v[178:179], v[244:245]
	v_lshlrev_b32_e32 v242, 16, v228
	v_and_b32_e32 v243, 0xffff0000, v228
	v_pk_mul_f32 v[20:21], v[20:21], v[192:193] op_sel_hi:[1,0]
	v_pk_fma_f32 v[20:21], v[20:21], v[180:181], v[242:243]
	v_lshlrev_b32_e32 v244, 16, v229
	v_and_b32_e32 v245, 0xffff0000, v229
	v_pk_mul_f32 v[22:23], v[22:23], v[192:193] op_sel_hi:[1,0]
	v_pk_fma_f32 v[22:23], v[22:23], v[182:183], v[244:245]
	v_lshlrev_b32_e32 v242, 16, v230
	v_and_b32_e32 v243, 0xffff0000, v230
	v_pk_mul_f32 v[16:17], v[16:17], v[192:193] op_sel_hi:[1,0]
	v_pk_fma_f32 v[16:17], v[16:17], v[184:185], v[242:243]
	v_lshlrev_b32_e32 v244, 16, v231
	v_and_b32_e32 v245, 0xffff0000, v231
	v_pk_mul_f32 v[18:19], v[18:19], v[192:193] op_sel_hi:[1,0]
	v_pk_fma_f32 v[18:19], v[18:19], v[186:187], v[244:245]
	v_pk_mul_f32 v[242:243], v[28:29], v[28:29]
	v_pk_fma_f32 v[242:243], v[30:31], v[30:31], v[242:243]
	v_pk_fma_f32 v[242:243], v[24:25], v[24:25], v[242:243]
	v_pk_fma_f32 v[242:243], v[26:27], v[26:27], v[242:243]
	v_pk_fma_f32 v[242:243], v[20:21], v[20:21], v[242:243]
	v_pk_fma_f32 v[242:243], v[22:23], v[22:23], v[242:243]
	v_pk_fma_f32 v[242:243], v[16:17], v[16:17], v[242:243]
	v_pk_fma_f32 v[242:243], v[18:19], v[18:19], v[242:243]
	v_add_f32_e32 v193, v242, v243
	v_cvt_pk_bf16_f32 v224, v28, v29
	v_cvt_pk_bf16_f32 v225, v30, v31
	v_cvt_pk_bf16_f32 v226, v24, v25
	v_cvt_pk_bf16_f32 v227, v26, v27
	v_cvt_pk_bf16_f32 v228, v20, v21
	v_cvt_pk_bf16_f32 v229, v22, v23
	v_cvt_pk_bf16_f32 v230, v16, v17
	v_cvt_pk_bf16_f32 v231, v18, v19
	v_add_u32_e32 v244, 0x50000, v153
	s_nop 0
	global_store_dwordx4 v244, v[224:227], s[66:67]
	global_store_dwordx4 v244, v[228:231], s[66:67] offset:256
	s_waitcnt vmcnt(10)
; __device__ __forceinline__ float bf_lo(unsigned w) { return __uint_as_float(w << 16); }
; __device__ __forceinline__ float bf_hi(unsigned w) { return __uint_as_float(w & 0xffff0000u); }
; __device__ __forceinline__ unsigned pk2(float lo, float hi) { bf16x2_t r = __builtin_convertvector((f32x2_t){lo, hi}, bf16x2_t); return __builtin_bit_cast(unsigned, r); }
; template <bool SRC_F32, bool FINAL, int R> __device__ __forceinline__ void ew_compute(const EwSet<SRC_F32, R>& S, int rb, const f32x4 (&g)[4], bf16* hb_out, float* out32, float scale, float* rs_out, int lane) {
;     ...
;         float s2 = 0.f;
; #pragma unroll
;         for (int j = 0; j < 4; ++j) {
;             f32x4 h;
;             if constexpr (SRC_F32) h = S.h32[i][j];
;             else { const v2u hw = S.hb[i][j]; h.x = bf_lo(hw.x); h.y = bf_hi(hw.x); h.z = bf_lo(hw.y); h.w = bf_hi(hw.y); }
;             const v2u fw = S.fw[i][j];
;             f32x4 v; v.x = h.x + bf_lo(fw.x) * rs * g[j].x; v.y = h.y + bf_hi(fw.x) * rs * g[j].y; v.z = h.z + bf_lo(fw.y) * rs * g[j].z; v.w = h.w + bf_hi(fw.y) * rs * g[j].w;
;             if (FINAL) __builtin_nontemporal_store(v, (f32x4*)(out32 + (size_t)(rb + i) * D) + lane + 64 * j);
;             else { v2u o; o.x = pk2(v.x, v.y); o.y = pk2(v.z, v.w); ((v2u*)(hb_out + (size_t)(rb + i) * D) + lane)[64 * j] = o; s2 += (v.x * v.x + v.y * v.y) + (v.z * v.z + v.w * v.w); }
;         }
;         if (!FINAL) { const float tot = wave_sum(s2); if (lane == 0) rs_out[rb + i] = 1.0f / sqrtf(tot * (1.f / D) + EPS); }
;     }
	v_lshlrev_b32_e32 v242, 16, v232
	v_and_b32_e32 v243, 0xffff0000, v232
	v_pk_mul_f32 v[12:13], v[12:13], v[240:241] op_sel_hi:[1,0]
	v_pk_fma_f32 v[12:13], v[12:13], v[172:173], v[242:243]
	v_lshlrev_b32_e32 v244, 16, v233
	v_and_b32_e32 v245, 0xffff0000, v233
	v_pk_mul_f32 v[14:15], v[14:15], v[240:241] op_sel_hi:[1,0]
	v_pk_fma_f32 v[14:15], v[14:15], v[174:175], v[244:245]
	v_lshlrev_b32_e32 v242, 16, v234
	v_and_b32_e32 v243, 0xffff0000, v234
	v_pk_mul_f32 v[8:9], v[8:9], v[240:241] op_sel_hi:[1,0]
	v_pk_fma_f32 v[8:9], v[8:9], v[176:177], v[242:243]
	v_lshlrev_b32_e32 v244, 16, v235
	v_and_b32_e32 v245, 0xffff0000, v235
	v_pk_mul_f32 v[10:11], v[10:11], v[240:241] op_sel_hi:[1,0]
	v_pk_fma_f32 v[10:11], v[10:11], v[178:179], v[244:245]
	v_lshlrev_b32_e32 v242, 16, v236
	v_and_b32_e32 v243, 0xffff0000, v236
	v_pk_mul_f32 v[4:5], v[4:5], v[240:241] op_sel_hi:[1,0]
	v_pk_fma_f32 v[4:5], v[4:5], v[180:181], v[242:243]
	v_lshlrev_b32_e32 v244, 16, v237
	v_and_b32_e32 v245, 0xffff0000, v237
	v_pk_mul_f32 v[6:7], v[6:7], v[240:241] op_sel_hi:[1,0]
	v_pk_fma_f32 v[6:7], v[6:7], v[182:183], v[244:245]
	v_lshlrev_b32_e32 v242, 16, v238
	v_and_b32_e32 v243, 0xffff0000, v238
	v_pk_mul_f32 v[0:1], v[0:1], v[240:241] op_sel_hi:[1,0]
	v_pk_fma_f32 v[0:1], v[0:1], v[184:185], v[242:243]
	v_lshlrev_b32_e32 v244, 16, v239
	v_and_b32_e32 v245, 0xffff0000, v239
	v_pk_mul_f32 v[2:3], v[2:3], v[240:241] op_sel_hi:[1,0]
	v_pk_fma_f32 v[2:3], v[2:3], v[186:187], v[244:245]
	v_pk_mul_f32 v[242:243], v[12:13], v[12:13]
	v_pk_fma_f32 v[242:243], v[14:15], v[14:15], v[242:243]
	v_pk_fma_f32 v[242:243], v[8:9], v[8:9], v[242:243]
	v_pk_fma_f32 v[242:243], v[10:11], v[10:11], v[242:243]
	v_pk_fma_f32 v[242:243], v[4:5], v[4:5], v[242:243]
	v_pk_fma_f32 v[242:243], v[6:7], v[6:7], v[242:243]
	v_pk_fma_f32 v[242:243], v[0:1], v[0:1], v[242:243]
	v_pk_fma_f32 v[242:243], v[2:3], v[2:3], v[242:243]
	v_add_f32_e32 v241, v242, v243
	v_cvt_pk_bf16_f32 v232, v12, v13
	v_cvt_pk_bf16_f32 v233, v14, v15
	v_cvt_pk_bf16_f32 v234, v8, v9
	v_cvt_pk_bf16_f32 v235, v10, v11
	v_cvt_pk_bf16_f32 v236, v4, v5
	v_cvt_pk_bf16_f32 v237, v6, v7
	v_cvt_pk_bf16_f32 v238, v0, v1
	v_cvt_pk_bf16_f32 v239, v2, v3
	v_add_u32_e32 v244, 0x58000, v153
	s_nop 0
	global_store_dwordx4 v244, v[232:235], s[66:67]
	global_store_dwordx4 v244, v[236:239], s[66:67] offset:256
	s_nop 1
	ds_bpermute_b32 v172, v166, v145
	ds_bpermute_b32 v173, v166, v155
	ds_bpermute_b32 v174, v166, v159
	ds_bpermute_b32 v175, v166, v163
	ds_bpermute_b32 v176, v166, v165
	ds_bpermute_b32 v177, v166, v171
	ds_bpermute_b32 v178, v166, v193
	ds_bpermute_b32 v179, v166, v241
	s_waitcnt lgkmcnt(0)
	v_add_f32_e32 v145, v145, v172
	v_add_f32_e32 v155, v155, v173
	v_add_f32_e32 v159, v159, v174
	v_add_f32_e32 v163, v163, v175
	v_add_f32_e32 v165, v165, v176
	v_add_f32_e32 v171, v171, v177
	v_add_f32_e32 v193, v193, v178
	v_add_f32_e32 v241, v241, v179
	s_nop 1
	ds_bpermute_b32 v172, v168, v145
	ds_bpermute_b32 v173, v168, v155
	ds_bpermute_b32 v174, v168, v159
	ds_bpermute_b32 v175, v168, v163
	ds_bpermute_b32 v176, v168, v165
	ds_bpermute_b32 v177, v168, v171
	ds_bpermute_b32 v178, v168, v193
	ds_bpermute_b32 v179, v168, v241
	s_waitcnt lgkmcnt(0)
	v_add_f32_e32 v145, v145, v172
	v_add_f32_e32 v155, v155, v173
	v_add_f32_e32 v159, v159, v174
	v_add_f32_e32 v163, v163, v175
	v_add_f32_e32 v165, v165, v176
	v_add_f32_e32 v171, v171, v177
	v_add_f32_e32 v193, v193, v178
	v_add_f32_e32 v241, v241, v179
	global_store_dword v157, v145, s[78:79]
	v_add_u32_e32 v173, 0x400, v157
	global_store_dword v173, v155, s[78:79]
	v_add_u32_e32 v174, 0x800, v157
	global_store_dword v174, v159, s[78:79]
	v_add_u32_e32 v175, 0xc00, v157
	global_store_dword v175, v163, s[78:79]
	v_add_u32_e32 v176, 0x2000, v157
	global_store_dword v176, v165, s[78:79]
	v_add_u32_e32 v177, 0x2400, v157
	global_store_dword v177, v171, s[78:79]
	v_add_u32_e32 v178, 0x2800, v157
	global_store_dword v178, v193, s[78:79]
	v_add_u32_e32 v179, 0x2c00, v157
	global_store_dword v179, v241, s[78:79]
	s_andn2_b64 vcc, exec, s[0:1]
	s_mov_b64 s[0:1], -1
	s_cbranch_vccnz .LBB0_878
	s_andn2_b64 vcc, exec, s[8:9]
	s_cbranch_vccnz .LBB0_877
	s_barrier
	s_branch .LBB0_877

; __device__ __forceinline__ unsigned xb_ld(unsigned* p)              { return __hip_atomic_load(p, __ATOMIC_RELAXED, __HIP_MEMORY_SCOPE_AGENT); }
; __device__ __forceinline__ unsigned xb_add(unsigned* p, unsigned v) { return __hip_atomic_fetch_add(p, v, __ATOMIC_RELAXED, __HIP_MEMORY_SCOPE_AGENT); }
; #define XB_SPIN(cond, bar) do { unsigned _sp = 0; while (cond) { __builtin_amdgcn_s_sleep(1); \
;     if ((++_sp & 255u) == 0u) { if (xb_ld(&(bar)[XB_TMO])) break; if (_sp > XB_SPIN_CAP) { atomicAdd(&(bar)[XB_TMO], 1u); break; } } } } while (0)
; __device__ __forceinline__ void xcd_barrier(const XcdBarrier& b) {
;     asm volatile("s_waitcnt vmcnt(0)" ::: "memory");
;     __syncthreads();
;     if (threadIdx.x == 0) {
;         unsigned* bar = b.bar;
;         __builtin_amdgcn_s_waitcnt(0);
;         unsigned nloc = b.st[0], nx = b.st[1];
;         if (nloc == 0u) { xcd_barrier_complete(bar, b.x, nloc, nx); b.st[0] = nloc; b.st[1] = nx; }
;         const unsigned old = xb_add(&bar[XB_XSUB(b.x)], 1u);
;         const unsigned gen = old / nloc;
;         if (old + 1u == (gen + 1u) * nloc) {
;             __builtin_amdgcn_fence(__ATOMIC_RELEASE, "agent");
;             asm volatile("s_waitcnt vmcnt(0)" ::: "memory");
;             const unsigned og = xb_add(&bar[XB_TOP], 1u);
;             const unsigned tg = og / nx;
;             if (og + 1u == (tg + 1u) * nx) xb_add(&bar[XB_TOPGEN], 1u);
;             else XB_SPIN(xb_ld(&bar[XB_TOPGEN]) == tg, bar);
;             __builtin_amdgcn_fence(__ATOMIC_ACQUIRE, "agent");
;             xb_add(&bar[XB_XGEN(b.x)], 1u);
;             asm volatile("s_waitcnt vmcnt(0)" ::: "memory");
;         } else {
;             XB_SPIN(xb_ld(&bar[XB_XGEN(b.x)]) == gen, bar);
;             __builtin_amdgcn_fence(__ATOMIC_ACQUIRE, "agent");
;             asm volatile("s_waitcnt vmcnt(0)" ::: "memory");
;         }
;     }
;     __syncthreads();
; }
.Ltb1039_frel:
.Ltb1039_done:
	s_or_b64 exec, exec, s[4:5]
	s_barrier
	s_mov_b32 s100, 24

;     __device__ __forceinline__ void operator()(const pg8::f32x4 (&acc)[2][2][4][2], const pg8::Unit& u, int wr, int wc, int fr, int fq) const {
;     ...
;             for (int m = 0; m < 4; ++m) {
;                 const int row = row0 + ai * 128 + m * 16;
;                 const size_t off = (size_t)row * D + col0;
;                 float s = 0.f;
; #pragma unroll
;                 for (int bj = 0; bj < 2; ++bj) {
;                     float r[8];
; #pragma unroll
;                     for (int j = 0; j < 4; ++j) { r[j] = acc[ai][bj][m][0][j]; r[4 + j] = acc[ai][bj][m][1][j]; }
;                     if (RSCALE) { const float rv = rvs[ai][m];
; #pragma unroll
;                         for (int j = 0; j < 8; ++j) r[j] *= rv; }
;                     if (ACT == 1) {
; #pragma unroll
;                         for (int j = 0; j < 8; ++j) r[j] = sigmoid_fast(r[j]);
;                     }
;                     if (GATE) { const v4u g = gq[m][bj];
;                         r[0] *= bf_lo(g.x); r[1] *= bf_hi(g.x); r[2] *= bf_lo(g.y); r[3] *= bf_hi(g.y); r[4] *= bf_lo(g.z); r[5] *= bf_hi(g.z); r[6] *= bf_lo(g.w); r[7] *= bf_hi(g.w); }
;                     if (ADD) { const v4u g = aq[m][bj];
;                         r[0] += bf_lo(g.x); r[1] += bf_hi(g.x); r[2] += bf_lo(g.y); r[3] += bf_hi(g.y); r[4] += bf_lo(g.z); r[5] += bf_hi(g.z); r[6] += bf_lo(g.w); r[7] += bf_hi(g.w); }
;                     if (PART) {
; #pragma unroll
;                         for (int j = 0; j < 8; ++j) s += r[j] * r[j];
;                     }
;                     v4u w; w.x = pk2(r[0], r[1]); w.y = pk2(r[2], r[3]); w.z = pk2(r[4], r[5]); w.w = pk2(r[6], r[7]);
;                     st16_wt(O + off + bj * 128, w);
;                 }
;                 if (PART) { s += __shfl_xor(s, 16); s += __shfl_xor(s, 32); st4_wt(part + (size_t)row * 16 + u.pn * 4 + wc, s); }
; template <bool SRC_F32, int R> __device__ __forceinline__ void ew_load(EwSet<SRC_F32, R>& S, int rb, const float* hsrc32, const bf16* hsrcb, const bf16* f, const float* part, int lane) {
; #pragma unroll
;     for (int i = 0; i < R; ++i) S.p[i] = (lane < 16) ? part[(size_t)(rb + i) * 16 + lane] : 0.f;
; #pragma unroll
;     for (int i = 0; i < R; ++i)
; #pragma unroll
;         for (int j = 0; j < 4; ++j) {
;             S.fw[i][j] = ((const v2u*)(f + (size_t)(rb + i) * D) + lane)[64 * j];
.LBB0_1159:
	s_waitcnt lgkmcnt(0)
	v_lshl_or_b32 v238, s52, 8, v148
	v_lshl_add_u32 v239, s51, 8, v146
	v_lshlrev_b32_e32 v243, 2, v238
	v_lshlrev_b32_e32 v153, 1, v238
	v_lshl_add_u32 v153, v239, 11, v153
	v_xor_b32_e32 v194, 16, v152
	v_lshlrev_b32_e32 v194, 2, v194
	v_xor_b32_e32 v242, 32, v152
	v_lshlrev_b32_e32 v242, 2, v242
	v_lshrrev_b32_e32 v168, 4, v152
	v_and_b32_e32 v168, 3, v168
	v_lshlrev_b32_e32 v168, 4, v168
	v_lshl_add_u32 v168, v239, 6, v168
	s_lshl_b32 s95, s52, 4
	s_add_u32 s95, s95, s8
	v_lshl_add_u32 v166, v239, 6, s95
	v_pk_mul_f32 v[238:239], v[124:125], v[124:125]
	v_pk_fma_f32 v[238:239], v[126:127], v[126:127], v[238:239]
	v_pk_fma_f32 v[238:239], v[120:121], v[120:121], v[238:239]
	v_pk_fma_f32 v[238:239], v[122:123], v[122:123], v[238:239]
	v_pk_fma_f32 v[238:239], v[116:117], v[116:117], v[238:239]
	v_pk_fma_f32 v[238:239], v[118:119], v[118:119], v[238:239]
	v_pk_fma_f32 v[238:239], v[112:113], v[112:113], v[238:239]
	v_pk_fma_f32 v[238:239], v[114:115], v[114:115], v[238:239]
	v_add_f32_e32 v145, v238, v239
	v_pk_mul_f32 v[240:241], v[108:109], v[108:109]
	v_pk_fma_f32 v[240:241], v[110:111], v[110:111], v[240:241]
	v_pk_fma_f32 v[240:241], v[104:105], v[104:105], v[240:241]
	v_pk_fma_f32 v[240:241], v[106:107], v[106:107], v[240:241]
	v_pk_fma_f32 v[240:241], v[100:101], v[100:101], v[240:241]
	v_pk_fma_f32 v[240:241], v[102:103], v[102:103], v[240:241]
	v_pk_fma_f32 v[240:241], v[96:97], v[96:97], v[240:241]
	v_pk_fma_f32 v[240:241], v[98:99], v[98:99], v[240:241]
	v_add_f32_e32 v155, v240, v241
	v_pk_mul_f32 v[238:239], v[92:93], v[92:93]
	v_pk_fma_f32 v[238:239], v[94:95], v[94:95], v[238:239]
	v_pk_fma_f32 v[238:239], v[88:89], v[88:89], v[238:239]
	v_pk_fma_f32 v[238:239], v[90:91], v[90:91], v[238:239]
	v_pk_fma_f32 v[238:239], v[84:85], v[84:85], v[238:239]
	v_pk_fma_f32 v[238:239], v[86:87], v[86:87], v[238:239]
	v_pk_fma_f32 v[238:239], v[80:81], v[80:81], v[238:239]
	v_pk_fma_f32 v[238:239], v[82:83], v[82:83], v[238:239]
	v_add_f32_e32 v165, v238, v239
	v_pk_mul_f32 v[240:241], v[76:77], v[76:77]
	v_pk_fma_f32 v[240:241], v[78:79], v[78:79], v[240:241]
	v_pk_fma_f32 v[240:241], v[72:73], v[72:73], v[240:241]
	v_pk_fma_f32 v[240:241], v[74:75], v[74:75], v[240:241]
	v_pk_fma_f32 v[240:241], v[68:69], v[68:69], v[240:241]
	v_pk_fma_f32 v[240:241], v[70:71], v[70:71], v[240:241]
	v_pk_fma_f32 v[240:241], v[64:65], v[64:65], v[240:241]
	v_pk_fma_f32 v[240:241], v[66:67], v[66:67], v[240:241]
	v_add_f32_e32 v171, v240, v241
	v_pk_mul_f32 v[238:239], v[60:61], v[60:61]
	v_pk_fma_f32 v[238:239], v[62:63], v[62:63], v[238:239]
	v_pk_fma_f32 v[238:239], v[56:57], v[56:57], v[238:239]
	v_pk_fma_f32 v[238:239], v[58:59], v[58:59], v[238:239]
	v_pk_fma_f32 v[238:239], v[52:53], v[52:53], v[238:239]
	v_pk_fma_f32 v[238:239], v[54:55], v[54:55], v[238:239]
	v_pk_fma_f32 v[238:239], v[48:49], v[48:49], v[238:239]
	v_pk_fma_f32 v[238:239], v[50:51], v[50:51], v[238:239]
	v_add_f32_e32 v193, v238, v239
	v_pk_mul_f32 v[240:241], v[44:45], v[44:45]
	v_pk_fma_f32 v[240:241], v[46:47], v[46:47], v[240:241]
	v_pk_fma_f32 v[240:241], v[40:41], v[40:41], v[240:241]
	v_pk_fma_f32 v[240:241], v[42:43], v[42:43], v[240:241]
	v_pk_fma_f32 v[240:241], v[36:37], v[36:37], v[240:241]
	v_pk_fma_f32 v[240:241], v[38:39], v[38:39], v[240:241]
	v_pk_fma_f32 v[240:241], v[32:33], v[32:33], v[240:241]
	v_pk_fma_f32 v[240:241], v[34:35], v[34:35], v[240:241]
	v_add_f32_e32 v233, v240, v241
	v_pk_mul_f32 v[238:239], v[28:29], v[28:29]
	v_pk_fma_f32 v[238:239], v[30:31], v[30:31], v[238:239]
	v_pk_fma_f32 v[238:239], v[24:25], v[24:25], v[238:239]
	v_pk_fma_f32 v[238:239], v[26:27], v[26:27], v[238:239]
	v_pk_fma_f32 v[238:239], v[20:21], v[20:21], v[238:239]
	v_pk_fma_f32 v[238:239], v[22:23], v[22:23], v[238:239]
	v_pk_fma_f32 v[238:239], v[16:17], v[16:17], v[238:239]
	v_pk_fma_f32 v[238:239], v[18:19], v[18:19], v[238:239]
	v_add_f32_e32 v235, v238, v239
	v_pk_mul_f32 v[240:241], v[12:13], v[12:13]
	v_pk_fma_f32 v[240:241], v[14:15], v[14:15], v[240:241]
	v_pk_fma_f32 v[240:241], v[8:9], v[8:9], v[240:241]
	v_pk_fma_f32 v[240:241], v[10:11], v[10:11], v[240:241]
	v_pk_fma_f32 v[240:241], v[4:5], v[4:5], v[240:241]
	v_pk_fma_f32 v[240:241], v[6:7], v[6:7], v[240:241]
	v_pk_fma_f32 v[240:241], v[0:1], v[0:1], v[240:241]
	v_pk_fma_f32 v[240:241], v[2:3], v[2:3], v[240:241]
	v_add_f32_e32 v237, v240, v241
	s_nop 1
	ds_bpermute_b32 v180, v194, v145
	ds_bpermute_b32 v184, v194, v155
	ds_bpermute_b32 v188, v194, v165
	ds_bpermute_b32 v196, v194, v171
	ds_bpermute_b32 v200, v194, v193
	ds_bpermute_b32 v204, v194, v233
	ds_bpermute_b32 v208, v194, v235
	ds_bpermute_b32 v212, v194, v237
	s_waitcnt lgkmcnt(0)
	v_add_f32_e32 v145, v145, v180
	v_add_f32_e32 v155, v155, v184
	v_add_f32_e32 v165, v165, v188
	v_add_f32_e32 v171, v171, v196
	v_add_f32_e32 v193, v193, v200
	v_add_f32_e32 v233, v233, v204
	v_add_f32_e32 v235, v235, v208
	v_add_f32_e32 v237, v237, v212
	s_nop 1
	ds_bpermute_b32 v180, v242, v145
	ds_bpermute_b32 v184, v242, v155
	ds_bpermute_b32 v188, v242, v165
	ds_bpermute_b32 v196, v242, v171
	ds_bpermute_b32 v200, v242, v193
	ds_bpermute_b32 v204, v242, v233
	ds_bpermute_b32 v208, v242, v235
	ds_bpermute_b32 v212, v242, v237
	s_waitcnt lgkmcnt(0)
	v_add_f32_e32 v145, v145, v180
	v_add_f32_e32 v155, v155, v184
	v_add_f32_e32 v165, v165, v188
	v_add_f32_e32 v171, v171, v196
	v_add_f32_e32 v193, v193, v200
	v_add_f32_e32 v233, v233, v204
	v_add_f32_e32 v235, v235, v208
	v_add_f32_e32 v237, v237, v212
	global_store_dword v166, v145, s[20:21]
	v_add_u32_e32 v184, 0x400, v166
	global_store_dword v184, v155, s[20:21]
	v_add_u32_e32 v188, 0x800, v166
	global_store_dword v188, v165, s[20:21]
	v_add_u32_e32 v196, 0xc00, v166
	global_store_dword v196, v171, s[20:21]
	v_add_u32_e32 v200, 0x2000, v166
	global_store_dword v200, v193, s[20:21]
	v_add_u32_e32 v204, 0x2400, v166
	global_store_dword v204, v233, s[20:21]
	v_add_u32_e32 v208, 0x2800, v166
	global_store_dword v208, v235, s[20:21]
	v_add_u32_e32 v212, 0x2c00, v166
	global_store_dword v212, v237, s[20:21]
	s_add_u32 s62, s84, 0xffffff10
	s_addc_u32 s63, s85, -1
	s_load_dwordx2 s[64:65], s[62:63], 0xb0
	s_add_u32 s66, s28, 0x5000000
	s_addc_u32 s67, s29, 0
	s_add_u32 s78, s28, 0x4c00000
	s_addc_u32 s79, s29, 0
	global_load_dwordx4 v[216:219], v153, s[66:67]
	global_load_dwordx4 v[220:223], v153, s[66:67] offset:256
	v_add_u32_e32 v240, 0x8000, v153
	global_load_dwordx4 v[224:227], v240, s[66:67]
	global_load_dwordx4 v[228:231], v240, s[66:67] offset:256
	s_waitcnt lgkmcnt(0)
	global_load_dwordx4 v[156:159], v243, s[64:65]
	global_load_dwordx4 v[160:163], v243, s[64:65] offset:16
	global_load_dwordx4 v[172:175], v243, s[64:65] offset:512
	global_load_dwordx4 v[176:179], v243, s[64:65] offset:528
	s_waitcnt vmcnt(0)
	s_barrier
; __device__ __forceinline__ unsigned xb_ld(unsigned* p)              { return __hip_atomic_load(p, __ATOMIC_RELAXED, __HIP_MEMORY_SCOPE_AGENT); }
; __device__ __forceinline__ unsigned xb_add(unsigned* p, unsigned v) { return __hip_atomic_fetch_add(p, v, __ATOMIC_RELAXED, __HIP_MEMORY_SCOPE_AGENT); }
; #define XB_SPIN(cond, bar) do { unsigned _sp = 0; while (cond) { __builtin_amdgcn_s_sleep(1); \
;     if ((++_sp & 255u) == 0u) { if (xb_ld(&(bar)[XB_TMO])) break; if (_sp > XB_SPIN_CAP) { atomicAdd(&(bar)[XB_TMO], 1u); break; } } } } while (0)
; __device__ __forceinline__ void xcd_barrier(const XcdBarrier& b) {
;     ...
;         const unsigned old = xb_add(&bar[XB_XSUB(b.x)], 1u);
;         const unsigned gen = old / nloc;
;         if (old + 1u == (gen + 1u) * nloc) {
;             __builtin_amdgcn_fence(__ATOMIC_RELEASE, "agent");
;             asm volatile("s_waitcnt vmcnt(0)" ::: "memory");
;             const unsigned og = xb_add(&bar[XB_TOP], 1u);
;             const unsigned tg = og / nx;
;             if (og + 1u == (tg + 1u) * nx) xb_add(&bar[XB_TOPGEN], 1u);
;             else XB_SPIN(xb_ld(&bar[XB_TOPGEN]) == tg, bar);
;             __builtin_amdgcn_fence(__ATOMIC_ACQUIRE, "agent");
;             xb_add(&bar[XB_XGEN(b.x)], 1u);
;             asm volatile("s_waitcnt vmcnt(0)" ::: "memory");
;         } else {
;             XB_SPIN(xb_ld(&bar[XB_XGEN(b.x)]) == gen, bar);
	v_readfirstlane_b32 s94, v195
	s_cmp_lg_u32 s94, 0
	s_cbranch_scc1 .Lfe2_bskip
	s_mov_b64 exec, 1
	s_and_b32 s94, s2, 7
	s_lshl_b32 s94, s94, 3
	s_bfe_u32 s96, s2, 0x30003
	s_or_b32 s94, s94, s96
	s_lshl_b32 s94, s94, 5
	s_add_u32 s62, s28, 0x3903600
	s_addc_u32 s63, s29, 0
	v_mov_b32_e32 v238, s94
	v_mov_b32_e32 v239, 1
	s_cmp_eq_u32 s99, 1
	s_cbranch_scc1 .Lfe2_bfast
	buffer_wbl2 sc1
	s_waitcnt vmcnt(0)
.Lfe2_bfast:
	global_atomic_add v240, v238, v239, s[62:63] offset:8 sc0
	buffer_inv sc1
	s_waitcnt vmcnt(0)
	v_add_u32_e32 v241, 1, v240
	v_and_b32_e32 v241, 3, v241
	v_cmp_eq_u32_e32 vcc, 0, v241
	s_cbranch_vccnz .Lfe2_bdone
	v_lshrrev_b32_e32 v240, 2, v240
	v_add_u32_e32 v240, 1, v240
	v_lshlrev_b32_e32 v240, 2, v240
	s_mov_b32 s94, 0

; __device__ __forceinline__ float bf_lo(unsigned w) { return __uint_as_float(w << 16); }
; __device__ __forceinline__ float bf_hi(unsigned w) { return __uint_as_float(w & 0xffff0000u); }
; template <bool SRC_F32, int R> __device__ __forceinline__ void ew_load(EwSet<SRC_F32, R>& S, int rb, const float* hsrc32, const bf16* hsrcb, const bf16* f, const float* part, int lane) {
; #pragma unroll
;     for (int i = 0; i < R; ++i) S.p[i] = (lane < 16) ? part[(size_t)(rb + i) * 16 + lane] : 0.f;
; #pragma unroll
;     for (int i = 0; i < R; ++i)
; #pragma unroll
;         for (int j = 0; j < 4; ++j) {
;             S.fw[i][j] = ((const v2u*)(f + (size_t)(rb + i) * D) + lane)[64 * j];
;             if constexpr (SRC_F32) S.h32[i][j] = __builtin_nontemporal_load((const f32x4*)(hsrc32 + (size_t)(rb + i) * D) + lane + 64 * j);
;             else S.hb[i][j] = ((const v2u*)(hsrcb + (size_t)(rb + i) * D) + lane)[64 * j];
;         }
; }
; template <bool SRC_F32, bool FINAL, int R> __device__ __forceinline__ void ew_compute(const EwSet<SRC_F32, R>& S, int rb, const f32x4 (&g)[4], bf16* hb_out, float* out32, float scale, float* rs_out, int lane) {
; #pragma unroll
;     for (int i = 0; i < R; ++i) {
;         float q = S.p[i];
;         q += __shfl_xor(q, 1); q += __shfl_xor(q, 2); q += __shfl_xor(q, 4); q += __shfl_xor(q, 8);
;         const float ss = __shfl(q, 0);
;         const float rs = scale / sqrtf(ss * (1.f / D) + EPS);
;         float s2 = 0.f;
; #pragma unroll
;         for (int j = 0; j < 4; ++j) {
;             f32x4 h;
;             if constexpr (SRC_F32) h = S.h32[i][j];
;             else { const v2u hw = S.hb[i][j]; h.x = bf_lo(hw.x); h.y = bf_hi(hw.x); h.z = bf_lo(hw.y); h.w = bf_hi(hw.y); }
;             const v2u fw = S.fw[i][j];
;             f32x4 v; v.x = h.x + bf_lo(fw.x) * rs * g[j].x; v.y = h.y + bf_hi(fw.x) * rs * g[j].y; v.z = h.z + bf_lo(fw.y) * rs * g[j].z; v.w = h.w + bf_hi(fw.y) * rs * g[j].w;
;             if (FINAL) __builtin_nontemporal_store(v, (f32x4*)(out32 + (size_t)(rb + i) * D) + lane + 64 * j);
;             else { v2u o; o.x = pk2(v.x, v.y); o.y = pk2(v.z, v.w); ((v2u*)(hb_out + (size_t)(rb + i) * D) + lane)[64 * j] = o; s2 += (v.x * v.x + v.y * v.y) + (v.z * v.z + v.w * v.w); }
;         }
.Lfe2_bskip:
	s_barrier
	global_load_dwordx4 v[180:183], v168, s[20:21]
	v_add_u32_e32 v240, 0x400, v168
	global_load_dwordx4 v[184:187], v240, s[20:21]
	v_add_u32_e32 v240, 0x800, v168
	global_load_dwordx4 v[188:191], v240, s[20:21]
	v_add_u32_e32 v240, 0xc00, v168
	global_load_dwordx4 v[196:199], v240, s[20:21]
	v_add_u32_e32 v240, 0x2000, v168
	global_load_dwordx4 v[200:203], v240, s[20:21]
	v_add_u32_e32 v240, 0x2400, v168
	global_load_dwordx4 v[204:207], v240, s[20:21]
	v_add_u32_e32 v240, 0x2800, v168
	global_load_dwordx4 v[208:211], v240, s[20:21]
	v_add_u32_e32 v240, 0x2c00, v168
	global_load_dwordx4 v[212:215], v240, s[20:21]
	s_waitcnt vmcnt(0)
	v_add_f32_e32 v145, v180, v181
	v_add_f32_e32 v145, v182, v145
	v_add_f32_e32 v145, v183, v145
	v_add_f32_e32 v155, v184, v185
	v_add_f32_e32 v155, v186, v155
	v_add_f32_e32 v155, v187, v155
	v_add_f32_e32 v165, v188, v189
	v_add_f32_e32 v165, v190, v165
	v_add_f32_e32 v165, v191, v165
	v_add_f32_e32 v171, v196, v197
	v_add_f32_e32 v171, v198, v171
	v_add_f32_e32 v171, v199, v171
	v_add_f32_e32 v193, v200, v201
	v_add_f32_e32 v193, v202, v193
	v_add_f32_e32 v193, v203, v193
	v_add_f32_e32 v233, v204, v205
	v_add_f32_e32 v233, v206, v233
	v_add_f32_e32 v233, v207, v233
	v_add_f32_e32 v235, v208, v209
	v_add_f32_e32 v235, v210, v235
	v_add_f32_e32 v235, v211, v235
	v_add_f32_e32 v237, v212, v213
	v_add_f32_e32 v237, v214, v237
	v_add_f32_e32 v237, v215, v237
	s_nop 1
	ds_bpermute_b32 v180, v194, v145
	ds_bpermute_b32 v184, v194, v155
	ds_bpermute_b32 v188, v194, v165
	ds_bpermute_b32 v196, v194, v171
	ds_bpermute_b32 v200, v194, v193
	ds_bpermute_b32 v204, v194, v233
	ds_bpermute_b32 v208, v194, v235
	ds_bpermute_b32 v212, v194, v237
	s_waitcnt lgkmcnt(0)
	v_add_f32_e32 v145, v145, v180
	v_add_f32_e32 v155, v155, v184
	v_add_f32_e32 v165, v165, v188
	v_add_f32_e32 v171, v171, v196
	v_add_f32_e32 v193, v193, v200
	v_add_f32_e32 v233, v233, v204
	v_add_f32_e32 v235, v235, v208
	v_add_f32_e32 v237, v237, v212
	s_nop 1
	ds_bpermute_b32 v180, v242, v145
	ds_bpermute_b32 v184, v242, v155
	ds_bpermute_b32 v188, v242, v165
	ds_bpermute_b32 v196, v242, v171
	ds_bpermute_b32 v200, v242, v193
	ds_bpermute_b32 v204, v242, v233
	ds_bpermute_b32 v208, v242, v235
	ds_bpermute_b32 v212, v242, v237
	s_waitcnt lgkmcnt(0)
	v_add_f32_e32 v145, v145, v180
	v_add_f32_e32 v155, v155, v184
	v_add_f32_e32 v165, v165, v188
	v_add_f32_e32 v171, v171, v196
	v_add_f32_e32 v193, v193, v200
	v_add_f32_e32 v233, v233, v204
	v_add_f32_e32 v235, v235, v208
	v_add_f32_e32 v237, v237, v212
	v_mul_f32_e32 v145, 0x3a800000, v145
	v_mul_f32_e32 v155, 0x3a800000, v155
	v_mul_f32_e32 v165, 0x3a800000, v165
	v_mul_f32_e32 v171, 0x3a800000, v171
	v_mul_f32_e32 v193, 0x3a800000, v193
	v_mul_f32_e32 v233, 0x3a800000, v233
	v_mul_f32_e32 v235, 0x3a800000, v235
	v_mul_f32_e32 v237, 0x3a800000, v237
	v_add_f32_e32 v145, 0x358637bd, v145
	v_add_f32_e32 v155, 0x358637bd, v155
	v_add_f32_e32 v165, 0x358637bd, v165
	v_add_f32_e32 v171, 0x358637bd, v171
	v_add_f32_e32 v193, 0x358637bd, v193
	v_add_f32_e32 v233, 0x358637bd, v233
	v_add_f32_e32 v235, 0x358637bd, v235
	v_add_f32_e32 v237, 0x358637bd, v237
	v_rsq_f32_e32 v144, v145
	v_rsq_f32_e32 v154, v155
	v_rsq_f32_e32 v164, v165
	v_rsq_f32_e32 v170, v171
	v_rsq_f32_e32 v192, v193
	v_rsq_f32_e32 v232, v233
	v_rsq_f32_e32 v234, v235
	v_rsq_f32_e32 v236, v237
	s_nop 0
	v_mul_f32_e32 v144, 0x3f000000, v144
	v_mul_f32_e32 v154, 0x3f000000, v154
	v_mul_f32_e32 v164, 0x3f000000, v164
	v_mul_f32_e32 v170, 0x3f000000, v170
	v_mul_f32_e32 v192, 0x3f000000, v192
	v_mul_f32_e32 v232, 0x3f000000, v232
	v_mul_f32_e32 v234, 0x3f000000, v234
	v_mul_f32_e32 v236, 0x3f000000, v236
	v_add_u32_e32 v240, 0x10000, v153
	global_load_dwordx4 v[180:183], v240, s[66:67]
	global_load_dwordx4 v[184:187], v240, s[66:67] offset:256
	v_add_u32_e32 v240, 0x18000, v153
	global_load_dwordx4 v[188:191], v240, s[66:67]
	global_load_dwordx4 v[196:199], v240, s[66:67] offset:256
	v_add_u32_e32 v240, 0x40000, v153
	global_load_dwordx4 v[200:203], v240, s[66:67]
	global_load_dwordx4 v[204:207], v240, s[66:67] offset:256
	v_add_u32_e32 v240, 0x48000, v153
	global_load_dwordx4 v[208:211], v240, s[66:67]
	global_load_dwordx4 v[212:215], v240, s[66:67] offset:256
	v_lshlrev_b32_e32 v238, 16, v216
	v_and_b32_e32 v239, 0xffff0000, v216
	v_pk_mul_f32 v[124:125], v[124:125], v[144:145] op_sel_hi:[1,0]
	v_pk_fma_f32 v[124:125], v[124:125], v[156:157], v[238:239]
	v_lshlrev_b32_e32 v240, 16, v217
	v_and_b32_e32 v241, 0xffff0000, v217
	v_pk_mul_f32 v[126:127], v[126:127], v[144:145] op_sel_hi:[1,0]
	v_pk_fma_f32 v[126:127], v[126:127], v[158:159], v[240:241]
	v_lshlrev_b32_e32 v238, 16, v218
	v_and_b32_e32 v239, 0xffff0000, v218
	v_pk_mul_f32 v[120:121], v[120:121], v[144:145] op_sel_hi:[1,0]
	v_pk_fma_f32 v[120:121], v[120:121], v[160:161], v[238:239]
	v_lshlrev_b32_e32 v240, 16, v219
	v_and_b32_e32 v241, 0xffff0000, v219
	v_pk_mul_f32 v[122:123], v[122:123], v[144:145] op_sel_hi:[1,0]
	v_pk_fma_f32 v[122:123], v[122:123], v[162:163], v[240:241]
	v_lshlrev_b32_e32 v238, 16, v220
	v_and_b32_e32 v239, 0xffff0000, v220
	v_pk_mul_f32 v[116:117], v[116:117], v[144:145] op_sel_hi:[1,0]
	v_pk_fma_f32 v[116:117], v[116:117], v[172:173], v[238:239]
	v_lshlrev_b32_e32 v240, 16, v221
	v_and_b32_e32 v241, 0xffff0000, v221
	v_pk_mul_f32 v[118:119], v[118:119], v[144:145] op_sel_hi:[1,0]
	v_pk_fma_f32 v[118:119], v[118:119], v[174:175], v[240:241]
	v_lshlrev_b32_e32 v238, 16, v222
	v_and_b32_e32 v239, 0xffff0000, v222
	v_pk_mul_f32 v[112:113], v[112:113], v[144:145] op_sel_hi:[1,0]
	v_pk_fma_f32 v[112:113], v[112:113], v[176:177], v[238:239]
; __device__ __forceinline__ float bf_lo(unsigned w) { return __uint_as_float(w << 16); }
; __device__ __forceinline__ float bf_hi(unsigned w) { return __uint_as_float(w & 0xffff0000u); }
; __device__ __forceinline__ unsigned pk2(float lo, float hi) { bf16x2_t r = __builtin_convertvector((f32x2_t){lo, hi}, bf16x2_t); return __builtin_bit_cast(unsigned, r); }
; template <bool SRC_F32, bool FINAL, int R> __device__ __forceinline__ void ew_compute(const EwSet<SRC_F32, R>& S, int rb, const f32x4 (&g)[4], bf16* hb_out, float* out32, float scale, float* rs_out, int lane) {
;     ...
; #pragma unroll
;         for (int j = 0; j < 4; ++j) {
;             f32x4 h;
;             if constexpr (SRC_F32) h = S.h32[i][j];
;             else { const v2u hw = S.hb[i][j]; h.x = bf_lo(hw.x); h.y = bf_hi(hw.x); h.z = bf_lo(hw.y); h.w = bf_hi(hw.y); }
;             const v2u fw = S.fw[i][j];
;             f32x4 v; v.x = h.x + bf_lo(fw.x) * rs * g[j].x; v.y = h.y + bf_hi(fw.x) * rs * g[j].y; v.z = h.z + bf_lo(fw.y) * rs * g[j].z; v.w = h.w + bf_hi(fw.y) * rs * g[j].w;
;             if (FINAL) __builtin_nontemporal_store(v, (f32x4*)(out32 + (size_t)(rb + i) * D) + lane + 64 * j);
;             else { v2u o; o.x = pk2(v.x, v.y); o.y = pk2(v.z, v.w); ((v2u*)(hb_out + (size_t)(rb + i) * D) + lane)[64 * j] = o; s2 += (v.x * v.x + v.y * v.y) + (v.z * v.z + v.w * v.w); }
;         }
	v_lshlrev_b32_e32 v240, 16, v223
	v_and_b32_e32 v241, 0xffff0000, v223
	v_pk_mul_f32 v[114:115], v[114:115], v[144:145] op_sel_hi:[1,0]
	v_pk_fma_f32 v[114:115], v[114:115], v[178:179], v[240:241]
	v_pk_mul_f32 v[238:239], v[124:125], v[124:125]
	v_pk_fma_f32 v[238:239], v[126:127], v[126:127], v[238:239]
	v_pk_fma_f32 v[238:239], v[120:121], v[120:121], v[238:239]
	v_pk_fma_f32 v[238:239], v[122:123], v[122:123], v[238:239]
	v_pk_fma_f32 v[238:239], v[116:117], v[116:117], v[238:239]
	v_pk_fma_f32 v[238:239], v[118:119], v[118:119], v[238:239]
	v_pk_fma_f32 v[238:239], v[112:113], v[112:113], v[238:239]
	v_pk_fma_f32 v[238:239], v[114:115], v[114:115], v[238:239]
	v_add_f32_e32 v145, v238, v239
	v_cvt_pk_bf16_f32 v216, v124, v125
	v_cvt_pk_bf16_f32 v217, v126, v127
	v_cvt_pk_bf16_f32 v218, v120, v121
	v_cvt_pk_bf16_f32 v219, v122, v123
	v_cvt_pk_bf16_f32 v220, v116, v117
	v_cvt_pk_bf16_f32 v221, v118, v119
	v_cvt_pk_bf16_f32 v222, v112, v113
	v_cvt_pk_bf16_f32 v223, v114, v115
	s_nop 0
	global_store_dwordx4 v153, v[216:219], s[66:67]
	global_store_dwordx4 v153, v[220:223], s[66:67] offset:256
	v_lshlrev_b32_e32 v238, 16, v224
	v_and_b32_e32 v239, 0xffff0000, v224
	v_pk_mul_f32 v[108:109], v[108:109], v[154:155] op_sel_hi:[1,0]
	v_pk_fma_f32 v[108:109], v[108:109], v[156:157], v[238:239]
	v_lshlrev_b32_e32 v240, 16, v225
	v_and_b32_e32 v241, 0xffff0000, v225
	v_pk_mul_f32 v[110:111], v[110:111], v[154:155] op_sel_hi:[1,0]
	v_pk_fma_f32 v[110:111], v[110:111], v[158:159], v[240:241]
	v_lshlrev_b32_e32 v238, 16, v226
	v_and_b32_e32 v239, 0xffff0000, v226
	v_pk_mul_f32 v[104:105], v[104:105], v[154:155] op_sel_hi:[1,0]
	v_pk_fma_f32 v[104:105], v[104:105], v[160:161], v[238:239]
	v_lshlrev_b32_e32 v240, 16, v227
	v_and_b32_e32 v241, 0xffff0000, v227
	v_pk_mul_f32 v[106:107], v[106:107], v[154:155] op_sel_hi:[1,0]
	v_pk_fma_f32 v[106:107], v[106:107], v[162:163], v[240:241]
	v_lshlrev_b32_e32 v238, 16, v228
	v_and_b32_e32 v239, 0xffff0000, v228
	v_pk_mul_f32 v[100:101], v[100:101], v[154:155] op_sel_hi:[1,0]
	v_pk_fma_f32 v[100:101], v[100:101], v[172:173], v[238:239]
	v_lshlrev_b32_e32 v240, 16, v229
	v_and_b32_e32 v241, 0xffff0000, v229
	v_pk_mul_f32 v[102:103], v[102:103], v[154:155] op_sel_hi:[1,0]
	v_pk_fma_f32 v[102:103], v[102:103], v[174:175], v[240:241]
	v_lshlrev_b32_e32 v238, 16, v230
	v_and_b32_e32 v239, 0xffff0000, v230
	v_pk_mul_f32 v[96:97], v[96:97], v[154:155] op_sel_hi:[1,0]
	v_pk_fma_f32 v[96:97], v[96:97], v[176:177], v[238:239]
	v_lshlrev_b32_e32 v240, 16, v231
	v_and_b32_e32 v241, 0xffff0000, v231
	v_pk_mul_f32 v[98:99], v[98:99], v[154:155] op_sel_hi:[1,0]
	v_pk_fma_f32 v[98:99], v[98:99], v[178:179], v[240:241]
	v_pk_mul_f32 v[238:239], v[108:109], v[108:109]
	v_pk_fma_f32 v[238:239], v[110:111], v[110:111], v[238:239]
	v_pk_fma_f32 v[238:239], v[104:105], v[104:105], v[238:239]
	v_pk_fma_f32 v[238:239], v[106:107], v[106:107], v[238:239]
	v_pk_fma_f32 v[238:239], v[100:101], v[100:101], v[238:239]
	v_pk_fma_f32 v[238:239], v[102:103], v[102:103], v[238:239]
	v_pk_fma_f32 v[238:239], v[96:97], v[96:97], v[238:239]
	v_pk_fma_f32 v[238:239], v[98:99], v[98:99], v[238:239]
	v_add_f32_e32 v155, v238, v239
	v_cvt_pk_bf16_f32 v224, v108, v109
	v_cvt_pk_bf16_f32 v225, v110, v111
	v_cvt_pk_bf16_f32 v226, v104, v105
	v_cvt_pk_bf16_f32 v227, v106, v107
	v_cvt_pk_bf16_f32 v228, v100, v101
	v_cvt_pk_bf16_f32 v229, v102, v103
	v_cvt_pk_bf16_f32 v230, v96, v97
	v_cvt_pk_bf16_f32 v231, v98, v99
	v_add_u32_e32 v240, 0x8000, v153
	s_nop 0
	global_store_dwordx4 v240, v[224:227], s[66:67]
	global_store_dwordx4 v240, v[228:231], s[66:67] offset:256
	s_nop 1
	v_add_u32_e32 v240, 0x50000, v153
	global_load_dwordx4 v[216:219], v240, s[66:67]
	global_load_dwordx4 v[220:223], v240, s[66:67] offset:256
	v_add_u32_e32 v240, 0x58000, v153
	global_load_dwordx4 v[224:227], v240, s[66:67]
	global_load_dwordx4 v[228:231], v240, s[66:67] offset:256
	s_waitcnt vmcnt(14)
	v_lshlrev_b32_e32 v238, 16, v180
	v_and_b32_e32 v239, 0xffff0000, v180
	v_pk_mul_f32 v[92:93], v[92:93], v[164:165] op_sel_hi:[1,0]
	v_pk_fma_f32 v[92:93], v[92:93], v[156:157], v[238:239]
	v_lshlrev_b32_e32 v240, 16, v181
	v_and_b32_e32 v241, 0xffff0000, v181
	v_pk_mul_f32 v[94:95], v[94:95], v[164:165] op_sel_hi:[1,0]
	v_pk_fma_f32 v[94:95], v[94:95], v[158:159], v[240:241]
	v_lshlrev_b32_e32 v238, 16, v182
	v_and_b32_e32 v239, 0xffff0000, v182
	v_pk_mul_f32 v[88:89], v[88:89], v[164:165] op_sel_hi:[1,0]
	v_pk_fma_f32 v[88:89], v[88:89], v[160:161], v[238:239]
	v_lshlrev_b32_e32 v240, 16, v183
	v_and_b32_e32 v241, 0xffff0000, v183
	v_pk_mul_f32 v[90:91], v[90:91], v[164:165] op_sel_hi:[1,0]
	v_pk_fma_f32 v[90:91], v[90:91], v[162:163], v[240:241]
	v_lshlrev_b32_e32 v238, 16, v184
	v_and_b32_e32 v239, 0xffff0000, v184
	v_pk_mul_f32 v[84:85], v[84:85], v[164:165] op_sel_hi:[1,0]
	v_pk_fma_f32 v[84:85], v[84:85], v[172:173], v[238:239]
	v_lshlrev_b32_e32 v240, 16, v185
	v_and_b32_e32 v241, 0xffff0000, v185
	v_pk_mul_f32 v[86:87], v[86:87], v[164:165] op_sel_hi:[1,0]
	v_pk_fma_f32 v[86:87], v[86:87], v[174:175], v[240:241]
	v_lshlrev_b32_e32 v238, 16, v186
	v_and_b32_e32 v239, 0xffff0000, v186
	v_pk_mul_f32 v[80:81], v[80:81], v[164:165] op_sel_hi:[1,0]
	v_pk_fma_f32 v[80:81], v[80:81], v[176:177], v[238:239]
	v_lshlrev_b32_e32 v240, 16, v187
	v_and_b32_e32 v241, 0xffff0000, v187
	v_pk_mul_f32 v[82:83], v[82:83], v[164:165] op_sel_hi:[1,0]
	v_pk_fma_f32 v[82:83], v[82:83], v[178:179], v[240:241]
	v_pk_mul_f32 v[238:239], v[92:93], v[92:93]
	v_pk_fma_f32 v[238:239], v[94:95], v[94:95], v[238:239]
	v_pk_fma_f32 v[238:239], v[88:89], v[88:89], v[238:239]
	v_pk_fma_f32 v[238:239], v[90:91], v[90:91], v[238:239]
	v_pk_fma_f32 v[238:239], v[84:85], v[84:85], v[238:239]
	v_pk_fma_f32 v[238:239], v[86:87], v[86:87], v[238:239]
	v_pk_fma_f32 v[238:239], v[80:81], v[80:81], v[238:239]
	v_pk_fma_f32 v[238:239], v[82:83], v[82:83], v[238:239]
	v_add_f32_e32 v165, v238, v239
	v_cvt_pk_bf16_f32 v180, v92, v93
	v_cvt_pk_bf16_f32 v181, v94, v95
	v_cvt_pk_bf16_f32 v182, v88, v89
	v_cvt_pk_bf16_f32 v183, v90, v91
	v_cvt_pk_bf16_f32 v184, v84, v85
	v_cvt_pk_bf16_f32 v185, v86, v87
	v_cvt_pk_bf16_f32 v186, v80, v81
	v_cvt_pk_bf16_f32 v187, v82, v83
	v_add_u32_e32 v240, 0x10000, v153
	s_nop 0
	global_store_dwordx4 v240, v[180:183], s[66:67]
	global_store_dwordx4 v240, v[184:187], s[66:67] offset:256
	s_waitcnt vmcnt(14)
; __device__ __forceinline__ float bf_lo(unsigned w) { return __uint_as_float(w << 16); }
; __device__ __forceinline__ float bf_hi(unsigned w) { return __uint_as_float(w & 0xffff0000u); }
; __device__ __forceinline__ unsigned pk2(float lo, float hi) { bf16x2_t r = __builtin_convertvector((f32x2_t){lo, hi}, bf16x2_t); return __builtin_bit_cast(unsigned, r); }
; template <bool SRC_F32, bool FINAL, int R> __device__ __forceinline__ void ew_compute(const EwSet<SRC_F32, R>& S, int rb, const f32x4 (&g)[4], bf16* hb_out, float* out32, float scale, float* rs_out, int lane) {
;     ...
; #pragma unroll
;         for (int j = 0; j < 4; ++j) {
;             f32x4 h;
;             if constexpr (SRC_F32) h = S.h32[i][j];
;             else { const v2u hw = S.hb[i][j]; h.x = bf_lo(hw.x); h.y = bf_hi(hw.x); h.z = bf_lo(hw.y); h.w = bf_hi(hw.y); }
;             const v2u fw = S.fw[i][j];
;             f32x4 v; v.x = h.x + bf_lo(fw.x) * rs * g[j].x; v.y = h.y + bf_hi(fw.x) * rs * g[j].y; v.z = h.z + bf_lo(fw.y) * rs * g[j].z; v.w = h.w + bf_hi(fw.y) * rs * g[j].w;
;             if (FINAL) __builtin_nontemporal_store(v, (f32x4*)(out32 + (size_t)(rb + i) * D) + lane + 64 * j);
;             else { v2u o; o.x = pk2(v.x, v.y); o.y = pk2(v.z, v.w); ((v2u*)(hb_out + (size_t)(rb + i) * D) + lane)[64 * j] = o; s2 += (v.x * v.x + v.y * v.y) + (v.z * v.z + v.w * v.w); }
;         }
	v_lshlrev_b32_e32 v238, 16, v188
	v_and_b32_e32 v239, 0xffff0000, v188
	v_pk_mul_f32 v[76:77], v[76:77], v[170:171] op_sel_hi:[1,0]
	v_pk_fma_f32 v[76:77], v[76:77], v[156:157], v[238:239]
	v_lshlrev_b32_e32 v240, 16, v189
	v_and_b32_e32 v241, 0xffff0000, v189
	v_pk_mul_f32 v[78:79], v[78:79], v[170:171] op_sel_hi:[1,0]
	v_pk_fma_f32 v[78:79], v[78:79], v[158:159], v[240:241]
	v_lshlrev_b32_e32 v238, 16, v190
	v_and_b32_e32 v239, 0xffff0000, v190
	v_pk_mul_f32 v[72:73], v[72:73], v[170:171] op_sel_hi:[1,0]
	v_pk_fma_f32 v[72:73], v[72:73], v[160:161], v[238:239]
	v_lshlrev_b32_e32 v240, 16, v191
	v_and_b32_e32 v241, 0xffff0000, v191
	v_pk_mul_f32 v[74:75], v[74:75], v[170:171] op_sel_hi:[1,0]
	v_pk_fma_f32 v[74:75], v[74:75], v[162:163], v[240:241]
	v_lshlrev_b32_e32 v238, 16, v196
	v_and_b32_e32 v239, 0xffff0000, v196
	v_pk_mul_f32 v[68:69], v[68:69], v[170:171] op_sel_hi:[1,0]
	v_pk_fma_f32 v[68:69], v[68:69], v[172:173], v[238:239]
	v_lshlrev_b32_e32 v240, 16, v197
	v_and_b32_e32 v241, 0xffff0000, v197
	v_pk_mul_f32 v[70:71], v[70:71], v[170:171] op_sel_hi:[1,0]
	v_pk_fma_f32 v[70:71], v[70:71], v[174:175], v[240:241]
	v_lshlrev_b32_e32 v238, 16, v198
	v_and_b32_e32 v239, 0xffff0000, v198
	v_pk_mul_f32 v[64:65], v[64:65], v[170:171] op_sel_hi:[1,0]
	v_pk_fma_f32 v[64:65], v[64:65], v[176:177], v[238:239]
	v_lshlrev_b32_e32 v240, 16, v199
	v_and_b32_e32 v241, 0xffff0000, v199
	v_pk_mul_f32 v[66:67], v[66:67], v[170:171] op_sel_hi:[1,0]
	v_pk_fma_f32 v[66:67], v[66:67], v[178:179], v[240:241]
	v_pk_mul_f32 v[238:239], v[76:77], v[76:77]
	v_pk_fma_f32 v[238:239], v[78:79], v[78:79], v[238:239]
	v_pk_fma_f32 v[238:239], v[72:73], v[72:73], v[238:239]
	v_pk_fma_f32 v[238:239], v[74:75], v[74:75], v[238:239]
	v_pk_fma_f32 v[238:239], v[68:69], v[68:69], v[238:239]
	v_pk_fma_f32 v[238:239], v[70:71], v[70:71], v[238:239]
	v_pk_fma_f32 v[238:239], v[64:65], v[64:65], v[238:239]
	v_pk_fma_f32 v[238:239], v[66:67], v[66:67], v[238:239]
	v_add_f32_e32 v171, v238, v239
	v_cvt_pk_bf16_f32 v188, v76, v77
	v_cvt_pk_bf16_f32 v189, v78, v79
	v_cvt_pk_bf16_f32 v190, v72, v73
	v_cvt_pk_bf16_f32 v191, v74, v75
	v_cvt_pk_bf16_f32 v196, v68, v69
	v_cvt_pk_bf16_f32 v197, v70, v71
	v_cvt_pk_bf16_f32 v198, v64, v65
	v_cvt_pk_bf16_f32 v199, v66, v67
	v_add_u32_e32 v240, 0x18000, v153
	s_nop 0
	global_store_dwordx4 v240, v[188:191], s[66:67]
	global_store_dwordx4 v240, v[196:199], s[66:67] offset:256
	s_waitcnt vmcnt(14)
	v_lshlrev_b32_e32 v238, 16, v200
	v_and_b32_e32 v239, 0xffff0000, v200
	v_pk_mul_f32 v[60:61], v[60:61], v[192:193] op_sel_hi:[1,0]
	v_pk_fma_f32 v[60:61], v[60:61], v[156:157], v[238:239]
	v_lshlrev_b32_e32 v240, 16, v201
	v_and_b32_e32 v241, 0xffff0000, v201
	v_pk_mul_f32 v[62:63], v[62:63], v[192:193] op_sel_hi:[1,0]
	v_pk_fma_f32 v[62:63], v[62:63], v[158:159], v[240:241]
	v_lshlrev_b32_e32 v238, 16, v202
	v_and_b32_e32 v239, 0xffff0000, v202
	v_pk_mul_f32 v[56:57], v[56:57], v[192:193] op_sel_hi:[1,0]
	v_pk_fma_f32 v[56:57], v[56:57], v[160:161], v[238:239]
	v_lshlrev_b32_e32 v240, 16, v203
	v_and_b32_e32 v241, 0xffff0000, v203
	v_pk_mul_f32 v[58:59], v[58:59], v[192:193] op_sel_hi:[1,0]
	v_pk_fma_f32 v[58:59], v[58:59], v[162:163], v[240:241]
	v_lshlrev_b32_e32 v238, 16, v204
	v_and_b32_e32 v239, 0xffff0000, v204
	v_pk_mul_f32 v[52:53], v[52:53], v[192:193] op_sel_hi:[1,0]
	v_pk_fma_f32 v[52:53], v[52:53], v[172:173], v[238:239]
	v_lshlrev_b32_e32 v240, 16, v205
	v_and_b32_e32 v241, 0xffff0000, v205
	v_pk_mul_f32 v[54:55], v[54:55], v[192:193] op_sel_hi:[1,0]
	v_pk_fma_f32 v[54:55], v[54:55], v[174:175], v[240:241]
	v_lshlrev_b32_e32 v238, 16, v206
	v_and_b32_e32 v239, 0xffff0000, v206
	v_pk_mul_f32 v[48:49], v[48:49], v[192:193] op_sel_hi:[1,0]
	v_pk_fma_f32 v[48:49], v[48:49], v[176:177], v[238:239]
	v_lshlrev_b32_e32 v240, 16, v207
	v_and_b32_e32 v241, 0xffff0000, v207
	v_pk_mul_f32 v[50:51], v[50:51], v[192:193] op_sel_hi:[1,0]
	v_pk_fma_f32 v[50:51], v[50:51], v[178:179], v[240:241]
	v_pk_mul_f32 v[238:239], v[60:61], v[60:61]
	v_pk_fma_f32 v[238:239], v[62:63], v[62:63], v[238:239]
	v_pk_fma_f32 v[238:239], v[56:57], v[56:57], v[238:239]
	v_pk_fma_f32 v[238:239], v[58:59], v[58:59], v[238:239]
	v_pk_fma_f32 v[238:239], v[52:53], v[52:53], v[238:239]
	v_pk_fma_f32 v[238:239], v[54:55], v[54:55], v[238:239]
	v_pk_fma_f32 v[238:239], v[48:49], v[48:49], v[238:239]
	v_pk_fma_f32 v[238:239], v[50:51], v[50:51], v[238:239]
	v_add_f32_e32 v193, v238, v239
	v_cvt_pk_bf16_f32 v200, v60, v61
	v_cvt_pk_bf16_f32 v201, v62, v63
	v_cvt_pk_bf16_f32 v202, v56, v57
	v_cvt_pk_bf16_f32 v203, v58, v59
	v_cvt_pk_bf16_f32 v204, v52, v53
	v_cvt_pk_bf16_f32 v205, v54, v55
	v_cvt_pk_bf16_f32 v206, v48, v49
	v_cvt_pk_bf16_f32 v207, v50, v51
	v_add_u32_e32 v240, 0x40000, v153
	s_nop 0
	global_store_dwordx4 v240, v[200:203], s[66:67]
	global_store_dwordx4 v240, v[204:207], s[66:67] offset:256
	s_waitcnt vmcnt(14)
; __device__ __forceinline__ float bf_lo(unsigned w) { return __uint_as_float(w << 16); }
; __device__ __forceinline__ float bf_hi(unsigned w) { return __uint_as_float(w & 0xffff0000u); }
; __device__ __forceinline__ unsigned pk2(float lo, float hi) { bf16x2_t r = __builtin_convertvector((f32x2_t){lo, hi}, bf16x2_t); return __builtin_bit_cast(unsigned, r); }
; template <bool SRC_F32, bool FINAL, int R> __device__ __forceinline__ void ew_compute(const EwSet<SRC_F32, R>& S, int rb, const f32x4 (&g)[4], bf16* hb_out, float* out32, float scale, float* rs_out, int lane) {
;     ...
; #pragma unroll
;         for (int j = 0; j < 4; ++j) {
;             f32x4 h;
;             if constexpr (SRC_F32) h = S.h32[i][j];
;             else { const v2u hw = S.hb[i][j]; h.x = bf_lo(hw.x); h.y = bf_hi(hw.x); h.z = bf_lo(hw.y); h.w = bf_hi(hw.y); }
;             const v2u fw = S.fw[i][j];
;             f32x4 v; v.x = h.x + bf_lo(fw.x) * rs * g[j].x; v.y = h.y + bf_hi(fw.x) * rs * g[j].y; v.z = h.z + bf_lo(fw.y) * rs * g[j].z; v.w = h.w + bf_hi(fw.y) * rs * g[j].w;
;             if (FINAL) __builtin_nontemporal_store(v, (f32x4*)(out32 + (size_t)(rb + i) * D) + lane + 64 * j);
;             else { v2u o; o.x = pk2(v.x, v.y); o.y = pk2(v.z, v.w); ((v2u*)(hb_out + (size_t)(rb + i) * D) + lane)[64 * j] = o; s2 += (v.x * v.x + v.y * v.y) + (v.z * v.z + v.w * v.w); }
;         }
	v_lshlrev_b32_e32 v238, 16, v208
	v_and_b32_e32 v239, 0xffff0000, v208
	v_pk_mul_f32 v[44:45], v[44:45], v[232:233] op_sel_hi:[1,0]
	v_pk_fma_f32 v[44:45], v[44:45], v[156:157], v[238:239]
	v_lshlrev_b32_e32 v240, 16, v209
	v_and_b32_e32 v241, 0xffff0000, v209
	v_pk_mul_f32 v[46:47], v[46:47], v[232:233] op_sel_hi:[1,0]
	v_pk_fma_f32 v[46:47], v[46:47], v[158:159], v[240:241]
	v_lshlrev_b32_e32 v238, 16, v210
	v_and_b32_e32 v239, 0xffff0000, v210
	v_pk_mul_f32 v[40:41], v[40:41], v[232:233] op_sel_hi:[1,0]
	v_pk_fma_f32 v[40:41], v[40:41], v[160:161], v[238:239]
	v_lshlrev_b32_e32 v240, 16, v211
	v_and_b32_e32 v241, 0xffff0000, v211
	v_pk_mul_f32 v[42:43], v[42:43], v[232:233] op_sel_hi:[1,0]
	v_pk_fma_f32 v[42:43], v[42:43], v[162:163], v[240:241]
	v_lshlrev_b32_e32 v238, 16, v212
	v_and_b32_e32 v239, 0xffff0000, v212
	v_pk_mul_f32 v[36:37], v[36:37], v[232:233] op_sel_hi:[1,0]
	v_pk_fma_f32 v[36:37], v[36:37], v[172:173], v[238:239]
	v_lshlrev_b32_e32 v240, 16, v213
	v_and_b32_e32 v241, 0xffff0000, v213
	v_pk_mul_f32 v[38:39], v[38:39], v[232:233] op_sel_hi:[1,0]
	v_pk_fma_f32 v[38:39], v[38:39], v[174:175], v[240:241]
	v_lshlrev_b32_e32 v238, 16, v214
	v_and_b32_e32 v239, 0xffff0000, v214
	v_pk_mul_f32 v[32:33], v[32:33], v[232:233] op_sel_hi:[1,0]
	v_pk_fma_f32 v[32:33], v[32:33], v[176:177], v[238:239]
	v_lshlrev_b32_e32 v240, 16, v215
	v_and_b32_e32 v241, 0xffff0000, v215
	v_pk_mul_f32 v[34:35], v[34:35], v[232:233] op_sel_hi:[1,0]
	v_pk_fma_f32 v[34:35], v[34:35], v[178:179], v[240:241]
	v_pk_mul_f32 v[238:239], v[44:45], v[44:45]
	v_pk_fma_f32 v[238:239], v[46:47], v[46:47], v[238:239]
	v_pk_fma_f32 v[238:239], v[40:41], v[40:41], v[238:239]
	v_pk_fma_f32 v[238:239], v[42:43], v[42:43], v[238:239]
	v_pk_fma_f32 v[238:239], v[36:37], v[36:37], v[238:239]
	v_pk_fma_f32 v[238:239], v[38:39], v[38:39], v[238:239]
	v_pk_fma_f32 v[238:239], v[32:33], v[32:33], v[238:239]
	v_pk_fma_f32 v[238:239], v[34:35], v[34:35], v[238:239]
	v_add_f32_e32 v233, v238, v239
	v_cvt_pk_bf16_f32 v208, v44, v45
	v_cvt_pk_bf16_f32 v209, v46, v47
	v_cvt_pk_bf16_f32 v210, v40, v41
	v_cvt_pk_bf16_f32 v211, v42, v43
	v_cvt_pk_bf16_f32 v212, v36, v37
	v_cvt_pk_bf16_f32 v213, v38, v39
	v_cvt_pk_bf16_f32 v214, v32, v33
	v_cvt_pk_bf16_f32 v215, v34, v35
	v_add_u32_e32 v240, 0x48000, v153
	s_nop 0
	global_store_dwordx4 v240, v[208:211], s[66:67]
	global_store_dwordx4 v240, v[212:215], s[66:67] offset:256
	s_waitcnt vmcnt(10)
	v_lshlrev_b32_e32 v238, 16, v216
	v_and_b32_e32 v239, 0xffff0000, v216
	v_pk_mul_f32 v[28:29], v[28:29], v[234:235] op_sel_hi:[1,0]
	v_pk_fma_f32 v[28:29], v[28:29], v[156:157], v[238:239]
	v_lshlrev_b32_e32 v240, 16, v217
	v_and_b32_e32 v241, 0xffff0000, v217
	v_pk_mul_f32 v[30:31], v[30:31], v[234:235] op_sel_hi:[1,0]
	v_pk_fma_f32 v[30:31], v[30:31], v[158:159], v[240:241]
	v_lshlrev_b32_e32 v238, 16, v218
	v_and_b32_e32 v239, 0xffff0000, v218
	v_pk_mul_f32 v[24:25], v[24:25], v[234:235] op_sel_hi:[1,0]
	v_pk_fma_f32 v[24:25], v[24:25], v[160:161], v[238:239]
	v_lshlrev_b32_e32 v240, 16, v219
	v_and_b32_e32 v241, 0xffff0000, v219
	v_pk_mul_f32 v[26:27], v[26:27], v[234:235] op_sel_hi:[1,0]
	v_pk_fma_f32 v[26:27], v[26:27], v[162:163], v[240:241]
	v_lshlrev_b32_e32 v238, 16, v220
	v_and_b32_e32 v239, 0xffff0000, v220
	v_pk_mul_f32 v[20:21], v[20:21], v[234:235] op_sel_hi:[1,0]
	v_pk_fma_f32 v[20:21], v[20:21], v[172:173], v[238:239]
	v_lshlrev_b32_e32 v240, 16, v221
	v_and_b32_e32 v241, 0xffff0000, v221
	v_pk_mul_f32 v[22:23], v[22:23], v[234:235] op_sel_hi:[1,0]
	v_pk_fma_f32 v[22:23], v[22:23], v[174:175], v[240:241]
	v_lshlrev_b32_e32 v238, 16, v222
	v_and_b32_e32 v239, 0xffff0000, v222
	v_pk_mul_f32 v[16:17], v[16:17], v[234:235] op_sel_hi:[1,0]
	v_pk_fma_f32 v[16:17], v[16:17], v[176:177], v[238:239]
	v_lshlrev_b32_e32 v240, 16, v223
	v_and_b32_e32 v241, 0xffff0000, v223
	v_pk_mul_f32 v[18:19], v[18:19], v[234:235] op_sel_hi:[1,0]
	v_pk_fma_f32 v[18:19], v[18:19], v[178:179], v[240:241]
	v_pk_mul_f32 v[238:239], v[28:29], v[28:29]
	v_pk_fma_f32 v[238:239], v[30:31], v[30:31], v[238:239]
	v_pk_fma_f32 v[238:239], v[24:25], v[24:25], v[238:239]
	v_pk_fma_f32 v[238:239], v[26:27], v[26:27], v[238:239]
	v_pk_fma_f32 v[238:239], v[20:21], v[20:21], v[238:239]
	v_pk_fma_f32 v[238:239], v[22:23], v[22:23], v[238:239]
	v_pk_fma_f32 v[238:239], v[16:17], v[16:17], v[238:239]
	v_pk_fma_f32 v[238:239], v[18:19], v[18:19], v[238:239]
	v_add_f32_e32 v235, v238, v239
	v_cvt_pk_bf16_f32 v216, v28, v29
	v_cvt_pk_bf16_f32 v217, v30, v31
	v_cvt_pk_bf16_f32 v218, v24, v25
	v_cvt_pk_bf16_f32 v219, v26, v27
	v_cvt_pk_bf16_f32 v220, v20, v21
	v_cvt_pk_bf16_f32 v221, v22, v23
	v_cvt_pk_bf16_f32 v222, v16, v17
	v_cvt_pk_bf16_f32 v223, v18, v19
	v_add_u32_e32 v240, 0x50000, v153
	s_nop 0
	global_store_dwordx4 v240, v[216:219], s[66:67]
	global_store_dwordx4 v240, v[220:223], s[66:67] offset:256
	s_waitcnt vmcnt(10)
; __device__ __forceinline__ float bf_lo(unsigned w) { return __uint_as_float(w << 16); }
; __device__ __forceinline__ float bf_hi(unsigned w) { return __uint_as_float(w & 0xffff0000u); }
; __device__ __forceinline__ unsigned pk2(float lo, float hi) { bf16x2_t r = __builtin_convertvector((f32x2_t){lo, hi}, bf16x2_t); return __builtin_bit_cast(unsigned, r); }
;     __device__ __forceinline__ void operator()(const pg8::f32x4 (&acc)[2][2][4][2], const pg8::Unit& u, int wr, int wc, int fr, int fq) const {
;     ...
;                     if (PART) {
; #pragma unroll
;                         for (int j = 0; j < 8; ++j) s += r[j] * r[j];
;                     }
;                     v4u w; w.x = pk2(r[0], r[1]); w.y = pk2(r[2], r[3]); w.z = pk2(r[4], r[5]); w.w = pk2(r[6], r[7]);
;                     st16_wt(O + off + bj * 128, w);
;                 }
;                 if (PART) { s += __shfl_xor(s, 16); s += __shfl_xor(s, 32); st4_wt(part + (size_t)row * 16 + u.pn * 4 + wc, s); }
; template <bool SRC_F32, bool FINAL, int R> __device__ __forceinline__ void ew_compute(const EwSet<SRC_F32, R>& S, int rb, const f32x4 (&g)[4], bf16* hb_out, float* out32, float scale, float* rs_out, int lane) {
;     ...
; #pragma unroll
;         for (int j = 0; j < 4; ++j) {
;             f32x4 h;
;             if constexpr (SRC_F32) h = S.h32[i][j];
;             else { const v2u hw = S.hb[i][j]; h.x = bf_lo(hw.x); h.y = bf_hi(hw.x); h.z = bf_lo(hw.y); h.w = bf_hi(hw.y); }
;             const v2u fw = S.fw[i][j];
;             f32x4 v; v.x = h.x + bf_lo(fw.x) * rs * g[j].x; v.y = h.y + bf_hi(fw.x) * rs * g[j].y; v.z = h.z + bf_lo(fw.y) * rs * g[j].z; v.w = h.w + bf_hi(fw.y) * rs * g[j].w;
;             if (FINAL) __builtin_nontemporal_store(v, (f32x4*)(out32 + (size_t)(rb + i) * D) + lane + 64 * j);
;             else { v2u o; o.x = pk2(v.x, v.y); o.y = pk2(v.z, v.w); ((v2u*)(hb_out + (size_t)(rb + i) * D) + lane)[64 * j] = o; s2 += (v.x * v.x + v.y * v.y) + (v.z * v.z + v.w * v.w); }
;         }
;         if (!FINAL) { const float tot = wave_sum(s2); if (lane == 0) rs_out[rb + i] = 1.0f / sqrtf(tot * (1.f / D) + EPS); }
	v_lshlrev_b32_e32 v238, 16, v224
	v_and_b32_e32 v239, 0xffff0000, v224
	v_pk_mul_f32 v[12:13], v[12:13], v[236:237] op_sel_hi:[1,0]
	v_pk_fma_f32 v[12:13], v[12:13], v[156:157], v[238:239]
	v_lshlrev_b32_e32 v240, 16, v225
	v_and_b32_e32 v241, 0xffff0000, v225
	v_pk_mul_f32 v[14:15], v[14:15], v[236:237] op_sel_hi:[1,0]
	v_pk_fma_f32 v[14:15], v[14:15], v[158:159], v[240:241]
	v_lshlrev_b32_e32 v238, 16, v226
	v_and_b32_e32 v239, 0xffff0000, v226
	v_pk_mul_f32 v[8:9], v[8:9], v[236:237] op_sel_hi:[1,0]
	v_pk_fma_f32 v[8:9], v[8:9], v[160:161], v[238:239]
	v_lshlrev_b32_e32 v240, 16, v227
	v_and_b32_e32 v241, 0xffff0000, v227
	v_pk_mul_f32 v[10:11], v[10:11], v[236:237] op_sel_hi:[1,0]
	v_pk_fma_f32 v[10:11], v[10:11], v[162:163], v[240:241]
	v_lshlrev_b32_e32 v238, 16, v228
	v_and_b32_e32 v239, 0xffff0000, v228
	v_pk_mul_f32 v[4:5], v[4:5], v[236:237] op_sel_hi:[1,0]
	v_pk_fma_f32 v[4:5], v[4:5], v[172:173], v[238:239]
	v_lshlrev_b32_e32 v240, 16, v229
	v_and_b32_e32 v241, 0xffff0000, v229
	v_pk_mul_f32 v[6:7], v[6:7], v[236:237] op_sel_hi:[1,0]
	v_pk_fma_f32 v[6:7], v[6:7], v[174:175], v[240:241]
	v_lshlrev_b32_e32 v238, 16, v230
	v_and_b32_e32 v239, 0xffff0000, v230
	v_pk_mul_f32 v[0:1], v[0:1], v[236:237] op_sel_hi:[1,0]
	v_pk_fma_f32 v[0:1], v[0:1], v[176:177], v[238:239]
	v_lshlrev_b32_e32 v240, 16, v231
	v_and_b32_e32 v241, 0xffff0000, v231
	v_pk_mul_f32 v[2:3], v[2:3], v[236:237] op_sel_hi:[1,0]
	v_pk_fma_f32 v[2:3], v[2:3], v[178:179], v[240:241]
	v_pk_mul_f32 v[238:239], v[12:13], v[12:13]
	v_pk_fma_f32 v[238:239], v[14:15], v[14:15], v[238:239]
	v_pk_fma_f32 v[238:239], v[8:9], v[8:9], v[238:239]
	v_pk_fma_f32 v[238:239], v[10:11], v[10:11], v[238:239]
	v_pk_fma_f32 v[238:239], v[4:5], v[4:5], v[238:239]
	v_pk_fma_f32 v[238:239], v[6:7], v[6:7], v[238:239]
	v_pk_fma_f32 v[238:239], v[0:1], v[0:1], v[238:239]
	v_pk_fma_f32 v[238:239], v[2:3], v[2:3], v[238:239]
	v_add_f32_e32 v237, v238, v239
	v_cvt_pk_bf16_f32 v224, v12, v13
	v_cvt_pk_bf16_f32 v225, v14, v15
	v_cvt_pk_bf16_f32 v226, v8, v9
	v_cvt_pk_bf16_f32 v227, v10, v11
	v_cvt_pk_bf16_f32 v228, v4, v5
	v_cvt_pk_bf16_f32 v229, v6, v7
	v_cvt_pk_bf16_f32 v230, v0, v1
	v_cvt_pk_bf16_f32 v231, v2, v3
	v_add_u32_e32 v240, 0x58000, v153
	s_nop 0
	global_store_dwordx4 v240, v[224:227], s[66:67]
	global_store_dwordx4 v240, v[228:231], s[66:67] offset:256
	s_nop 1
	ds_bpermute_b32 v156, v194, v145
	ds_bpermute_b32 v157, v194, v155
	ds_bpermute_b32 v158, v194, v165
	ds_bpermute_b32 v159, v194, v171
	ds_bpermute_b32 v160, v194, v193
	ds_bpermute_b32 v161, v194, v233
	ds_bpermute_b32 v162, v194, v235
	ds_bpermute_b32 v163, v194, v237
	s_waitcnt lgkmcnt(0)
	v_add_f32_e32 v145, v145, v156
	v_add_f32_e32 v155, v155, v157
	v_add_f32_e32 v165, v165, v158
	v_add_f32_e32 v171, v171, v159
	v_add_f32_e32 v193, v193, v160
	v_add_f32_e32 v233, v233, v161
	v_add_f32_e32 v235, v235, v162
	v_add_f32_e32 v237, v237, v163
	s_nop 1
	ds_bpermute_b32 v156, v242, v145
	ds_bpermute_b32 v157, v242, v155
	ds_bpermute_b32 v158, v242, v165
	ds_bpermute_b32 v159, v242, v171
	ds_bpermute_b32 v160, v242, v193
	ds_bpermute_b32 v161, v242, v233
	ds_bpermute_b32 v162, v242, v235
	ds_bpermute_b32 v163, v242, v237
	s_waitcnt lgkmcnt(0)
	v_add_f32_e32 v145, v145, v156
	v_add_f32_e32 v155, v155, v157
	v_add_f32_e32 v165, v165, v158
	v_add_f32_e32 v171, v171, v159
	v_add_f32_e32 v193, v193, v160
	v_add_f32_e32 v233, v233, v161
	v_add_f32_e32 v235, v235, v162
	v_add_f32_e32 v237, v237, v163
	global_store_dword v166, v145, s[78:79]
	v_add_u32_e32 v157, 0x400, v166
	global_store_dword v157, v155, s[78:79]
	v_add_u32_e32 v158, 0x800, v166
	global_store_dword v158, v165, s[78:79]
	v_add_u32_e32 v159, 0xc00, v166
	global_store_dword v159, v171, s[78:79]
	v_add_u32_e32 v160, 0x2000, v166
	global_store_dword v160, v193, s[78:79]
	v_add_u32_e32 v161, 0x2400, v166
	global_store_dword v161, v233, s[78:79]
	v_add_u32_e32 v162, 0x2800, v166
	global_store_dword v162, v235, s[78:79]
	v_add_u32_e32 v163, 0x2c00, v166
	global_store_dword v163, v237, s[78:79]
	s_and_b64 vcc, exec, s[0:1]
	s_mov_b64 s[0:1], -1
	s_cbranch_vccnz .LBB0_1144
	s_andn2_b64 vcc, exec, s[10:11]
	s_cbranch_vccnz .LBB0_1143
	s_barrier
	s_branch .LBB0_1143

; __device__ __forceinline__ unsigned xb_ld(unsigned* p)              { return __hip_atomic_load(p, __ATOMIC_RELAXED, __HIP_MEMORY_SCOPE_AGENT); }
; __device__ __forceinline__ unsigned xb_add(unsigned* p, unsigned v) { return __hip_atomic_fetch_add(p, v, __ATOMIC_RELAXED, __HIP_MEMORY_SCOPE_AGENT); }
; #define XB_SPIN(cond, bar) do { unsigned _sp = 0; while (cond) { __builtin_amdgcn_s_sleep(1); \
;     if ((++_sp & 255u) == 0u) { if (xb_ld(&(bar)[XB_TMO])) break; if (_sp > XB_SPIN_CAP) { atomicAdd(&(bar)[XB_TMO], 1u); break; } } } } while (0)
; __device__ __forceinline__ void xcd_barrier(const XcdBarrier& b) {
;     asm volatile("s_waitcnt vmcnt(0)" ::: "memory");
;     __syncthreads();
;     if (threadIdx.x == 0) {
;         unsigned* bar = b.bar;
;         __builtin_amdgcn_s_waitcnt(0);
;         unsigned nloc = b.st[0], nx = b.st[1];
;         if (nloc == 0u) { xcd_barrier_complete(bar, b.x, nloc, nx); b.st[0] = nloc; b.st[1] = nx; }
;         const unsigned old = xb_add(&bar[XB_XSUB(b.x)], 1u);
;         const unsigned gen = old / nloc;
;         if (old + 1u == (gen + 1u) * nloc) {
;             __builtin_amdgcn_fence(__ATOMIC_RELEASE, "agent");
;             asm volatile("s_waitcnt vmcnt(0)" ::: "memory");
;             const unsigned og = xb_add(&bar[XB_TOP], 1u);
;             const unsigned tg = og / nx;
;             if (og + 1u == (tg + 1u) * nx) xb_add(&bar[XB_TOPGEN], 1u);
;             else XB_SPIN(xb_ld(&bar[XB_TOPGEN]) == tg, bar);
;             __builtin_amdgcn_fence(__ATOMIC_ACQUIRE, "agent");
;             xb_add(&bar[XB_XGEN(b.x)], 1u);
;             asm volatile("s_waitcnt vmcnt(0)" ::: "memory");
;         } else {
;             XB_SPIN(xb_ld(&bar[XB_XGEN(b.x)]) == gen, bar);
;             __builtin_amdgcn_fence(__ATOMIC_ACQUIRE, "agent");
;             asm volatile("s_waitcnt vmcnt(0)" ::: "memory");
;         }
;     }
;     __syncthreads();
; }
.Ltb1309_frel:
.Ltb1309_done:
	s_or_b64 exec, exec, s[4:5]
	s_barrier
	s_mov_b32 s100, 32

; __device__ __forceinline__ float bf_lo(unsigned w) { return __uint_as_float(w << 16); }
; __device__ __forceinline__ float bf_hi(unsigned w) { return __uint_as_float(w & 0xffff0000u); }
;     __device__ __forceinline__ void operator()(const pg8::f32x4 (&acc)[2][2][4][2], const pg8::Unit& u, int wr, int wc, int fr, int fq) const {
;     ...
;         for (int ai = 0; ai < 2; ++ai) {
;             v4u gq[4][2], aq[4][2];
;             if (GATE) {
; #pragma unroll
;                 for (int m = 0; m < 4; ++m)
; #pragma unroll
;                     for (int bj = 0; bj < 2; ++bj) gq[m][bj] = *(const v4u*)(G + (size_t)(row0 + ai * 128 + m * 16) * D + col0 + bj * 128);
;             }
;             if (ADD) {
; #pragma unroll
;                 for (int m = 0; m < 4; ++m)
; #pragma unroll
;                     for (int bj = 0; bj < 2; ++bj) aq[m][bj] = *(const v4u*)(A2 + (size_t)(row0 + ai * 128 + m * 16) * D + col0 + bj * 128);
;             }
; #pragma unroll
;             for (int m = 0; m < 4; ++m) {
;                 const int row = row0 + ai * 128 + m * 16;
;                 const size_t off = (size_t)row * D + col0;
;                 float s = 0.f;
; #pragma unroll
;                 for (int bj = 0; bj < 2; ++bj) {
;                     float r[8];
; #pragma unroll
;                     for (int j = 0; j < 4; ++j) { r[j] = acc[ai][bj][m][0][j]; r[4 + j] = acc[ai][bj][m][1][j]; }
;                     if (RSCALE) { const float rv = rvs[ai][m];
; #pragma unroll
;                         for (int j = 0; j < 8; ++j) r[j] *= rv; }
;                     if (ACT == 1) {
; #pragma unroll
;                         for (int j = 0; j < 8; ++j) r[j] = sigmoid_fast(r[j]);
;                     }
;                     if (GATE) { const v4u g = gq[m][bj];
;                         r[0] *= bf_lo(g.x); r[1] *= bf_hi(g.x); r[2] *= bf_lo(g.y); r[3] *= bf_hi(g.y); r[4] *= bf_lo(g.z); r[5] *= bf_hi(g.z); r[6] *= bf_lo(g.w); r[7] *= bf_hi(g.w); }
;                     if (ADD) { const v4u g = aq[m][bj];
;                         r[0] += bf_lo(g.x); r[1] += bf_hi(g.x); r[2] += bf_lo(g.y); r[3] += bf_hi(g.y); r[4] += bf_lo(g.z); r[5] += bf_hi(g.z); r[6] += bf_lo(g.w); r[7] += bf_hi(g.w); }
;                     if (PART) {
; #pragma unroll
;                         for (int j = 0; j < 8; ++j) s += r[j] * r[j];
.LBB0_1392:
	s_waitcnt lgkmcnt(0)
	v_lshl_or_b32 v128, s58, 8, v172
	v_lshl_add_u32 v154, s57, 8, v170
	v_lshlrev_b32_e32 v156, 2, v128
	v_lshlrev_b32_e32 v129, 1, v128
	v_lshl_add_u32 v152, v154, 11, v129
	v_xor_b32_e32 v130, 16, v176
	v_lshlrev_b32_e32 v177, 2, v130
	v_xor_b32_e32 v130, 32, v176
	v_lshlrev_b32_e32 v155, 2, v130
	v_lshrrev_b32_e32 v130, 4, v176
	v_and_b32_e32 v130, 3, v130
	v_lshlrev_b32_e32 v157, 4, v130
	s_lshl_b32 s38, s58, 4
	s_add_u32 s38, s38, s14
	v_lshl_add_u32 v153, v154, 6, s38
	global_load_dwordx4 v[178:181], v152, s[16:17]
	global_load_dwordx4 v[182:185], v152, s[16:17] offset:256
	v_add_u32_e32 v159, 0x8000, v152
	global_load_dwordx4 v[186:189], v159, s[16:17]
	global_load_dwordx4 v[190:193], v159, s[16:17] offset:256
	v_add_u32_e32 v160, 0x10000, v152
	global_load_dwordx4 v[196:199], v160, s[16:17]
	global_load_dwordx4 v[200:203], v160, s[16:17] offset:256
	v_add_u32_e32 v161, 0x18000, v152
	global_load_dwordx4 v[204:207], v161, s[16:17]
	global_load_dwordx4 v[208:211], v161, s[16:17] offset:256
	v_add_u32_e32 v162, 0x40000, v152
	global_load_dwordx4 v[212:215], v162, s[16:17]
	global_load_dwordx4 v[216:219], v162, s[16:17] offset:256
	v_add_u32_e32 v163, 0x48000, v152
	global_load_dwordx4 v[220:223], v163, s[16:17]
	global_load_dwordx4 v[224:227], v163, s[16:17] offset:256
	v_add_u32_e32 v164, 0x50000, v152
	global_load_dwordx4 v[228:231], v164, s[16:17]
	global_load_dwordx4 v[232:235], v164, s[16:17] offset:256
	v_add_u32_e32 v165, 0x58000, v152
	global_load_dwordx4 v[236:239], v165, s[16:17]
	global_load_dwordx4 v[240:243], v165, s[16:17] offset:256
	s_waitcnt vmcnt(14)
	v_lshlrev_b32_e32 v248, 16, v178
	v_and_b32_e32 v249, 0xffff0000, v178
	v_pk_mul_f32 v[124:125], v[124:125], v[248:249]
	v_lshlrev_b32_e32 v250, 16, v179
	v_and_b32_e32 v251, 0xffff0000, v179
	v_pk_mul_f32 v[126:127], v[126:127], v[250:251]
	v_lshlrev_b32_e32 v252, 16, v180
	v_and_b32_e32 v253, 0xffff0000, v180
	v_pk_mul_f32 v[120:121], v[120:121], v[252:253]
	v_lshlrev_b32_e32 v248, 16, v181
	v_and_b32_e32 v249, 0xffff0000, v181
	v_pk_mul_f32 v[122:123], v[122:123], v[248:249]
	v_lshlrev_b32_e32 v250, 16, v182
	v_and_b32_e32 v251, 0xffff0000, v182
	v_pk_mul_f32 v[116:117], v[116:117], v[250:251]
	v_lshlrev_b32_e32 v252, 16, v183
	v_and_b32_e32 v253, 0xffff0000, v183
	v_pk_mul_f32 v[118:119], v[118:119], v[252:253]
	v_lshlrev_b32_e32 v248, 16, v184
	v_and_b32_e32 v249, 0xffff0000, v184
	v_pk_mul_f32 v[112:113], v[112:113], v[248:249]
	v_lshlrev_b32_e32 v250, 16, v185
	v_and_b32_e32 v251, 0xffff0000, v185
	v_pk_mul_f32 v[114:115], v[114:115], v[250:251]
	v_pk_mul_f32 v[244:245], v[124:125], v[124:125]
	v_pk_fma_f32 v[244:245], v[126:127], v[126:127], v[244:245]
	v_pk_fma_f32 v[244:245], v[120:121], v[120:121], v[244:245]
	v_pk_fma_f32 v[244:245], v[122:123], v[122:123], v[244:245]
	v_pk_fma_f32 v[244:245], v[116:117], v[116:117], v[244:245]
	v_pk_fma_f32 v[244:245], v[118:119], v[118:119], v[244:245]
	v_pk_fma_f32 v[244:245], v[112:113], v[112:113], v[244:245]
	v_pk_fma_f32 v[244:245], v[114:115], v[114:115], v[244:245]
	v_add_f32_e32 v128, v244, v245
	s_waitcnt vmcnt(12)
	v_lshlrev_b32_e32 v248, 16, v186
	v_and_b32_e32 v249, 0xffff0000, v186
	v_pk_mul_f32 v[108:109], v[108:109], v[248:249]
	v_lshlrev_b32_e32 v250, 16, v187
	v_and_b32_e32 v251, 0xffff0000, v187
	v_pk_mul_f32 v[110:111], v[110:111], v[250:251]
	v_lshlrev_b32_e32 v252, 16, v188
	v_and_b32_e32 v253, 0xffff0000, v188
	v_pk_mul_f32 v[104:105], v[104:105], v[252:253]
	v_lshlrev_b32_e32 v248, 16, v189
	v_and_b32_e32 v249, 0xffff0000, v189
	v_pk_mul_f32 v[106:107], v[106:107], v[248:249]
	v_lshlrev_b32_e32 v250, 16, v190
	v_and_b32_e32 v251, 0xffff0000, v190
	v_pk_mul_f32 v[100:101], v[100:101], v[250:251]
	v_lshlrev_b32_e32 v252, 16, v191
	v_and_b32_e32 v253, 0xffff0000, v191
	v_pk_mul_f32 v[102:103], v[102:103], v[252:253]
	v_lshlrev_b32_e32 v248, 16, v192
	v_and_b32_e32 v249, 0xffff0000, v192
	v_pk_mul_f32 v[96:97], v[96:97], v[248:249]
	v_lshlrev_b32_e32 v250, 16, v193
	v_and_b32_e32 v251, 0xffff0000, v193
	v_pk_mul_f32 v[98:99], v[98:99], v[250:251]
	v_pk_mul_f32 v[244:245], v[108:109], v[108:109]
	v_pk_fma_f32 v[244:245], v[110:111], v[110:111], v[244:245]
	v_pk_fma_f32 v[244:245], v[104:105], v[104:105], v[244:245]
	v_pk_fma_f32 v[244:245], v[106:107], v[106:107], v[244:245]
	v_pk_fma_f32 v[244:245], v[100:101], v[100:101], v[244:245]
	v_pk_fma_f32 v[244:245], v[102:103], v[102:103], v[244:245]
	v_pk_fma_f32 v[244:245], v[96:97], v[96:97], v[244:245]
	v_pk_fma_f32 v[244:245], v[98:99], v[98:99], v[244:245]
	v_add_f32_e32 v129, v244, v245
	s_waitcnt vmcnt(10)
	v_lshlrev_b32_e32 v248, 16, v196
	v_and_b32_e32 v249, 0xffff0000, v196
	v_pk_mul_f32 v[92:93], v[92:93], v[248:249]
	v_lshlrev_b32_e32 v250, 16, v197
	v_and_b32_e32 v251, 0xffff0000, v197
	v_pk_mul_f32 v[94:95], v[94:95], v[250:251]
	v_lshlrev_b32_e32 v252, 16, v198
	v_and_b32_e32 v253, 0xffff0000, v198
	v_pk_mul_f32 v[88:89], v[88:89], v[252:253]
	v_lshlrev_b32_e32 v248, 16, v199
	v_and_b32_e32 v249, 0xffff0000, v199
	v_pk_mul_f32 v[90:91], v[90:91], v[248:249]
	v_lshlrev_b32_e32 v250, 16, v200
	v_and_b32_e32 v251, 0xffff0000, v200
	v_pk_mul_f32 v[84:85], v[84:85], v[250:251]
	v_lshlrev_b32_e32 v252, 16, v201
	v_and_b32_e32 v253, 0xffff0000, v201
	v_pk_mul_f32 v[86:87], v[86:87], v[252:253]
	v_lshlrev_b32_e32 v248, 16, v202
	v_and_b32_e32 v249, 0xffff0000, v202
	v_pk_mul_f32 v[80:81], v[80:81], v[248:249]
	v_lshlrev_b32_e32 v250, 16, v203
	v_and_b32_e32 v251, 0xffff0000, v203
	v_pk_mul_f32 v[82:83], v[82:83], v[250:251]
	v_pk_mul_f32 v[244:245], v[92:93], v[92:93]
	v_pk_fma_f32 v[244:245], v[94:95], v[94:95], v[244:245]
	v_pk_fma_f32 v[244:245], v[88:89], v[88:89], v[244:245]
	v_pk_fma_f32 v[244:245], v[90:91], v[90:91], v[244:245]
	v_pk_fma_f32 v[244:245], v[84:85], v[84:85], v[244:245]
	v_pk_fma_f32 v[244:245], v[86:87], v[86:87], v[244:245]
	v_pk_fma_f32 v[244:245], v[80:81], v[80:81], v[244:245]
	v_pk_fma_f32 v[244:245], v[82:83], v[82:83], v[244:245]
	v_add_f32_e32 v130, v244, v245
	s_waitcnt vmcnt(8)
; __device__ __forceinline__ float bf_lo(unsigned w) { return __uint_as_float(w << 16); }
; __device__ __forceinline__ float bf_hi(unsigned w) { return __uint_as_float(w & 0xffff0000u); }
; __device__ __forceinline__ float sigmoid_fast(float x) { return __builtin_amdgcn_rcpf(1.0f + __builtin_amdgcn_exp2f(-1.44269504089f * x)); }
;     __device__ __forceinline__ void operator()(const pg8::f32x4 (&acc)[2][2][4][2], const pg8::Unit& u, int wr, int wc, int fr, int fq) const {
;     ...
;             for (int m = 0; m < 4; ++m) {
;                 const int row = row0 + ai * 128 + m * 16;
;                 const size_t off = (size_t)row * D + col0;
;                 float s = 0.f;
; #pragma unroll
;                 for (int bj = 0; bj < 2; ++bj) {
;                     float r[8];
; #pragma unroll
;                     for (int j = 0; j < 4; ++j) { r[j] = acc[ai][bj][m][0][j]; r[4 + j] = acc[ai][bj][m][1][j]; }
;                     if (RSCALE) { const float rv = rvs[ai][m];
; #pragma unroll
;                         for (int j = 0; j < 8; ++j) r[j] *= rv; }
;                     if (ACT == 1) {
; #pragma unroll
;                         for (int j = 0; j < 8; ++j) r[j] = sigmoid_fast(r[j]);
;                     }
;                     if (GATE) { const v4u g = gq[m][bj];
;                         r[0] *= bf_lo(g.x); r[1] *= bf_hi(g.x); r[2] *= bf_lo(g.y); r[3] *= bf_hi(g.y); r[4] *= bf_lo(g.z); r[5] *= bf_hi(g.z); r[6] *= bf_lo(g.w); r[7] *= bf_hi(g.w); }
;                     if (ADD) { const v4u g = aq[m][bj];
;                         r[0] += bf_lo(g.x); r[1] += bf_hi(g.x); r[2] += bf_lo(g.y); r[3] += bf_hi(g.y); r[4] += bf_lo(g.z); r[5] += bf_hi(g.z); r[6] += bf_lo(g.w); r[7] += bf_hi(g.w); }
;                     if (PART) {
; #pragma unroll
;                         for (int j = 0; j < 8; ++j) s += r[j] * r[j];
	v_lshlrev_b32_e32 v248, 16, v204
	v_and_b32_e32 v249, 0xffff0000, v204
	v_pk_mul_f32 v[76:77], v[76:77], v[248:249]
	v_lshlrev_b32_e32 v250, 16, v205
	v_and_b32_e32 v251, 0xffff0000, v205
	v_pk_mul_f32 v[78:79], v[78:79], v[250:251]
	v_lshlrev_b32_e32 v252, 16, v206
	v_and_b32_e32 v253, 0xffff0000, v206
	v_pk_mul_f32 v[72:73], v[72:73], v[252:253]
	v_lshlrev_b32_e32 v248, 16, v207
	v_and_b32_e32 v249, 0xffff0000, v207
	v_pk_mul_f32 v[74:75], v[74:75], v[248:249]
	v_lshlrev_b32_e32 v250, 16, v208
	v_and_b32_e32 v251, 0xffff0000, v208
	v_pk_mul_f32 v[68:69], v[68:69], v[250:251]
	v_lshlrev_b32_e32 v252, 16, v209
	v_and_b32_e32 v253, 0xffff0000, v209
	v_pk_mul_f32 v[70:71], v[70:71], v[252:253]
	v_lshlrev_b32_e32 v248, 16, v210
	v_and_b32_e32 v249, 0xffff0000, v210
	v_pk_mul_f32 v[64:65], v[64:65], v[248:249]
	v_lshlrev_b32_e32 v250, 16, v211
	v_and_b32_e32 v251, 0xffff0000, v211
	v_pk_mul_f32 v[66:67], v[66:67], v[250:251]
	v_pk_mul_f32 v[244:245], v[76:77], v[76:77]
	v_pk_fma_f32 v[244:245], v[78:79], v[78:79], v[244:245]
	v_pk_fma_f32 v[244:245], v[72:73], v[72:73], v[244:245]
	v_pk_fma_f32 v[244:245], v[74:75], v[74:75], v[244:245]
	v_pk_fma_f32 v[244:245], v[68:69], v[68:69], v[244:245]
	v_pk_fma_f32 v[244:245], v[70:71], v[70:71], v[244:245]
	v_pk_fma_f32 v[244:245], v[64:65], v[64:65], v[244:245]
	v_pk_fma_f32 v[244:245], v[66:67], v[66:67], v[244:245]
	v_add_f32_e32 v131, v244, v245
	s_waitcnt vmcnt(6)
	v_lshlrev_b32_e32 v248, 16, v212
	v_and_b32_e32 v249, 0xffff0000, v212
	v_pk_mul_f32 v[60:61], v[60:61], v[248:249]
	v_lshlrev_b32_e32 v250, 16, v213
	v_and_b32_e32 v251, 0xffff0000, v213
	v_pk_mul_f32 v[62:63], v[62:63], v[250:251]
	v_lshlrev_b32_e32 v252, 16, v214
	v_and_b32_e32 v253, 0xffff0000, v214
	v_pk_mul_f32 v[56:57], v[56:57], v[252:253]
	v_lshlrev_b32_e32 v248, 16, v215
	v_and_b32_e32 v249, 0xffff0000, v215
	v_pk_mul_f32 v[58:59], v[58:59], v[248:249]
	v_lshlrev_b32_e32 v250, 16, v216
	v_and_b32_e32 v251, 0xffff0000, v216
	v_pk_mul_f32 v[52:53], v[52:53], v[250:251]
	v_lshlrev_b32_e32 v252, 16, v217
	v_and_b32_e32 v253, 0xffff0000, v217
	v_pk_mul_f32 v[54:55], v[54:55], v[252:253]
	v_lshlrev_b32_e32 v248, 16, v218
	v_and_b32_e32 v249, 0xffff0000, v218
	v_pk_mul_f32 v[48:49], v[48:49], v[248:249]
	v_lshlrev_b32_e32 v250, 16, v219
	v_and_b32_e32 v251, 0xffff0000, v219
	v_pk_mul_f32 v[50:51], v[50:51], v[250:251]
	v_pk_mul_f32 v[244:245], v[60:61], v[60:61]
	v_pk_fma_f32 v[244:245], v[62:63], v[62:63], v[244:245]
	v_pk_fma_f32 v[244:245], v[56:57], v[56:57], v[244:245]
	v_pk_fma_f32 v[244:245], v[58:59], v[58:59], v[244:245]
	v_pk_fma_f32 v[244:245], v[52:53], v[52:53], v[244:245]
	v_pk_fma_f32 v[244:245], v[54:55], v[54:55], v[244:245]
	v_pk_fma_f32 v[244:245], v[48:49], v[48:49], v[244:245]
	v_pk_fma_f32 v[244:245], v[50:51], v[50:51], v[244:245]
	v_add_f32_e32 v132, v244, v245
	s_waitcnt vmcnt(4)
	v_lshlrev_b32_e32 v248, 16, v220
	v_and_b32_e32 v249, 0xffff0000, v220
	v_pk_mul_f32 v[44:45], v[44:45], v[248:249]
	v_lshlrev_b32_e32 v250, 16, v221
	v_and_b32_e32 v251, 0xffff0000, v221
	v_pk_mul_f32 v[46:47], v[46:47], v[250:251]
	v_lshlrev_b32_e32 v252, 16, v222
	v_and_b32_e32 v253, 0xffff0000, v222
	v_pk_mul_f32 v[40:41], v[40:41], v[252:253]
	v_lshlrev_b32_e32 v248, 16, v223
	v_and_b32_e32 v249, 0xffff0000, v223
	v_pk_mul_f32 v[42:43], v[42:43], v[248:249]
	v_lshlrev_b32_e32 v250, 16, v224
	v_and_b32_e32 v251, 0xffff0000, v224
	v_pk_mul_f32 v[36:37], v[36:37], v[250:251]
	v_lshlrev_b32_e32 v252, 16, v225
	v_and_b32_e32 v253, 0xffff0000, v225
	v_pk_mul_f32 v[38:39], v[38:39], v[252:253]
	v_lshlrev_b32_e32 v248, 16, v226
	v_and_b32_e32 v249, 0xffff0000, v226
	v_pk_mul_f32 v[32:33], v[32:33], v[248:249]
	v_lshlrev_b32_e32 v250, 16, v227
	v_and_b32_e32 v251, 0xffff0000, v227
	v_pk_mul_f32 v[34:35], v[34:35], v[250:251]
	v_pk_mul_f32 v[244:245], v[44:45], v[44:45]
	v_pk_fma_f32 v[244:245], v[46:47], v[46:47], v[244:245]
	v_pk_fma_f32 v[244:245], v[40:41], v[40:41], v[244:245]
	v_pk_fma_f32 v[244:245], v[42:43], v[42:43], v[244:245]
	v_pk_fma_f32 v[244:245], v[36:37], v[36:37], v[244:245]
	v_pk_fma_f32 v[244:245], v[38:39], v[38:39], v[244:245]
	v_pk_fma_f32 v[244:245], v[32:33], v[32:33], v[244:245]
	v_pk_fma_f32 v[244:245], v[34:35], v[34:35], v[244:245]
	v_add_f32_e32 v133, v244, v245
	s_waitcnt vmcnt(2)
	v_lshlrev_b32_e32 v248, 16, v228
	v_and_b32_e32 v249, 0xffff0000, v228
	v_pk_mul_f32 v[28:29], v[28:29], v[248:249]
	v_lshlrev_b32_e32 v250, 16, v229
	v_and_b32_e32 v251, 0xffff0000, v229
	v_pk_mul_f32 v[30:31], v[30:31], v[250:251]
	v_lshlrev_b32_e32 v252, 16, v230
	v_and_b32_e32 v253, 0xffff0000, v230
	v_pk_mul_f32 v[24:25], v[24:25], v[252:253]
	v_lshlrev_b32_e32 v248, 16, v231
	v_and_b32_e32 v249, 0xffff0000, v231
	v_pk_mul_f32 v[26:27], v[26:27], v[248:249]
	v_lshlrev_b32_e32 v250, 16, v232
	v_and_b32_e32 v251, 0xffff0000, v232
	v_pk_mul_f32 v[20:21], v[20:21], v[250:251]
	v_lshlrev_b32_e32 v252, 16, v233
	v_and_b32_e32 v253, 0xffff0000, v233
	v_pk_mul_f32 v[22:23], v[22:23], v[252:253]
	v_lshlrev_b32_e32 v248, 16, v234
	v_and_b32_e32 v249, 0xffff0000, v234
	v_pk_mul_f32 v[16:17], v[16:17], v[248:249]
	v_lshlrev_b32_e32 v250, 16, v235
	v_and_b32_e32 v251, 0xffff0000, v235
	v_pk_mul_f32 v[18:19], v[18:19], v[250:251]
	v_pk_mul_f32 v[244:245], v[28:29], v[28:29]
	v_pk_fma_f32 v[244:245], v[30:31], v[30:31], v[244:245]
	v_pk_fma_f32 v[244:245], v[24:25], v[24:25], v[244:245]
	v_pk_fma_f32 v[244:245], v[26:27], v[26:27], v[244:245]
	v_pk_fma_f32 v[244:245], v[20:21], v[20:21], v[244:245]
	v_pk_fma_f32 v[244:245], v[22:23], v[22:23], v[244:245]
	v_pk_fma_f32 v[244:245], v[16:17], v[16:17], v[244:245]
	v_pk_fma_f32 v[244:245], v[18:19], v[18:19], v[244:245]
	v_add_f32_e32 v134, v244, v245
	s_waitcnt vmcnt(0)
; __device__ __forceinline__ unsigned pk2(float lo, float hi) { bf16x2_t r = __builtin_convertvector((f32x2_t){lo, hi}, bf16x2_t); return __builtin_bit_cast(unsigned, r); }
;     __device__ __forceinline__ void operator()(const pg8::f32x4 (&acc)[2][2][4][2], const pg8::Unit& u, int wr, int wc, int fr, int fq) const {
;     ...
;                     if (PART) {
; #pragma unroll
;                         for (int j = 0; j < 8; ++j) s += r[j] * r[j];
;                     }
;                     v4u w; w.x = pk2(r[0], r[1]); w.y = pk2(r[2], r[3]); w.z = pk2(r[4], r[5]); w.w = pk2(r[6], r[7]);
;                     st16_wt(O + off + bj * 128, w);
;                 }
;                 if (PART) { s += __shfl_xor(s, 16); s += __shfl_xor(s, 32); st4_wt(part + (size_t)row * 16 + u.pn * 4 + wc, s); }
; template <bool SRC_F32, int R> __device__ __forceinline__ void ew_load(EwSet<SRC_F32, R>& S, int rb, const float* hsrc32, const bf16* hsrcb, const bf16* f, const float* part, int lane) {
; #pragma unroll
;     for (int i = 0; i < R; ++i) S.p[i] = (lane < 16) ? part[(size_t)(rb + i) * 16 + lane] : 0.f;
; #pragma unroll
;     for (int i = 0; i < R; ++i)
; #pragma unroll
;         for (int j = 0; j < 4; ++j) {
;             S.fw[i][j] = ((const v2u*)(f + (size_t)(rb + i) * D) + lane)[64 * j];
;             if constexpr (SRC_F32) S.h32[i][j] = __builtin_nontemporal_load((const f32x4*)(hsrc32 + (size_t)(rb + i) * D) + lane + 64 * j);
;             else S.hb[i][j] = ((const v2u*)(hsrcb + (size_t)(rb + i) * D) + lane)[64 * j];
;         }
	v_lshlrev_b32_e32 v248, 16, v236
	v_and_b32_e32 v249, 0xffff0000, v236
	v_pk_mul_f32 v[12:13], v[12:13], v[248:249]
	v_lshlrev_b32_e32 v250, 16, v237
	v_and_b32_e32 v251, 0xffff0000, v237
	v_pk_mul_f32 v[14:15], v[14:15], v[250:251]
	v_lshlrev_b32_e32 v252, 16, v238
	v_and_b32_e32 v253, 0xffff0000, v238
	v_pk_mul_f32 v[8:9], v[8:9], v[252:253]
	v_lshlrev_b32_e32 v248, 16, v239
	v_and_b32_e32 v249, 0xffff0000, v239
	v_pk_mul_f32 v[10:11], v[10:11], v[248:249]
	v_lshlrev_b32_e32 v250, 16, v240
	v_and_b32_e32 v251, 0xffff0000, v240
	v_pk_mul_f32 v[4:5], v[4:5], v[250:251]
	v_lshlrev_b32_e32 v252, 16, v241
	v_and_b32_e32 v253, 0xffff0000, v241
	v_pk_mul_f32 v[6:7], v[6:7], v[252:253]
	v_lshlrev_b32_e32 v248, 16, v242
	v_and_b32_e32 v249, 0xffff0000, v242
	v_pk_mul_f32 v[0:1], v[0:1], v[248:249]
	v_lshlrev_b32_e32 v250, 16, v243
	v_and_b32_e32 v251, 0xffff0000, v243
	v_pk_mul_f32 v[2:3], v[2:3], v[250:251]
	v_pk_mul_f32 v[244:245], v[12:13], v[12:13]
	v_pk_fma_f32 v[244:245], v[14:15], v[14:15], v[244:245]
	v_pk_fma_f32 v[244:245], v[8:9], v[8:9], v[244:245]
	v_pk_fma_f32 v[244:245], v[10:11], v[10:11], v[244:245]
	v_pk_fma_f32 v[244:245], v[4:5], v[4:5], v[244:245]
	v_pk_fma_f32 v[244:245], v[6:7], v[6:7], v[244:245]
	v_pk_fma_f32 v[244:245], v[0:1], v[0:1], v[244:245]
	v_pk_fma_f32 v[244:245], v[2:3], v[2:3], v[244:245]
	v_add_f32_e32 v135, v244, v245
	s_nop 1
	ds_bpermute_b32 v158, v177, v128
	ds_bpermute_b32 v159, v177, v129
	ds_bpermute_b32 v160, v177, v130
	ds_bpermute_b32 v161, v177, v131
	ds_bpermute_b32 v162, v177, v132
	ds_bpermute_b32 v163, v177, v133
	ds_bpermute_b32 v164, v177, v134
	ds_bpermute_b32 v165, v177, v135
	s_waitcnt lgkmcnt(0)
	v_add_f32_e32 v128, v128, v158
	v_add_f32_e32 v129, v129, v159
	v_add_f32_e32 v130, v130, v160
	v_add_f32_e32 v131, v131, v161
	v_add_f32_e32 v132, v132, v162
	v_add_f32_e32 v133, v133, v163
	v_add_f32_e32 v134, v134, v164
	v_add_f32_e32 v135, v135, v165
	s_nop 1
	ds_bpermute_b32 v158, v155, v128
	ds_bpermute_b32 v159, v155, v129
	ds_bpermute_b32 v160, v155, v130
	ds_bpermute_b32 v161, v155, v131
	ds_bpermute_b32 v162, v155, v132
	ds_bpermute_b32 v163, v155, v133
	ds_bpermute_b32 v164, v155, v134
	ds_bpermute_b32 v165, v155, v135
	s_waitcnt lgkmcnt(0)
	v_add_f32_e32 v128, v128, v158
	v_add_f32_e32 v129, v129, v159
	v_add_f32_e32 v130, v130, v160
	v_add_f32_e32 v131, v131, v161
	v_add_f32_e32 v132, v132, v162
	v_add_f32_e32 v133, v133, v163
	v_add_f32_e32 v134, v134, v164
	v_add_f32_e32 v135, v135, v165
	global_store_dword v153, v128, s[20:21]
	v_add_u32_e32 v159, 0x400, v153
	global_store_dword v159, v129, s[20:21]
	v_add_u32_e32 v160, 0x800, v153
	global_store_dword v160, v130, s[20:21]
	v_add_u32_e32 v161, 0xc00, v153
	global_store_dword v161, v131, s[20:21]
	v_add_u32_e32 v162, 0x2000, v153
	global_store_dword v162, v132, s[20:21]
	v_add_u32_e32 v163, 0x2400, v153
	global_store_dword v163, v133, s[20:21]
	v_add_u32_e32 v164, 0x2800, v153
	global_store_dword v164, v134, s[20:21]
	v_add_u32_e32 v165, 0x2c00, v153
	global_store_dword v165, v135, s[20:21]
	s_add_u32 s60, s84, 0xffffff10
	s_addc_u32 s61, s85, -1
	s_load_dwordx2 s[62:63], s[60:61], 0xd0
	s_load_dwordx2 s[64:65], s[60:61], 0xd8
	s_add_u32 s66, s28, 0x5000000
	s_addc_u32 s67, s29, 0
	global_load_dwordx4 v[178:181], v152, s[66:67]
	global_load_dwordx4 v[182:185], v152, s[66:67] offset:256
	v_add_u32_e32 v159, 0x8000, v152
	global_load_dwordx4 v[186:189], v159, s[66:67]
	global_load_dwordx4 v[190:193], v159, s[66:67] offset:256
	s_waitcnt lgkmcnt(0)
	global_load_dwordx4 v[228:231], v156, s[62:63]
	global_load_dwordx4 v[232:235], v156, s[62:63] offset:16
	global_load_dwordx4 v[236:239], v156, s[62:63] offset:512
	global_load_dwordx4 v[240:243], v156, s[62:63] offset:528
	s_waitcnt vmcnt(0)
	s_barrier
	v_readfirstlane_b32 s59, v195
	s_cmp_lg_u32 s59, 0
	s_cbranch_scc1 .Lp13_bskip
	s_mov_b64 exec, 1
	s_and_b32 s59, s2, 7
	s_lshl_b32 s59, s59, 3
	s_bfe_u32 s60, s2, 0x30003
	s_or_b32 s59, s59, s60
	s_lshl_b32 s59, s59, 5
	s_add_u32 s60, s28, 0x3903600
	s_addc_u32 s61, s29, 0
	v_mov_b32_e32 v244, s59
	v_mov_b32_e32 v245, 1
	s_cmp_eq_u32 s99, 1
	s_cbranch_scc1 .Lp13_bfast
	buffer_wbl2 sc1
	s_waitcnt vmcnt(0)
.Lp13_bfast:
	global_atomic_add v246, v244, v245, s[60:61] offset:8 sc0
	buffer_inv sc1
	s_waitcnt vmcnt(0)
	v_add_u32_e32 v247, 1, v246
	v_and_b32_e32 v247, 3, v247
	v_cmp_eq_u32_e32 vcc, 0, v247
	s_cbranch_vccnz .Lp13_bdone
	v_lshrrev_b32_e32 v246, 2, v246
	v_add_u32_e32 v246, 1, v246
	v_lshlrev_b32_e32 v246, 2, v246
	s_mov_b32 s59, 0

; __device__ __forceinline__ float bf_lo(unsigned w) { return __uint_as_float(w << 16); }
; __device__ __forceinline__ float bf_hi(unsigned w) { return __uint_as_float(w & 0xffff0000u); }
; template <bool SRC_F32, bool FINAL, int R> __device__ __forceinline__ void ew_compute(const EwSet<SRC_F32, R>& S, int rb, const f32x4 (&g)[4], bf16* hb_out, float* out32, float scale, float* rs_out, int lane) {
; #pragma unroll
;     for (int i = 0; i < R; ++i) {
;         float q = S.p[i];
;         q += __shfl_xor(q, 1); q += __shfl_xor(q, 2); q += __shfl_xor(q, 4); q += __shfl_xor(q, 8);
;         const float ss = __shfl(q, 0);
;         const float rs = scale / sqrtf(ss * (1.f / D) + EPS);
;         float s2 = 0.f;
; #pragma unroll
;         for (int j = 0; j < 4; ++j) {
;             f32x4 h;
;             if constexpr (SRC_F32) h = S.h32[i][j];
;             else { const v2u hw = S.hb[i][j]; h.x = bf_lo(hw.x); h.y = bf_hi(hw.x); h.z = bf_lo(hw.y); h.w = bf_hi(hw.y); }
;             const v2u fw = S.fw[i][j];
;             f32x4 v; v.x = h.x + bf_lo(fw.x) * rs * g[j].x; v.y = h.y + bf_hi(fw.x) * rs * g[j].y; v.z = h.z + bf_lo(fw.y) * rs * g[j].z; v.w = h.w + bf_hi(fw.y) * rs * g[j].w;
;             if (FINAL) __builtin_nontemporal_store(v, (f32x4*)(out32 + (size_t)(rb + i) * D) + lane + 64 * j);
.Lp13_bskip:
	s_barrier
	v_lshl_add_u32 v165, v154, 6, v157
	global_load_dwordx4 v[196:199], v165, s[20:21]
	v_add_u32_e32 v163, 0x400, v165
	global_load_dwordx4 v[200:203], v163, s[20:21]
	v_add_u32_e32 v163, 0x800, v165
	global_load_dwordx4 v[204:207], v163, s[20:21]
	v_add_u32_e32 v163, 0xc00, v165
	global_load_dwordx4 v[208:211], v163, s[20:21]
	v_add_u32_e32 v163, 0x2000, v165
	global_load_dwordx4 v[212:215], v163, s[20:21]
	v_add_u32_e32 v163, 0x2400, v165
	global_load_dwordx4 v[216:219], v163, s[20:21]
	v_add_u32_e32 v163, 0x2800, v165
	global_load_dwordx4 v[220:223], v163, s[20:21]
	v_add_u32_e32 v163, 0x2c00, v165
	global_load_dwordx4 v[224:227], v163, s[20:21]
	s_waitcnt vmcnt(0)
	v_add_f32_e32 v128, v196, v197
	v_add_f32_e32 v128, v198, v128
	v_add_f32_e32 v128, v199, v128
	v_add_f32_e32 v129, v200, v201
	v_add_f32_e32 v129, v202, v129
	v_add_f32_e32 v129, v203, v129
	v_add_f32_e32 v130, v204, v205
	v_add_f32_e32 v130, v206, v130
	v_add_f32_e32 v130, v207, v130
	v_add_f32_e32 v131, v208, v209
	v_add_f32_e32 v131, v210, v131
	v_add_f32_e32 v131, v211, v131
	v_add_f32_e32 v132, v212, v213
	v_add_f32_e32 v132, v214, v132
	v_add_f32_e32 v132, v215, v132
	v_add_f32_e32 v133, v216, v217
	v_add_f32_e32 v133, v218, v133
	v_add_f32_e32 v133, v219, v133
	v_add_f32_e32 v134, v220, v221
	v_add_f32_e32 v134, v222, v134
	v_add_f32_e32 v134, v223, v134
	v_add_f32_e32 v135, v224, v225
	v_add_f32_e32 v135, v226, v135
	v_add_f32_e32 v135, v227, v135
	s_nop 1
	ds_bpermute_b32 v248, v177, v128
	ds_bpermute_b32 v249, v177, v129
	ds_bpermute_b32 v250, v177, v130
	ds_bpermute_b32 v251, v177, v131
	ds_bpermute_b32 v252, v177, v132
	ds_bpermute_b32 v253, v177, v133
	ds_bpermute_b32 v247, v177, v134
	ds_bpermute_b32 v245, v177, v135
	s_waitcnt lgkmcnt(0)
	v_add_f32_e32 v128, v128, v248
	v_add_f32_e32 v129, v129, v249
	v_add_f32_e32 v130, v130, v250
	v_add_f32_e32 v131, v131, v251
	v_add_f32_e32 v132, v132, v252
	v_add_f32_e32 v133, v133, v253
	v_add_f32_e32 v134, v134, v247
	v_add_f32_e32 v135, v135, v245
	s_nop 1
	ds_bpermute_b32 v248, v155, v128
	ds_bpermute_b32 v249, v155, v129
	ds_bpermute_b32 v250, v155, v130
	ds_bpermute_b32 v251, v155, v131
	ds_bpermute_b32 v252, v155, v132
	ds_bpermute_b32 v253, v155, v133
	ds_bpermute_b32 v247, v155, v134
	ds_bpermute_b32 v245, v155, v135
	s_waitcnt lgkmcnt(0)
	v_add_f32_e32 v128, v128, v248
	v_add_f32_e32 v129, v129, v249
	v_add_f32_e32 v130, v130, v250
	v_add_f32_e32 v131, v131, v251
	v_add_f32_e32 v132, v132, v252
	v_add_f32_e32 v133, v133, v253
	v_add_f32_e32 v134, v134, v247
	v_add_f32_e32 v135, v135, v245
	v_mul_f32_e32 v128, 0x3a800000, v128
	v_mul_f32_e32 v129, 0x3a800000, v129
	v_mul_f32_e32 v130, 0x3a800000, v130
	v_mul_f32_e32 v131, 0x3a800000, v131
	v_mul_f32_e32 v132, 0x3a800000, v132
	v_mul_f32_e32 v133, 0x3a800000, v133
	v_mul_f32_e32 v134, 0x3a800000, v134
	v_mul_f32_e32 v135, 0x3a800000, v135
	v_add_f32_e32 v128, 0x358637bd, v128
	v_add_f32_e32 v129, 0x358637bd, v129
	v_add_f32_e32 v130, 0x358637bd, v130
	v_add_f32_e32 v131, 0x358637bd, v131
	v_add_f32_e32 v132, 0x358637bd, v132
	v_add_f32_e32 v133, 0x358637bd, v133
	v_add_f32_e32 v134, 0x358637bd, v134
	v_add_f32_e32 v135, 0x358637bd, v135
	v_rsq_f32_e32 v158, v128
	v_rsq_f32_e32 v160, v129
	v_rsq_f32_e32 v162, v130
	v_rsq_f32_e32 v164, v131
	v_rsq_f32_e32 v166, v132
	v_rsq_f32_e32 v168, v133
	v_rsq_f32_e32 v244, v134
	v_rsq_f32_e32 v246, v135
	s_nop 0
	v_add_u32_e32 v159, 0x10000, v152
	global_load_dwordx4 v[196:199], v159, s[66:67]
	global_load_dwordx4 v[200:203], v159, s[66:67] offset:256
	v_add_u32_e32 v159, 0x18000, v152
	global_load_dwordx4 v[204:207], v159, s[66:67]
	global_load_dwordx4 v[208:211], v159, s[66:67] offset:256
	v_add_u32_e32 v159, 0x40000, v152
	global_load_dwordx4 v[212:215], v159, s[66:67]
	global_load_dwordx4 v[216:219], v159, s[66:67] offset:256
	v_add_u32_e32 v159, 0x48000, v152
	global_load_dwordx4 v[220:223], v159, s[66:67]
	global_load_dwordx4 v[224:227], v159, s[66:67] offset:256
	v_lshlrev_b32_e32 v248, 16, v178
	v_and_b32_e32 v249, 0xffff0000, v178
	v_pk_mul_f32 v[124:125], v[124:125], v[158:159] op_sel_hi:[1,0]
	v_pk_fma_f32 v[124:125], v[124:125], v[228:229], v[248:249]
	v_lshlrev_b32_e32 v250, 16, v179
	v_and_b32_e32 v251, 0xffff0000, v179
	v_pk_mul_f32 v[126:127], v[126:127], v[158:159] op_sel_hi:[1,0]
	v_pk_fma_f32 v[126:127], v[126:127], v[230:231], v[250:251]
	v_lshlrev_b32_e32 v252, 16, v180
	v_and_b32_e32 v253, 0xffff0000, v180
	v_pk_mul_f32 v[120:121], v[120:121], v[158:159] op_sel_hi:[1,0]
	v_pk_fma_f32 v[120:121], v[120:121], v[232:233], v[252:253]
	v_lshlrev_b32_e32 v248, 16, v181
	v_and_b32_e32 v249, 0xffff0000, v181
	v_pk_mul_f32 v[122:123], v[122:123], v[158:159] op_sel_hi:[1,0]
	v_pk_fma_f32 v[122:123], v[122:123], v[234:235], v[248:249]
	v_lshlrev_b32_e32 v250, 16, v182
	v_and_b32_e32 v251, 0xffff0000, v182
	v_pk_mul_f32 v[116:117], v[116:117], v[158:159] op_sel_hi:[1,0]
	v_pk_fma_f32 v[116:117], v[116:117], v[236:237], v[250:251]
	v_lshlrev_b32_e32 v252, 16, v183
	v_and_b32_e32 v253, 0xffff0000, v183
	v_pk_mul_f32 v[118:119], v[118:119], v[158:159] op_sel_hi:[1,0]
	v_pk_fma_f32 v[118:119], v[118:119], v[238:239], v[252:253]
	v_lshlrev_b32_e32 v248, 16, v184
	v_and_b32_e32 v249, 0xffff0000, v184
	v_pk_mul_f32 v[112:113], v[112:113], v[158:159] op_sel_hi:[1,0]
	v_pk_fma_f32 v[112:113], v[112:113], v[240:241], v[248:249]
	v_lshlrev_b32_e32 v250, 16, v185
	v_and_b32_e32 v251, 0xffff0000, v185
	v_pk_mul_f32 v[114:115], v[114:115], v[158:159] op_sel_hi:[1,0]
	v_pk_fma_f32 v[114:115], v[114:115], v[242:243], v[250:251]
	v_lshlrev_b32_e32 v161, 1, v152
	global_store_dwordx4 v161, v[124:127], s[64:65] nt
; __device__ __forceinline__ float bf_lo(unsigned w) { return __uint_as_float(w << 16); }
; __device__ __forceinline__ float bf_hi(unsigned w) { return __uint_as_float(w & 0xffff0000u); }
; template <bool SRC_F32, bool FINAL, int R> __device__ __forceinline__ void ew_compute(const EwSet<SRC_F32, R>& S, int rb, const f32x4 (&g)[4], bf16* hb_out, float* out32, float scale, float* rs_out, int lane) {
;     ...
; #pragma unroll
;         for (int j = 0; j < 4; ++j) {
;             f32x4 h;
;             if constexpr (SRC_F32) h = S.h32[i][j];
;             else { const v2u hw = S.hb[i][j]; h.x = bf_lo(hw.x); h.y = bf_hi(hw.x); h.z = bf_lo(hw.y); h.w = bf_hi(hw.y); }
;             const v2u fw = S.fw[i][j];
;             f32x4 v; v.x = h.x + bf_lo(fw.x) * rs * g[j].x; v.y = h.y + bf_hi(fw.x) * rs * g[j].y; v.z = h.z + bf_lo(fw.y) * rs * g[j].z; v.w = h.w + bf_hi(fw.y) * rs * g[j].w;
;             if (FINAL) __builtin_nontemporal_store(v, (f32x4*)(out32 + (size_t)(rb + i) * D) + lane + 64 * j);
	global_store_dwordx4 v161, v[120:123], s[64:65] offset:16 nt
	global_store_dwordx4 v161, v[116:119], s[64:65] offset:512 nt
	global_store_dwordx4 v161, v[112:115], s[64:65] offset:528 nt
	v_lshlrev_b32_e32 v248, 16, v186
	v_and_b32_e32 v249, 0xffff0000, v186
	v_pk_mul_f32 v[108:109], v[108:109], v[160:161] op_sel_hi:[1,0]
	v_pk_fma_f32 v[108:109], v[108:109], v[228:229], v[248:249]
	v_lshlrev_b32_e32 v250, 16, v187
	v_and_b32_e32 v251, 0xffff0000, v187
	v_pk_mul_f32 v[110:111], v[110:111], v[160:161] op_sel_hi:[1,0]
	v_pk_fma_f32 v[110:111], v[110:111], v[230:231], v[250:251]
	v_lshlrev_b32_e32 v252, 16, v188
	v_and_b32_e32 v253, 0xffff0000, v188
	v_pk_mul_f32 v[104:105], v[104:105], v[160:161] op_sel_hi:[1,0]
	v_pk_fma_f32 v[104:105], v[104:105], v[232:233], v[252:253]
	v_lshlrev_b32_e32 v248, 16, v189
	v_and_b32_e32 v249, 0xffff0000, v189
	v_pk_mul_f32 v[106:107], v[106:107], v[160:161] op_sel_hi:[1,0]
	v_pk_fma_f32 v[106:107], v[106:107], v[234:235], v[248:249]
	v_lshlrev_b32_e32 v250, 16, v190
	v_and_b32_e32 v251, 0xffff0000, v190
	v_pk_mul_f32 v[100:101], v[100:101], v[160:161] op_sel_hi:[1,0]
	v_pk_fma_f32 v[100:101], v[100:101], v[236:237], v[250:251]
	v_lshlrev_b32_e32 v252, 16, v191
	v_and_b32_e32 v253, 0xffff0000, v191
	v_pk_mul_f32 v[102:103], v[102:103], v[160:161] op_sel_hi:[1,0]
	v_pk_fma_f32 v[102:103], v[102:103], v[238:239], v[252:253]
	v_lshlrev_b32_e32 v248, 16, v192
	v_and_b32_e32 v249, 0xffff0000, v192
	v_pk_mul_f32 v[96:97], v[96:97], v[160:161] op_sel_hi:[1,0]
	v_pk_fma_f32 v[96:97], v[96:97], v[240:241], v[248:249]
	v_lshlrev_b32_e32 v250, 16, v193
	v_and_b32_e32 v251, 0xffff0000, v193
	v_pk_mul_f32 v[98:99], v[98:99], v[160:161] op_sel_hi:[1,0]
	v_pk_fma_f32 v[98:99], v[98:99], v[242:243], v[250:251]
	v_add_u32_e32 v161, 0x8000, v152
	v_lshlrev_b32_e32 v161, 1, v161
	global_store_dwordx4 v161, v[108:111], s[64:65] nt
	global_store_dwordx4 v161, v[104:107], s[64:65] offset:16 nt
	global_store_dwordx4 v161, v[100:103], s[64:65] offset:512 nt
	global_store_dwordx4 v161, v[96:99], s[64:65] offset:528 nt
	v_add_u32_e32 v159, 0x50000, v152
	global_load_dwordx4 v[178:181], v159, s[66:67]
	global_load_dwordx4 v[182:185], v159, s[66:67] offset:256
	v_add_u32_e32 v159, 0x58000, v152
	global_load_dwordx4 v[186:189], v159, s[66:67]
	global_load_dwordx4 v[190:193], v159, s[66:67] offset:256
	s_waitcnt vmcnt(18)
	v_lshlrev_b32_e32 v248, 16, v196
	v_and_b32_e32 v249, 0xffff0000, v196
	v_pk_mul_f32 v[92:93], v[92:93], v[162:163] op_sel_hi:[1,0]
	v_pk_fma_f32 v[92:93], v[92:93], v[228:229], v[248:249]
	v_lshlrev_b32_e32 v250, 16, v197
	v_and_b32_e32 v251, 0xffff0000, v197
	v_pk_mul_f32 v[94:95], v[94:95], v[162:163] op_sel_hi:[1,0]
	v_pk_fma_f32 v[94:95], v[94:95], v[230:231], v[250:251]
	v_lshlrev_b32_e32 v252, 16, v198
	v_and_b32_e32 v253, 0xffff0000, v198
	v_pk_mul_f32 v[88:89], v[88:89], v[162:163] op_sel_hi:[1,0]
	v_pk_fma_f32 v[88:89], v[88:89], v[232:233], v[252:253]
	v_lshlrev_b32_e32 v248, 16, v199
	v_and_b32_e32 v249, 0xffff0000, v199
	v_pk_mul_f32 v[90:91], v[90:91], v[162:163] op_sel_hi:[1,0]
	v_pk_fma_f32 v[90:91], v[90:91], v[234:235], v[248:249]
	v_lshlrev_b32_e32 v250, 16, v200
	v_and_b32_e32 v251, 0xffff0000, v200
	v_pk_mul_f32 v[84:85], v[84:85], v[162:163] op_sel_hi:[1,0]
	v_pk_fma_f32 v[84:85], v[84:85], v[236:237], v[250:251]
	v_lshlrev_b32_e32 v252, 16, v201
	v_and_b32_e32 v253, 0xffff0000, v201
	v_pk_mul_f32 v[86:87], v[86:87], v[162:163] op_sel_hi:[1,0]
	v_pk_fma_f32 v[86:87], v[86:87], v[238:239], v[252:253]
	v_lshlrev_b32_e32 v248, 16, v202
	v_and_b32_e32 v249, 0xffff0000, v202
	v_pk_mul_f32 v[80:81], v[80:81], v[162:163] op_sel_hi:[1,0]
	v_pk_fma_f32 v[80:81], v[80:81], v[240:241], v[248:249]
	v_lshlrev_b32_e32 v250, 16, v203
	v_and_b32_e32 v251, 0xffff0000, v203
	v_pk_mul_f32 v[82:83], v[82:83], v[162:163] op_sel_hi:[1,0]
	v_pk_fma_f32 v[82:83], v[82:83], v[242:243], v[250:251]
	v_add_u32_e32 v161, 0x10000, v152
	v_lshlrev_b32_e32 v161, 1, v161
	global_store_dwordx4 v161, v[92:95], s[64:65] nt
	global_store_dwordx4 v161, v[88:91], s[64:65] offset:16 nt
	global_store_dwordx4 v161, v[84:87], s[64:65] offset:512 nt
	global_store_dwordx4 v161, v[80:83], s[64:65] offset:528 nt
	s_waitcnt vmcnt(20)
	v_lshlrev_b32_e32 v248, 16, v204
	v_and_b32_e32 v249, 0xffff0000, v204
	v_pk_mul_f32 v[76:77], v[76:77], v[164:165] op_sel_hi:[1,0]
	v_pk_fma_f32 v[76:77], v[76:77], v[228:229], v[248:249]
	v_lshlrev_b32_e32 v250, 16, v205
	v_and_b32_e32 v251, 0xffff0000, v205
	v_pk_mul_f32 v[78:79], v[78:79], v[164:165] op_sel_hi:[1,0]
	v_pk_fma_f32 v[78:79], v[78:79], v[230:231], v[250:251]
	v_lshlrev_b32_e32 v252, 16, v206
	v_and_b32_e32 v253, 0xffff0000, v206
	v_pk_mul_f32 v[72:73], v[72:73], v[164:165] op_sel_hi:[1,0]
	v_pk_fma_f32 v[72:73], v[72:73], v[232:233], v[252:253]
	v_lshlrev_b32_e32 v248, 16, v207
	v_and_b32_e32 v249, 0xffff0000, v207
	v_pk_mul_f32 v[74:75], v[74:75], v[164:165] op_sel_hi:[1,0]
	v_pk_fma_f32 v[74:75], v[74:75], v[234:235], v[248:249]
	v_lshlrev_b32_e32 v250, 16, v208
	v_and_b32_e32 v251, 0xffff0000, v208
	v_pk_mul_f32 v[68:69], v[68:69], v[164:165] op_sel_hi:[1,0]
	v_pk_fma_f32 v[68:69], v[68:69], v[236:237], v[250:251]
	v_lshlrev_b32_e32 v252, 16, v209
	v_and_b32_e32 v253, 0xffff0000, v209
	v_pk_mul_f32 v[70:71], v[70:71], v[164:165] op_sel_hi:[1,0]
	v_pk_fma_f32 v[70:71], v[70:71], v[238:239], v[252:253]
	v_lshlrev_b32_e32 v248, 16, v210
	v_and_b32_e32 v249, 0xffff0000, v210
	v_pk_mul_f32 v[64:65], v[64:65], v[164:165] op_sel_hi:[1,0]
	v_pk_fma_f32 v[64:65], v[64:65], v[240:241], v[248:249]
	v_lshlrev_b32_e32 v250, 16, v211
	v_and_b32_e32 v251, 0xffff0000, v211
	v_pk_mul_f32 v[66:67], v[66:67], v[164:165] op_sel_hi:[1,0]
	v_pk_fma_f32 v[66:67], v[66:67], v[242:243], v[250:251]
	v_add_u32_e32 v161, 0x18000, v152
	v_lshlrev_b32_e32 v161, 1, v161
	global_store_dwordx4 v161, v[76:79], s[64:65] nt
	global_store_dwordx4 v161, v[72:75], s[64:65] offset:16 nt
	global_store_dwordx4 v161, v[68:71], s[64:65] offset:512 nt
	global_store_dwordx4 v161, v[64:67], s[64:65] offset:528 nt
	s_waitcnt vmcnt(22)
; __device__ __forceinline__ float bf_lo(unsigned w) { return __uint_as_float(w << 16); }
; __device__ __forceinline__ float bf_hi(unsigned w) { return __uint_as_float(w & 0xffff0000u); }
; template <bool SRC_F32, bool FINAL, int R> __device__ __forceinline__ void ew_compute(const EwSet<SRC_F32, R>& S, int rb, const f32x4 (&g)[4], bf16* hb_out, float* out32, float scale, float* rs_out, int lane) {
;     ...
; #pragma unroll
;         for (int j = 0; j < 4; ++j) {
;             f32x4 h;
;             if constexpr (SRC_F32) h = S.h32[i][j];
;             else { const v2u hw = S.hb[i][j]; h.x = bf_lo(hw.x); h.y = bf_hi(hw.x); h.z = bf_lo(hw.y); h.w = bf_hi(hw.y); }
;             const v2u fw = S.fw[i][j];
;             f32x4 v; v.x = h.x + bf_lo(fw.x) * rs * g[j].x; v.y = h.y + bf_hi(fw.x) * rs * g[j].y; v.z = h.z + bf_lo(fw.y) * rs * g[j].z; v.w = h.w + bf_hi(fw.y) * rs * g[j].w;
;             if (FINAL) __builtin_nontemporal_store(v, (f32x4*)(out32 + (size_t)(rb + i) * D) + lane + 64 * j);
	v_lshlrev_b32_e32 v248, 16, v212
	v_and_b32_e32 v249, 0xffff0000, v212
	v_pk_mul_f32 v[60:61], v[60:61], v[166:167] op_sel_hi:[1,0]
	v_pk_fma_f32 v[60:61], v[60:61], v[228:229], v[248:249]
	v_lshlrev_b32_e32 v250, 16, v213
	v_and_b32_e32 v251, 0xffff0000, v213
	v_pk_mul_f32 v[62:63], v[62:63], v[166:167] op_sel_hi:[1,0]
	v_pk_fma_f32 v[62:63], v[62:63], v[230:231], v[250:251]
	v_lshlrev_b32_e32 v252, 16, v214
	v_and_b32_e32 v253, 0xffff0000, v214
	v_pk_mul_f32 v[56:57], v[56:57], v[166:167] op_sel_hi:[1,0]
	v_pk_fma_f32 v[56:57], v[56:57], v[232:233], v[252:253]
	v_lshlrev_b32_e32 v248, 16, v215
	v_and_b32_e32 v249, 0xffff0000, v215
	v_pk_mul_f32 v[58:59], v[58:59], v[166:167] op_sel_hi:[1,0]
	v_pk_fma_f32 v[58:59], v[58:59], v[234:235], v[248:249]
	v_lshlrev_b32_e32 v250, 16, v216
	v_and_b32_e32 v251, 0xffff0000, v216
	v_pk_mul_f32 v[52:53], v[52:53], v[166:167] op_sel_hi:[1,0]
	v_pk_fma_f32 v[52:53], v[52:53], v[236:237], v[250:251]
	v_lshlrev_b32_e32 v252, 16, v217
	v_and_b32_e32 v253, 0xffff0000, v217
	v_pk_mul_f32 v[54:55], v[54:55], v[166:167] op_sel_hi:[1,0]
	v_pk_fma_f32 v[54:55], v[54:55], v[238:239], v[252:253]
	v_lshlrev_b32_e32 v248, 16, v218
	v_and_b32_e32 v249, 0xffff0000, v218
	v_pk_mul_f32 v[48:49], v[48:49], v[166:167] op_sel_hi:[1,0]
	v_pk_fma_f32 v[48:49], v[48:49], v[240:241], v[248:249]
	v_lshlrev_b32_e32 v250, 16, v219
	v_and_b32_e32 v251, 0xffff0000, v219
	v_pk_mul_f32 v[50:51], v[50:51], v[166:167] op_sel_hi:[1,0]
	v_pk_fma_f32 v[50:51], v[50:51], v[242:243], v[250:251]
	v_add_u32_e32 v161, 0x40000, v152
	v_lshlrev_b32_e32 v161, 1, v161
	global_store_dwordx4 v161, v[60:63], s[64:65] nt
	global_store_dwordx4 v161, v[56:59], s[64:65] offset:16 nt
	global_store_dwordx4 v161, v[52:55], s[64:65] offset:512 nt
	global_store_dwordx4 v161, v[48:51], s[64:65] offset:528 nt
	s_waitcnt vmcnt(24)
	v_lshlrev_b32_e32 v248, 16, v220
	v_and_b32_e32 v249, 0xffff0000, v220
	v_pk_mul_f32 v[44:45], v[44:45], v[168:169] op_sel_hi:[1,0]
	v_pk_fma_f32 v[44:45], v[44:45], v[228:229], v[248:249]
	v_lshlrev_b32_e32 v250, 16, v221
	v_and_b32_e32 v251, 0xffff0000, v221
	v_pk_mul_f32 v[46:47], v[46:47], v[168:169] op_sel_hi:[1,0]
	v_pk_fma_f32 v[46:47], v[46:47], v[230:231], v[250:251]
	v_lshlrev_b32_e32 v252, 16, v222
	v_and_b32_e32 v253, 0xffff0000, v222
	v_pk_mul_f32 v[40:41], v[40:41], v[168:169] op_sel_hi:[1,0]
	v_pk_fma_f32 v[40:41], v[40:41], v[232:233], v[252:253]
	v_lshlrev_b32_e32 v248, 16, v223
	v_and_b32_e32 v249, 0xffff0000, v223
	v_pk_mul_f32 v[42:43], v[42:43], v[168:169] op_sel_hi:[1,0]
	v_pk_fma_f32 v[42:43], v[42:43], v[234:235], v[248:249]
	v_lshlrev_b32_e32 v250, 16, v224
	v_and_b32_e32 v251, 0xffff0000, v224
	v_pk_mul_f32 v[36:37], v[36:37], v[168:169] op_sel_hi:[1,0]
	v_pk_fma_f32 v[36:37], v[36:37], v[236:237], v[250:251]
	v_lshlrev_b32_e32 v252, 16, v225
	v_and_b32_e32 v253, 0xffff0000, v225
	v_pk_mul_f32 v[38:39], v[38:39], v[168:169] op_sel_hi:[1,0]
	v_pk_fma_f32 v[38:39], v[38:39], v[238:239], v[252:253]
	v_lshlrev_b32_e32 v248, 16, v226
	v_and_b32_e32 v249, 0xffff0000, v226
	v_pk_mul_f32 v[32:33], v[32:33], v[168:169] op_sel_hi:[1,0]
	v_pk_fma_f32 v[32:33], v[32:33], v[240:241], v[248:249]
	v_lshlrev_b32_e32 v250, 16, v227
	v_and_b32_e32 v251, 0xffff0000, v227
	v_pk_mul_f32 v[34:35], v[34:35], v[168:169] op_sel_hi:[1,0]
	v_pk_fma_f32 v[34:35], v[34:35], v[242:243], v[250:251]
	v_add_u32_e32 v161, 0x48000, v152
	v_lshlrev_b32_e32 v161, 1, v161
	global_store_dwordx4 v161, v[44:47], s[64:65] nt
	global_store_dwordx4 v161, v[40:43], s[64:65] offset:16 nt
	global_store_dwordx4 v161, v[36:39], s[64:65] offset:512 nt
	global_store_dwordx4 v161, v[32:35], s[64:65] offset:528 nt
	s_waitcnt vmcnt(18)
; __device__ __forceinline__ float bf_lo(unsigned w) { return __uint_as_float(w << 16); }
; __device__ __forceinline__ float bf_hi(unsigned w) { return __uint_as_float(w & 0xffff0000u); }
; template <bool SRC_F32, bool FINAL, int R> __device__ __forceinline__ void ew_compute(const EwSet<SRC_F32, R>& S, int rb, const f32x4 (&g)[4], bf16* hb_out, float* out32, float scale, float* rs_out, int lane) {
;     ...
; #pragma unroll
;         for (int j = 0; j < 4; ++j) {
;             f32x4 h;
;             if constexpr (SRC_F32) h = S.h32[i][j];
;             else { const v2u hw = S.hb[i][j]; h.x = bf_lo(hw.x); h.y = bf_hi(hw.x); h.z = bf_lo(hw.y); h.w = bf_hi(hw.y); }
;             const v2u fw = S.fw[i][j];
;             f32x4 v; v.x = h.x + bf_lo(fw.x) * rs * g[j].x; v.y = h.y + bf_hi(fw.x) * rs * g[j].y; v.z = h.z + bf_lo(fw.y) * rs * g[j].z; v.w = h.w + bf_hi(fw.y) * rs * g[j].w;
;             if (FINAL) __builtin_nontemporal_store(v, (f32x4*)(out32 + (size_t)(rb + i) * D) + lane + 64 * j);
	v_lshlrev_b32_e32 v248, 16, v178
	v_and_b32_e32 v249, 0xffff0000, v178
	v_pk_mul_f32 v[28:29], v[28:29], v[244:245] op_sel_hi:[1,0]
	v_pk_fma_f32 v[28:29], v[28:29], v[228:229], v[248:249]
	v_lshlrev_b32_e32 v250, 16, v179
	v_and_b32_e32 v251, 0xffff0000, v179
	v_pk_mul_f32 v[30:31], v[30:31], v[244:245] op_sel_hi:[1,0]
	v_pk_fma_f32 v[30:31], v[30:31], v[230:231], v[250:251]
	v_lshlrev_b32_e32 v252, 16, v180
	v_and_b32_e32 v253, 0xffff0000, v180
	v_pk_mul_f32 v[24:25], v[24:25], v[244:245] op_sel_hi:[1,0]
	v_pk_fma_f32 v[24:25], v[24:25], v[232:233], v[252:253]
	v_lshlrev_b32_e32 v248, 16, v181
	v_and_b32_e32 v249, 0xffff0000, v181
	v_pk_mul_f32 v[26:27], v[26:27], v[244:245] op_sel_hi:[1,0]
	v_pk_fma_f32 v[26:27], v[26:27], v[234:235], v[248:249]
	v_lshlrev_b32_e32 v250, 16, v182
	v_and_b32_e32 v251, 0xffff0000, v182
	v_pk_mul_f32 v[20:21], v[20:21], v[244:245] op_sel_hi:[1,0]
	v_pk_fma_f32 v[20:21], v[20:21], v[236:237], v[250:251]
	v_lshlrev_b32_e32 v252, 16, v183
	v_and_b32_e32 v253, 0xffff0000, v183
	v_pk_mul_f32 v[22:23], v[22:23], v[244:245] op_sel_hi:[1,0]
	v_pk_fma_f32 v[22:23], v[22:23], v[238:239], v[252:253]
	v_lshlrev_b32_e32 v248, 16, v184
	v_and_b32_e32 v249, 0xffff0000, v184
	v_pk_mul_f32 v[16:17], v[16:17], v[244:245] op_sel_hi:[1,0]
	v_pk_fma_f32 v[16:17], v[16:17], v[240:241], v[248:249]
	v_lshlrev_b32_e32 v250, 16, v185
	v_and_b32_e32 v251, 0xffff0000, v185
	v_pk_mul_f32 v[18:19], v[18:19], v[244:245] op_sel_hi:[1,0]
	v_pk_fma_f32 v[18:19], v[18:19], v[242:243], v[250:251]
	v_add_u32_e32 v161, 0x50000, v152
	v_lshlrev_b32_e32 v161, 1, v161
	global_store_dwordx4 v161, v[28:31], s[64:65] nt
	global_store_dwordx4 v161, v[24:27], s[64:65] offset:16 nt
	global_store_dwordx4 v161, v[20:23], s[64:65] offset:512 nt
	global_store_dwordx4 v161, v[16:19], s[64:65] offset:528 nt
	s_waitcnt vmcnt(20)
	v_lshlrev_b32_e32 v248, 16, v186
	v_and_b32_e32 v249, 0xffff0000, v186
	v_pk_mul_f32 v[12:13], v[12:13], v[246:247] op_sel_hi:[1,0]
	v_pk_fma_f32 v[12:13], v[12:13], v[228:229], v[248:249]
	v_lshlrev_b32_e32 v250, 16, v187
	v_and_b32_e32 v251, 0xffff0000, v187
	v_pk_mul_f32 v[14:15], v[14:15], v[246:247] op_sel_hi:[1,0]
	v_pk_fma_f32 v[14:15], v[14:15], v[230:231], v[250:251]
	v_lshlrev_b32_e32 v252, 16, v188
	v_and_b32_e32 v253, 0xffff0000, v188
	v_pk_mul_f32 v[8:9], v[8:9], v[246:247] op_sel_hi:[1,0]
	v_pk_fma_f32 v[8:9], v[8:9], v[232:233], v[252:253]
	v_lshlrev_b32_e32 v248, 16, v189
	v_and_b32_e32 v249, 0xffff0000, v189
	v_pk_mul_f32 v[10:11], v[10:11], v[246:247] op_sel_hi:[1,0]
	v_pk_fma_f32 v[10:11], v[10:11], v[234:235], v[248:249]
	v_lshlrev_b32_e32 v250, 16, v190
	v_and_b32_e32 v251, 0xffff0000, v190
	v_pk_mul_f32 v[4:5], v[4:5], v[246:247] op_sel_hi:[1,0]
	v_pk_fma_f32 v[4:5], v[4:5], v[236:237], v[250:251]
	v_lshlrev_b32_e32 v252, 16, v191
	v_and_b32_e32 v253, 0xffff0000, v191
	v_pk_mul_f32 v[6:7], v[6:7], v[246:247] op_sel_hi:[1,0]
	v_pk_fma_f32 v[6:7], v[6:7], v[238:239], v[252:253]
	v_lshlrev_b32_e32 v248, 16, v192
	v_and_b32_e32 v249, 0xffff0000, v192
	v_pk_mul_f32 v[0:1], v[0:1], v[246:247] op_sel_hi:[1,0]
	v_pk_fma_f32 v[0:1], v[0:1], v[240:241], v[248:249]
	v_lshlrev_b32_e32 v250, 16, v193
	v_and_b32_e32 v251, 0xffff0000, v193
	v_pk_mul_f32 v[2:3], v[2:3], v[246:247] op_sel_hi:[1,0]
	v_pk_fma_f32 v[2:3], v[2:3], v[242:243], v[250:251]
	v_add_u32_e32 v161, 0x58000, v152
	v_lshlrev_b32_e32 v161, 1, v161
	global_store_dwordx4 v161, v[12:15], s[64:65] nt
	global_store_dwordx4 v161, v[8:11], s[64:65] offset:16 nt
	global_store_dwordx4 v161, v[4:7], s[64:65] offset:512 nt
	global_store_dwordx4 v161, v[0:3], s[64:65] offset:528 nt
	s_and_b64 vcc, exec, s[4:5]
	s_mov_b64 s[4:5], -1
	s_cbranch_vccnz .LBB0_1376
	s_andn2_b64 vcc, exec, s[22:23]
	s_cbranch_vccnz .LBB0_1375
	s_barrier
	s_branch .LBB0_1375
